# attention K/V staging by direct HBM->LDS loads (no VGPR round trip, no ds_write), counted vmcnt two tiles ahead; K tile swizzle widened to 16 rows
# speedup vs baseline: 1.0617x; 1.0189x over previous
; __device__ __forceinline__ int v_st(int k, int c) { const int kk = (k & ~0xC) | ((k & 4) << 1) | ((k & 8) >> 1); return ((kk >> 3) * 4 + (c >> 5)) * 512 + ((kk & 7) * 32 + (c & 31)) * 2; }
; __device__ __forceinline__ int v_rd_base(int lane) { return ((lane & 3) << 3) | (((lane >> 2) & 3) << 6) | (((lane >> 4) & 1) << 5) | (((lane >> 5) & 1) << 8); }
; #define SLOAD(i, k0) do { sr_[i].vs0 = St::ld8(&Vh[(long)((k0) + sr) * LDK + sc]); sr_[i].vs1 = St::ld8(&Vh[(long)((k0) + 32 + sr) * LDK + sc]); \
;     sr_[i].ks0 = St::ld8(&Kh[(long)((k0) + sr) * LDK + sc]); sr_[i].ks1 = St::ld8(&Kh[(long)((k0) + 32 + sr) * LDK + sc]); } while (0)
; #define QF(d, e) __uint_as_float(((unsigned)(unsigned short)qr[d][e]) << 16)
; template <typename TQ> ...
;     ...
;   const int tid = tid_, wid = __builtin_amdgcn_readfirstlane(tid >> 6), lane = tid & 63, r32 = lane & 31, hi = lane >> 5;
;   bf16* V_lds = (bf16*)lds; bf16* K_lds = (bf16*)(lds + 2 * SHM_V);
;   float* ws = (float*)(lds + 2 * SHM_V + 2 * SHM_K) + wid * 64; float* li_l = ws;
;   float l_reg = 0; f32x16 o[4] = {}; bf16x8 qr[8];
;   const TQ* Qw = Qb + (long)(wid * QBLK + r32) * LDQ + hi * 8;
; #pragma unroll
;   for (int d0 = 0; d0 < 8; ++d0) qr[d0] = SQ::tobf(SQ::ld8(Qw + d0 * 16));
;   const int sr = tid >> 4, sc = (tid & 15) * 8, vst0 = v_st(sr, sc), vst1 = v_st(32 + sr, sc);
;   const int vb0 = (int)(uintptr_t)V_lds + v_rd_base(lane);
;   struct { typename St::T vs0, vs1, ks0, ks1; } sr_[SDEPTH];
;     ...
;   constexpr int SE = 0, SO = SDEPTH - 1;
;   SLOAD(SE, 0);
;   {
;     float ss = 0.f;
;     ...
; #pragma unroll
;     for (int d0 = 0; d0 < 8; ++d0)
; #pragma unroll
;       for (int e = 0; e < 8; ++e) { const float x = QF(d0, e); ss += x * x; }
; __global__ void __launch_bounds__(NTHR, 2) fwd_megakernel(KArgs a) {
;     ...
;         for (int i = 0; i < upb; ++i) {
;             const int unit = vcu * upb + i; if (unit >= 512) break;
;             const int grp = unit >> 7, rem = unit & 127, gq = rem >> 5, qb = rem & 31, b = grp >> 1, kvh = grp & 1, h = kvh * 4 + gq;
;             const size_t qoff = ((size_t)(b * SEQ + qb * 256)) * DM + h * 128, koff = (size_t)b * SKV * 256 + kvh * 128;
;             att::attn_dense_body<att::bf16>(Q + qoff, Kb + koff, Vb + koff, O + qoff, SKV, (char*)lds_raw, mC, a.g_q, (const float*)(ws + WS_ROPE), (const float*)(ws + WS_ROPE) + 4096, qb * 256);
.LBB0_819:
	s_add_i32 s12, s74, s73
	s_cmpk_gt_i32 s12, 0x1ff
	s_mov_b64 s[0:1], -1
	s_cbranch_scc1 .LBB0_818
	s_lshl_b32 s0, s94, 1
	s_ashr_i32 s96, s12, 8
	s_lshl_b32 s1, s12, 8
	s_and_b32 s95, s0, 0x100
	s_lshl_b32 s0, s96, 13
	s_and_b32 s33, s1, 0x1f00
	s_bfe_u32 s15, s12, 0x10007
	s_or_b32 s0, s0, s33
	s_lshl_b32 s12, s12, 2
	s_ashr_i32 s1, s0, 31
	s_lshl_b32 s13, s15, 9
	s_and_b32 s12, s12, 0x180
	s_lshl_b64 s[0:1], s[0:1], 10
	s_or_b32 s12, s13, s12
	s_or_b32 s0, s0, s12
	s_mul_i32 s12, s96, 0x210000
	s_lshl_b32 s15, s15, 7
	s_or_b32 s12, s12, s15
	s_lshl_b64 s[48:49], s[0:1], 1
	s_mul_hi_i32 s13, s96, 0x210000
	s_add_u32 s0, s20, s48
	s_addc_u32 s1, s21, s49
	s_lshl_b64 s[12:13], s[12:13], 1
	s_add_u32 s54, s69, s12
	s_addc_u32 s55, s70, s13
	v_mov_b32_e32 v114, v0
	s_add_u32 s64, s67, s12
	s_addc_u32 s65, s68, s13
	v_readfirstlane_b32 s53, v114
	s_ashr_i32 s12, s53, 1
	v_mov_b32_e32 v18, s12
	v_bfi_b32 v66, s75, v18, v114
	v_ashrrev_i32_e32 v67, 31, v66
	v_lshlrev_b64 v[18:19], 11, v[66:67]
	v_lshrrev_b32_e32 v20, 1, v114
	v_lshl_add_u64 v[18:19], s[0:1], 0, v[18:19]
	v_and_b32_e32 v194, 16, v20
	v_lshl_add_u64 v[18:19], v[18:19], 0, v[194:195]
	global_load_dwordx4 v[22:25], v[18:19], off offset:224
	global_load_dwordx4 v[28:31], v[18:19], off offset:160
	global_load_dwordx4 v[80:83], v[18:19], off offset:192
	global_load_dwordx4 v[84:87], v[18:19], off offset:128
	global_load_dwordx4 v[116:119], v[18:19], off
	global_load_dwordx4 v[96:99], v[18:19], off offset:32
	global_load_dwordx4 v[120:123], v[18:19], off offset:64
	global_load_dwordx4 v[124:127], v[18:19], off offset:96
	v_and_b32_e32 v42, 32, v114
	global_load_dwordx2 v[100:101], v42, s[26:27]
	global_load_dwordx2 v[60:61], v42, s[26:27] offset:128
	v_ashrrev_i32_e32 v38, 4, v114
	v_ashrrev_i32_e32 v39, 31, v38
	v_lshlrev_b64 v[34:35], 9, v[38:39]
	v_and_b32_e32 v202, 31, v114
	v_or_b32_e32 v32, s33, v202
	s_and_b32 s52, s12, 0xffffffe0
	v_add_u32_e32 v32, s52, v32
	v_ashrrev_i32_e32 v32, 1, v32
	v_and_b32_e32 v32, 0xffffffe0, v32
	v_ashrrev_i32_e32 v33, 31, v32
	v_lshlrev_b64 v[32:33], 2, v[32:33]
	v_mov_b32_e32 v43, v195
	v_lshl_add_u64 v[44:45], s[4:5], 0, v[32:33]
	v_lshl_add_u64 v[32:33], s[6:7], 0, v[32:33]
	v_lshl_add_u64 v[76:77], v[44:45], 0, v[42:43]
	v_lshl_add_u64 v[78:79], v[32:33], 0, v[42:43]
	global_load_dwordx2 v[106:107], v[76:77], off
	global_load_dwordx2 v[104:105], v[78:79], off
	v_add_u32_e32 v40, 32, v38
	v_ashrrev_i32_e32 v41, 31, v40
	v_lshlrev_b64 v[26:27], 9, v[40:41]
	v_lshlrev_b32_e32 v111, 3, v114
	v_and_b32_e32 v18, 0x78, v111
	v_lshlrev_b32_e32 v110, 1, v18
	v_or_b32_e32 v36, v34, v110
	v_mov_b32_e32 v37, v35
	v_or_b32_e32 v26, v26, v110
	v_lshl_add_u64 v[18:19], s[64:65], 0, v[36:37]
	v_lshl_add_u64 v[20:21], s[64:65], 0, v[26:27]
	v_lshl_add_u64 v[26:27], s[54:55], 0, v[26:27]
	v_and_b32_e32 v203, 63, v114
	v_mov_b32_e32 v205, 0
	s_waitcnt vmcnt(11)
	v_lshlrev_b32_e32 v56, 16, v22
	s_waitcnt vmcnt(7)
	v_lshlrev_b32_e32 v163, 16, v117
	v_and_b32_e32 v167, 0xffff0000, v117
	v_lshlrev_b32_e32 v171, 16, v116
	s_waitcnt vmcnt(5)
	v_lshlrev_b32_e32 v170, 16, v120
	v_and_b32_e32 v117, 0xffff0000, v116
	v_and_b32_e32 v116, 0xffff0000, v120
	v_lshlrev_b32_e32 v162, 16, v121
	v_and_b32_e32 v166, 0xffff0000, v121
	v_pk_mul_f32 v[172:173], v[170:171], v[170:171]
	v_pk_mul_f32 v[120:121], v[116:117], v[116:117]
	v_pk_mul_f32 v[164:165], v[162:163], v[162:163]
	v_add_f32_e32 v39, v173, v121
	v_lshlrev_b32_e32 v159, 16, v118
	v_lshlrev_b32_e32 v158, 16, v122
	v_pk_mul_f32 v[168:169], v[166:167], v[166:167]
	v_add_f32_e32 v39, v165, v39
	v_lshlrev_b32_e32 v109, 16, v119
	v_and_b32_e32 v103, 0xffff0000, v119
	v_pk_mul_f32 v[160:161], v[158:159], v[158:159]
	v_and_b32_e32 v119, 0xffff0000, v118
	v_and_b32_e32 v118, 0xffff0000, v122
	v_add_f32_e32 v39, v169, v39
	v_lshlrev_b32_e32 v108, 16, v123
	v_and_b32_e32 v102, 0xffff0000, v123
	v_pk_mul_f32 v[122:123], v[118:119], v[118:119]
	v_add_f32_e32 v39, v161, v39
	v_pk_mul_f32 v[146:147], v[108:109], v[108:109]
	v_add_f32_e32 v39, v123, v39
	v_lshlrev_b32_e32 v64, 16, v87
	v_and_b32_e32 v62, 0xffff0000, v87
	v_lshlrev_b32_e32 v75, 16, v85
	v_and_b32_e32 v73, 0xffff0000, v85
	v_lshlrev_b32_e32 v87, 16, v99
	v_and_b32_e32 v85, 0xffff0000, v99
	v_pk_mul_f32 v[148:149], v[102:103], v[102:103]
	v_lshlrev_b32_e32 v91, 16, v98
	v_and_b32_e32 v89, 0xffff0000, v98
	v_lshlrev_b32_e32 v99, 16, v96
	s_waitcnt vmcnt(4)
; #define SLOAD(i, k0) do { sr_[i].vs0 = St::ld8(&Vh[(long)((k0) + sr) * LDK + sc]); sr_[i].vs1 = St::ld8(&Vh[(long)((k0) + 32 + sr) * LDK + sc]); \
;     sr_[i].ks0 = St::ld8(&Kh[(long)((k0) + sr) * LDK + sc]); sr_[i].ks1 = St::ld8(&Kh[(long)((k0) + 32 + sr) * LDK + sc]); } while (0)
; #define QF(d, e) __uint_as_float(((unsigned)(unsigned short)qr[d][e]) << 16)
; template <typename TQ> ...
;     ...
;   SLOAD(SE, 0);
;   {
;     float ss = 0.f;
;     ...
; #pragma unroll
;     for (int d0 = 0; d0 < 8; ++d0)
; #pragma unroll
;       for (int e = 0; e < 8; ++e) { const float x = QF(d0, e); ss += x * x; }
;     ss += __shfl_xor(ss, 32);
;     const float rn = (SCALE * 1.4426950408889634f) / sqrtf(ss * (1.0f / 128.0f) + 1e-6f);
;     const int t = trow0 + wid * QBLK + r32; const int prow = t >> 6, pcol = t & 63;
; #pragma unroll
;     for (int hf = 0; hf < 2; ++hf)
; #pragma unroll
;       for (int dd = 0; dd < 2; ++dd) {
;         const int dl = 4 * hf + dd, du = dl + 2;
;         const int f0 = 16 * dd + 8 * hi;
;         const float* cp = rc + (hf ? pcol : prow) * 32 + f0; const float* sp = rsn + (hf ? pcol : prow) * 32 + f0;
;         const float* gl = gq + 16 * dl + 8 * hi; const float* gu = gq + 16 * du + 8 * hi;
;         unsigned wl[4], wu[4];
; #pragma unroll
;         for (int e = 0; e < 8; e += 2) {
;           float o1[2], o2[2];
; #pragma unroll
;           for (int k = 0; k < 2; ++k) { const float x1 = QF(dl, e + k) * rn * gl[e + k], x2 = QF(du, e + k) * rn * gu[e + k]; const float c = cp[e + k], sn = sp[e + k];
;             o1[k] = x1 * c - x2 * sn; o2[k] = x2 * c + x1 * sn; }
;           wl[e >> 1] = cvtpk(o1[0], o1[1]); wu[e >> 1] = cvtpk(o2[0], o2[1]);
;         }
;         u32x4 vl = {wl[0], wl[1], wl[2], wl[3]}, vu = {wu[0], wu[1], wu[2], wu[3]};
;         qr[dl] = *reinterpret_cast<bf16x8*>(&vl); qr[du] = *reinterpret_cast<bf16x8*>(&vu);
;       }
	v_lshlrev_b32_e32 v98, 16, v124
	v_add_f32_e32 v39, v147, v39
	v_lshlrev_b32_e32 v95, 16, v97
	v_and_b32_e32 v93, 0xffff0000, v97
	v_pk_mul_f32 v[156:157], v[98:99], v[98:99]
	v_and_b32_e32 v97, 0xffff0000, v96
	v_and_b32_e32 v96, 0xffff0000, v124
	v_add_f32_e32 v39, v149, v39
	v_lshlrev_b32_e32 v94, 16, v125
	v_and_b32_e32 v92, 0xffff0000, v125
	v_pk_mul_f32 v[124:125], v[96:97], v[96:97]
	v_add_f32_e32 v39, v157, v39
	v_pk_mul_f32 v[152:153], v[94:95], v[94:95]
	v_add_f32_e32 v39, v125, v39
	v_lshlrev_b32_e32 v90, 16, v126
	v_pk_mul_f32 v[154:155], v[92:93], v[92:93]
	v_add_f32_e32 v39, v153, v39
	v_pk_mul_f32 v[150:151], v[90:91], v[90:91]
	v_and_b32_e32 v88, 0xffff0000, v126
	v_add_f32_e32 v39, v155, v39
	v_lshlrev_b32_e32 v65, 16, v83
	v_and_b32_e32 v63, 0xffff0000, v83
	v_lshlrev_b32_e32 v71, 16, v86
	v_and_b32_e32 v69, 0xffff0000, v86
	v_lshlrev_b32_e32 v74, 16, v81
	v_and_b32_e32 v72, 0xffff0000, v81
	v_lshlrev_b32_e32 v83, 16, v84
	v_and_b32_e32 v81, 0xffff0000, v84
	v_lshlrev_b32_e32 v86, 16, v127
	v_and_b32_e32 v84, 0xffff0000, v127
	v_pk_mul_f32 v[126:127], v[88:89], v[88:89]
	v_add_f32_e32 v39, v151, v39
	v_pk_mul_f32 v[142:143], v[86:87], v[86:87]
	v_add_f32_e32 v39, v127, v39
	v_pk_mul_f32 v[144:145], v[84:85], v[84:85]
	v_add_f32_e32 v39, v143, v39
	v_add_f32_e32 v39, v145, v39
	v_add_f32_e32 v39, v172, v39
	v_add_f32_e32 v39, v120, v39
	v_add_f32_e32 v39, v164, v39
	v_add_f32_e32 v39, v168, v39
	v_add_f32_e32 v39, v160, v39
	v_add_f32_e32 v39, v122, v39
	v_add_f32_e32 v39, v146, v39
	v_add_f32_e32 v39, v148, v39
	v_add_f32_e32 v39, v156, v39
	v_add_f32_e32 v39, v124, v39
	v_add_f32_e32 v39, v152, v39
	v_add_f32_e32 v39, v154, v39
	v_add_f32_e32 v39, v150, v39
	v_add_f32_e32 v39, v126, v39
	v_lshlrev_b32_e32 v70, 16, v82
	v_and_b32_e32 v68, 0xffff0000, v82
	v_lshlrev_b32_e32 v82, 16, v80
	v_add_f32_e32 v39, v142, v39
	v_pk_mul_f32 v[138:139], v[82:83], v[82:83]
	v_and_b32_e32 v80, 0xffff0000, v80
	v_add_f32_e32 v39, v144, v39
	v_pk_mul_f32 v[140:141], v[80:81], v[80:81]
	v_add_f32_e32 v39, v139, v39
	v_pk_mul_f32 v[134:135], v[74:75], v[74:75]
	v_add_f32_e32 v39, v141, v39
	v_pk_mul_f32 v[136:137], v[72:73], v[72:73]
	v_add_f32_e32 v39, v135, v39
	v_pk_mul_f32 v[130:131], v[70:71], v[70:71]
	v_add_f32_e32 v39, v137, v39
	v_pk_mul_f32 v[132:133], v[68:69], v[68:69]
	v_add_f32_e32 v39, v131, v39
	v_lshlrev_b32_e32 v55, 16, v29
	v_and_b32_e32 v53, 0xffff0000, v29
	v_lshlrev_b32_e32 v57, 16, v28
	v_and_b32_e32 v59, 0xffff0000, v28
	v_pk_mul_f32 v[28:29], v[64:65], v[64:65]
	v_add_f32_e32 v39, v133, v39
	v_pk_mul_f32 v[128:129], v[62:63], v[62:63]
	v_add_f32_e32 v28, v28, v39
	v_pk_mul_f32 v[112:113], v[56:57], v[56:57]
	v_and_b32_e32 v58, 0xffff0000, v22
	v_add_f32_e32 v28, v128, v28
	v_lshlrev_b32_e32 v54, 16, v23
	v_and_b32_e32 v52, 0xffff0000, v23
	v_pk_mul_f32 v[22:23], v[58:59], v[58:59]
	v_add_f32_e32 v28, v113, v28
	v_add_f32_e32 v23, v23, v28
	v_fmac_f32_e32 v23, v55, v55
	v_lshlrev_b32_e32 v51, 16, v30
	v_fmac_f32_e32 v23, v53, v53
	v_and_b32_e32 v49, 0xffff0000, v30
	v_fmac_f32_e32 v23, v51, v51
	v_lshlrev_b32_e32 v47, 16, v31
	v_fmac_f32_e32 v23, v49, v49
	v_and_b32_e32 v45, 0xffff0000, v31
	v_fmac_f32_e32 v23, v47, v47
	v_fmac_f32_e32 v23, v45, v45
	v_add_f32_e32 v23, v138, v23
	v_add_f32_e32 v23, v140, v23
	v_add_f32_e32 v23, v134, v23
	v_add_f32_e32 v23, v136, v23
	v_add_f32_e32 v23, v130, v23
	v_add_f32_e32 v23, v132, v23
	v_add_f32_e32 v23, v29, v23
	v_add_f32_e32 v23, v129, v23
	v_mov_b32_e32 v32, v52
	v_mov_b32_e32 v33, v54
	v_add_f32_e32 v23, v112, v23
	v_lshlrev_b32_e32 v50, 16, v24
	v_and_b32_e32 v48, 0xffff0000, v24
	v_pk_mul_f32 v[32:33], v[32:33], v[32:33]
	v_add_f32_e32 v22, v22, v23
	v_mov_b32_e32 v30, v48
	v_mov_b32_e32 v31, v50
	v_add_f32_e32 v22, v33, v22
	v_lshlrev_b32_e32 v46, 16, v25
	v_and_b32_e32 v44, 0xffff0000, v25
	v_pk_mul_f32 v[30:31], v[30:31], v[30:31]
	v_add_f32_e32 v22, v32, v22
	v_mov_b32_e32 v24, v44
	v_mov_b32_e32 v25, v46
	v_add_f32_e32 v22, v31, v22
	v_pk_mul_f32 v[24:25], v[24:25], v[24:25]
	v_add_f32_e32 v22, v30, v22
	v_add_f32_e32 v22, v25, v22
	v_add_f32_e32 v30, v24, v22
	ds_bpermute_b32 v31, v1, v30
	s_waitcnt vmcnt(2)
	v_mov_b32_e32 v112, v60
	v_mov_b32_e32 v113, v100
	s_waitcnt vmcnt(1)
	v_mov_b32_e32 v120, v106
	s_waitcnt vmcnt(0)
	v_mov_b32_e32 v121, v104
	s_waitcnt lgkmcnt(0)
	v_add_f32_e32 v30, v30, v31
	v_fmamk_f32 v30, v30, 0x3c000000, v199
	v_mul_f32_e32 v31, 0x4f800000, v30
	v_cmp_gt_f32_e32 vcc, s76, v30
	v_lshl_add_u64 v[28:29], s[54:55], 0, v[36:37]
	global_load_dwordx4 v[22:25], v[18:19], off
	s_nop 0
	global_load_dwordx4 v[18:21], v[20:21], off
	v_cndmask_b32_e32 v39, v30, v31, vcc
	v_sqrt_f32_e32 v41, v39
	global_load_dwordx4 v[30:33], v[28:29], off
	s_nop 0
	global_load_dwordx4 v[26:29], v[26:27], off
	v_add_u32_e32 v60, -1, v41
	v_fma_f32 v67, -v60, v41, v39
	v_cmp_ge_f32_e64 s[0:1], 0, v67
	v_add_u32_e32 v67, 1, v41
	s_nop 0
	v_cndmask_b32_e64 v60, v41, v60, s[0:1]
	v_fma_f32 v41, -v67, v41, v39
	v_cmp_lt_f32_e64 s[0:1], 0, v41
	s_nop 1
	v_cndmask_b32_e64 v41, v60, v67, s[0:1]
	v_mul_f32_e32 v60, 0x37800000, v41
	v_cndmask_b32_e32 v41, v41, v60, vcc
	v_cmp_class_f32_e32 vcc, v39, v200
	s_nop 1
	v_cndmask_b32_e32 v39, v41, v39, vcc
	v_div_scale_f32 v41, s[0:1], v39, v39, s77
	v_rcp_f32_e32 v60, v41
	s_mov_b32 s0, -1
	v_fma_f32 v67, -v41, v60, 1.0
	v_fmac_f32_e32 v60, v67, v60
	v_div_scale_f32 v67, vcc, s77, v39, s77
	v_mul_f32_e32 v100, v67, v60
	v_fma_f32 v115, -v41, v100, v67
	v_fmac_f32_e32 v100, v115, v60
	v_fma_f32 v41, -v41, v100, v67
	v_div_fmas_f32 v41, v41, v60, v100
	v_div_fixup_f32 v60, v41, v39, s77
	v_pk_mul_f32 v[122:123], v[60:61], v[170:171] op_sel_hi:[0,1]
	v_pk_mul_f32 v[112:113], v[112:113], v[122:123]
	v_mov_b32_e32 v122, v104
	v_mov_b32_e32 v123, v106
	v_pk_mul_f32 v[122:123], v[122:123], v[112:113]
	v_pk_mul_f32 v[112:113], v[120:121], v[112:113]
	v_mov_b32_e32 v100, v61
	v_add_f32_e32 v41, v112, v113
	v_pk_mul_f32 v[112:113], v[60:61], v[116:117] op_sel_hi:[0,1]
	v_pk_mul_f32 v[100:101], v[100:101], v[112:113]
	v_mov_b32_e32 v106, v105
	v_mov_b32_e32 v104, v107
	v_pk_mul_f32 v[112:113], v[106:107], v[100:101]
	v_pk_mul_f32 v[100:101], v[104:105], v[100:101]
	v_sub_f32_e32 v39, v123, v122
	v_sub_f32_e32 v61, v113, v112
	v_add_f32_e32 v67, v100, v101
	v_cvt_pk_bf16_f32 v150, v39, v61
	v_cvt_pk_bf16_f32 v146, v41, v67
	global_load_dwordx2 v[100:101], v42, s[26:27] offset:136
	global_load_dwordx2 v[104:105], v42, s[26:27] offset:8
	global_load_dwordx2 v[106:107], v[78:79], off offset:8
	global_load_dwordx2 v[112:113], v[76:77], off offset:8
	v_pk_mul_f32 v[116:117], v[60:61], v[162:163] op_sel_hi:[0,1]
	s_waitcnt vmcnt(3)
; #define QF(d, e) __uint_as_float(((unsigned)(unsigned short)qr[d][e]) << 16)
; template <typename TQ> ...
;     ...
;     for (int hf = 0; hf < 2; ++hf)
; #pragma unroll
;       for (int dd = 0; dd < 2; ++dd) {
;         const int dl = 4 * hf + dd, du = dl + 2;
;         const int f0 = 16 * dd + 8 * hi;
;         const float* cp = rc + (hf ? pcol : prow) * 32 + f0; const float* sp = rsn + (hf ? pcol : prow) * 32 + f0;
;         const float* gl = gq + 16 * dl + 8 * hi; const float* gu = gq + 16 * du + 8 * hi;
;         unsigned wl[4], wu[4];
; #pragma unroll
;         for (int e = 0; e < 8; e += 2) {
;           float o1[2], o2[2];
; #pragma unroll
;           for (int k = 0; k < 2; ++k) { const float x1 = QF(dl, e + k) * rn * gl[e + k], x2 = QF(du, e + k) * rn * gu[e + k]; const float c = cp[e + k], sn = sp[e + k];
;             o1[k] = x1 * c - x2 * sn; o2[k] = x2 * c + x1 * sn; }
;           wl[e >> 1] = cvtpk(o1[0], o1[1]); wu[e >> 1] = cvtpk(o2[0], o2[1]);
;         }
;         u32x4 vl = {wl[0], wl[1], wl[2], wl[3]}, vu = {wu[0], wu[1], wu[2], wu[3]};
;         qr[dl] = *reinterpret_cast<bf16x8*>(&vl); qr[du] = *reinterpret_cast<bf16x8*>(&vu);
	v_mov_b32_e32 v120, v100
	s_waitcnt vmcnt(2)
	v_mov_b32_e32 v121, v104
	v_pk_mul_f32 v[116:117], v[120:121], v[116:117]
	s_waitcnt vmcnt(1)
	v_mov_b32_e32 v120, v106
	s_waitcnt vmcnt(0)
	v_mov_b32_e32 v121, v112
	v_pk_mul_f32 v[120:121], v[120:121], v[116:117]
	v_mov_b32_e32 v104, v101
	v_sub_f32_e32 v39, v121, v120
	v_mov_b32_e32 v120, v112
	v_mov_b32_e32 v121, v106
	v_pk_mul_f32 v[116:117], v[120:121], v[116:117]
	v_mov_b32_e32 v112, v107
	v_add_f32_e32 v41, v116, v117
	v_pk_mul_f32 v[116:117], v[60:61], v[166:167] op_sel_hi:[0,1]
	v_pk_mul_f32 v[100:101], v[104:105], v[116:117]
	v_mov_b32_e32 v106, v113
	v_pk_mul_f32 v[104:105], v[112:113], v[100:101]
	v_pk_mul_f32 v[100:101], v[106:107], v[100:101]
	v_sub_f32_e32 v61, v105, v104
	v_add_f32_e32 v67, v100, v101
	v_cvt_pk_bf16_f32 v151, v39, v61
	v_cvt_pk_bf16_f32 v147, v41, v67
	global_load_dwordx2 v[100:101], v42, s[26:27] offset:144
	global_load_dwordx2 v[104:105], v42, s[26:27] offset:16
	global_load_dwordx2 v[106:107], v[78:79], off offset:16
	global_load_dwordx2 v[112:113], v[76:77], off offset:16
	v_pk_mul_f32 v[116:117], v[60:61], v[158:159] op_sel_hi:[0,1]
	v_pk_mul_f32 v[118:119], v[60:61], v[118:119] op_sel_hi:[0,1]
	s_waitcnt vmcnt(3)
	v_mov_b32_e32 v120, v100
	s_waitcnt vmcnt(2)
	v_mov_b32_e32 v121, v104
	v_mov_b32_e32 v104, v101
	s_waitcnt vmcnt(1)
	v_mov_b32_e32 v122, v106
	s_waitcnt vmcnt(0)
	v_mov_b32_e32 v123, v112
	v_mov_b32_e32 v124, v112
	v_mov_b32_e32 v125, v106
	v_mov_b32_e32 v112, v107
	v_mov_b32_e32 v106, v113
	v_pk_mul_f32 v[100:101], v[120:121], v[116:117]
	v_pk_mul_f32 v[104:105], v[104:105], v[118:119]
	v_pk_mul_f32 v[116:117], v[122:123], v[100:101]
	v_pk_mul_f32 v[100:101], v[124:125], v[100:101]
	v_pk_mul_f32 v[112:113], v[112:113], v[104:105]
	v_pk_mul_f32 v[104:105], v[106:107], v[104:105]
	v_sub_f32_e32 v39, v117, v116
	v_add_f32_e32 v41, v100, v101
	v_sub_f32_e32 v61, v113, v112
	v_add_f32_e32 v67, v104, v105
	v_cvt_pk_bf16_f32 v152, v39, v61
	v_cvt_pk_bf16_f32 v148, v41, v67
	global_load_dwordx2 v[100:101], v42, s[26:27] offset:152
	global_load_dwordx2 v[104:105], v42, s[26:27] offset:24
	global_load_dwordx2 v[106:107], v[78:79], off offset:24
	global_load_dwordx2 v[112:113], v[76:77], off offset:24
	v_pk_mul_f32 v[108:109], v[60:61], v[108:109] op_sel_hi:[0,1]
	v_pk_mul_f32 v[102:103], v[60:61], v[102:103] op_sel_hi:[0,1]
	s_waitcnt vmcnt(3)
	v_mov_b32_e32 v116, v100
	s_waitcnt vmcnt(2)
	v_mov_b32_e32 v117, v104
	v_mov_b32_e32 v104, v101
	s_waitcnt vmcnt(1)
	v_mov_b32_e32 v118, v106
	s_waitcnt vmcnt(0)
	v_mov_b32_e32 v119, v112
	v_mov_b32_e32 v120, v112
	v_mov_b32_e32 v121, v106
	v_mov_b32_e32 v112, v107
	v_mov_b32_e32 v106, v113
	v_pk_mul_f32 v[100:101], v[116:117], v[108:109]
	v_pk_mul_f32 v[102:103], v[104:105], v[102:103]
	v_pk_mul_f32 v[104:105], v[118:119], v[100:101]
	v_pk_mul_f32 v[100:101], v[120:121], v[100:101]
	v_pk_mul_f32 v[108:109], v[112:113], v[102:103]
	v_pk_mul_f32 v[102:103], v[106:107], v[102:103]
	v_sub_f32_e32 v39, v105, v104
	v_add_f32_e32 v41, v100, v101
	v_sub_f32_e32 v61, v109, v108
	v_add_f32_e32 v67, v102, v103
	v_cvt_pk_bf16_f32 v153, v39, v61
	v_cvt_pk_bf16_f32 v149, v41, v67
	global_load_dwordx2 v[100:101], v42, s[26:27] offset:192
	global_load_dwordx2 v[102:103], v42, s[26:27] offset:64
	global_load_dwordx2 v[104:105], v[78:79], off offset:64
	global_load_dwordx2 v[106:107], v[76:77], off offset:64
	v_pk_mul_f32 v[98:99], v[60:61], v[98:99] op_sel_hi:[0,1]
	v_pk_mul_f32 v[96:97], v[60:61], v[96:97] op_sel_hi:[0,1]
	s_waitcnt vmcnt(3)
	v_mov_b32_e32 v108, v100
	s_waitcnt vmcnt(2)
	v_mov_b32_e32 v109, v102
	v_mov_b32_e32 v102, v101
	s_waitcnt vmcnt(1)
	v_mov_b32_e32 v112, v104
	s_waitcnt vmcnt(0)
	v_mov_b32_e32 v113, v106
	v_mov_b32_e32 v116, v106
	v_mov_b32_e32 v117, v104
	v_mov_b32_e32 v106, v105
	v_mov_b32_e32 v104, v107
	v_pk_mul_f32 v[98:99], v[108:109], v[98:99]
	v_pk_mul_f32 v[96:97], v[102:103], v[96:97]
	v_pk_mul_f32 v[100:101], v[112:113], v[98:99]
	v_pk_mul_f32 v[98:99], v[116:117], v[98:99]
	v_pk_mul_f32 v[102:103], v[106:107], v[96:97]
	v_pk_mul_f32 v[96:97], v[104:105], v[96:97]
	v_sub_f32_e32 v39, v101, v100
	v_add_f32_e32 v41, v98, v99
	v_sub_f32_e32 v61, v103, v102
	v_add_f32_e32 v67, v96, v97
	v_cvt_pk_bf16_f32 v158, v39, v61
	v_cvt_pk_bf16_f32 v154, v41, v67
	global_load_dwordx2 v[96:97], v42, s[26:27] offset:200
	global_load_dwordx2 v[98:99], v42, s[26:27] offset:72
	global_load_dwordx2 v[100:101], v[78:79], off offset:72
	global_load_dwordx2 v[102:103], v[76:77], off offset:72
	v_pk_mul_f32 v[94:95], v[60:61], v[94:95] op_sel_hi:[0,1]
	v_pk_mul_f32 v[92:93], v[60:61], v[92:93] op_sel_hi:[0,1]
	s_waitcnt vmcnt(3)
	v_mov_b32_e32 v104, v96
	s_waitcnt vmcnt(2)
	v_mov_b32_e32 v105, v98
	v_mov_b32_e32 v98, v97
	s_waitcnt vmcnt(1)
	v_mov_b32_e32 v106, v100
	s_waitcnt vmcnt(0)
	v_mov_b32_e32 v107, v102
	v_mov_b32_e32 v108, v102
	v_mov_b32_e32 v109, v100
	v_mov_b32_e32 v102, v101
	v_mov_b32_e32 v100, v103
	v_pk_mul_f32 v[94:95], v[104:105], v[94:95]
	v_pk_mul_f32 v[92:93], v[98:99], v[92:93]
	v_pk_mul_f32 v[96:97], v[106:107], v[94:95]
	v_pk_mul_f32 v[94:95], v[108:109], v[94:95]
	v_pk_mul_f32 v[98:99], v[102:103], v[92:93]
	v_pk_mul_f32 v[92:93], v[100:101], v[92:93]
	v_sub_f32_e32 v39, v97, v96
	v_add_f32_e32 v41, v94, v95
	v_sub_f32_e32 v61, v99, v98
	v_add_f32_e32 v67, v92, v93
	v_cvt_pk_bf16_f32 v159, v39, v61
	v_cvt_pk_bf16_f32 v155, v41, v67
	global_load_dwordx2 v[92:93], v42, s[26:27] offset:208
	global_load_dwordx2 v[94:95], v42, s[26:27] offset:80
	global_load_dwordx2 v[96:97], v[78:79], off offset:80
	global_load_dwordx2 v[98:99], v[76:77], off offset:80
	v_pk_mul_f32 v[90:91], v[60:61], v[90:91] op_sel_hi:[0,1]
	v_pk_mul_f32 v[88:89], v[60:61], v[88:89] op_sel_hi:[0,1]
	s_waitcnt vmcnt(3)
; #define QF(d, e) __uint_as_float(((unsigned)(unsigned short)qr[d][e]) << 16)
; template <typename TQ> ...
;     ...
;     for (int hf = 0; hf < 2; ++hf)
; #pragma unroll
;       for (int dd = 0; dd < 2; ++dd) {
;         const int dl = 4 * hf + dd, du = dl + 2;
;         const int f0 = 16 * dd + 8 * hi;
;         const float* cp = rc + (hf ? pcol : prow) * 32 + f0; const float* sp = rsn + (hf ? pcol : prow) * 32 + f0;
;         const float* gl = gq + 16 * dl + 8 * hi; const float* gu = gq + 16 * du + 8 * hi;
;         unsigned wl[4], wu[4];
; #pragma unroll
;         for (int e = 0; e < 8; e += 2) {
;           float o1[2], o2[2];
; #pragma unroll
;           for (int k = 0; k < 2; ++k) { const float x1 = QF(dl, e + k) * rn * gl[e + k], x2 = QF(du, e + k) * rn * gu[e + k]; const float c = cp[e + k], sn = sp[e + k];
;             o1[k] = x1 * c - x2 * sn; o2[k] = x2 * c + x1 * sn; }
;           wl[e >> 1] = cvtpk(o1[0], o1[1]); wu[e >> 1] = cvtpk(o2[0], o2[1]);
;         }
;         u32x4 vl = {wl[0], wl[1], wl[2], wl[3]}, vu = {wu[0], wu[1], wu[2], wu[3]};
;         qr[dl] = *reinterpret_cast<bf16x8*>(&vl); qr[du] = *reinterpret_cast<bf16x8*>(&vu);
	v_mov_b32_e32 v100, v92
	s_waitcnt vmcnt(2)
	v_mov_b32_e32 v101, v94
	v_mov_b32_e32 v94, v93
	s_waitcnt vmcnt(1)
	v_mov_b32_e32 v102, v96
	s_waitcnt vmcnt(0)
	v_mov_b32_e32 v103, v98
	v_mov_b32_e32 v104, v98
	v_mov_b32_e32 v105, v96
	v_mov_b32_e32 v98, v97
	v_mov_b32_e32 v96, v99
	v_pk_mul_f32 v[90:91], v[90:91], v[100:101]
	v_pk_mul_f32 v[88:89], v[88:89], v[94:95]
	v_pk_mul_f32 v[92:93], v[90:91], v[102:103]
	v_pk_mul_f32 v[90:91], v[90:91], v[104:105]
	v_pk_mul_f32 v[94:95], v[88:89], v[98:99]
	v_pk_mul_f32 v[88:89], v[88:89], v[96:97]
	v_sub_f32_e32 v39, v93, v92
	v_add_f32_e32 v41, v90, v91
	v_sub_f32_e32 v61, v95, v94
	v_add_f32_e32 v67, v88, v89
	v_cvt_pk_bf16_f32 v160, v39, v61
	v_cvt_pk_bf16_f32 v156, v41, v67
	global_load_dwordx2 v[88:89], v42, s[26:27] offset:216
	global_load_dwordx2 v[90:91], v42, s[26:27] offset:88
	s_nop 0
	global_load_dwordx2 v[78:79], v[78:79], off offset:88
	s_nop 0
	global_load_dwordx2 v[76:77], v[76:77], off offset:88
	v_lshlrev_b32_e32 v39, 7, v66
	v_mov_b32_e32 v67, v195
	v_and_b32_e32 v66, 0x1f80, v39
	v_lshl_add_u64 v[92:93], s[4:5], 0, v[66:67]
	v_lshl_add_u64 v[94:95], s[6:7], 0, v[66:67]
	v_lshl_add_u64 v[66:67], v[92:93], 0, v[42:43]
	v_pk_mul_f32 v[84:85], v[60:61], v[84:85] op_sel_hi:[0,1]
	v_pk_mul_f32 v[86:87], v[60:61], v[86:87] op_sel_hi:[0,1]
	s_waitcnt vmcnt(3)
	v_mov_b32_e32 v92, v88
	s_waitcnt vmcnt(2)
	v_mov_b32_e32 v93, v90
	v_mov_b32_e32 v90, v89
	s_waitcnt vmcnt(1)
	v_mov_b32_e32 v96, v78
	s_waitcnt vmcnt(0)
	v_mov_b32_e32 v97, v76
	v_mov_b32_e32 v98, v76
	v_mov_b32_e32 v99, v78
	v_mov_b32_e32 v76, v79
	v_mov_b32_e32 v78, v77
	v_pk_mul_f32 v[84:85], v[84:85], v[90:91]
	v_pk_mul_f32 v[86:87], v[86:87], v[92:93]
	v_pk_mul_f32 v[76:77], v[84:85], v[76:77]
	v_pk_mul_f32 v[78:79], v[84:85], v[78:79]
	v_pk_mul_f32 v[88:89], v[86:87], v[96:97]
	v_pk_mul_f32 v[86:87], v[86:87], v[98:99]
	v_sub_f32_e32 v61, v77, v76
	v_add_f32_e32 v76, v78, v79
	v_sub_f32_e32 v39, v89, v88
	v_add_f32_e32 v41, v86, v87
	v_cvt_pk_bf16_f32 v161, v39, v61
	v_cvt_pk_bf16_f32 v157, v41, v76
	global_load_dwordx2 v[78:79], v42, s[26:27] offset:256
	global_load_dwordx2 v[84:85], v42, s[26:27] offset:384
	v_lshl_add_u64 v[76:77], v[94:95], 0, v[42:43]
	global_load_dwordx2 v[86:87], v[76:77], off
	global_load_dwordx2 v[88:89], v[66:67], off
	v_pk_mul_f32 v[82:83], v[60:61], v[82:83] op_sel_hi:[0,1]
	v_pk_mul_f32 v[80:81], v[60:61], v[80:81] op_sel_hi:[0,1]
	s_waitcnt vmcnt(3)
	v_mov_b32_e32 v91, v78
	s_waitcnt vmcnt(2)
	v_mov_b32_e32 v90, v84
	v_mov_b32_e32 v78, v85
	s_waitcnt vmcnt(1)
	v_mov_b32_e32 v92, v86
	s_waitcnt vmcnt(0)
	v_mov_b32_e32 v93, v88
	v_mov_b32_e32 v94, v88
	v_mov_b32_e32 v95, v86
	v_mov_b32_e32 v88, v87
	v_mov_b32_e32 v86, v89
	v_pk_mul_f32 v[82:83], v[82:83], v[90:91]
	v_pk_mul_f32 v[78:79], v[80:81], v[78:79]
	v_pk_mul_f32 v[80:81], v[82:83], v[92:93]
	v_pk_mul_f32 v[82:83], v[82:83], v[94:95]
	v_pk_mul_f32 v[84:85], v[78:79], v[88:89]
	v_pk_mul_f32 v[78:79], v[78:79], v[86:87]
	v_sub_f32_e32 v39, v81, v80
	v_add_f32_e32 v41, v82, v83
	v_sub_f32_e32 v43, v85, v84
	v_add_f32_e32 v61, v78, v79
	v_cvt_pk_bf16_f32 v166, v39, v43
	v_cvt_pk_bf16_f32 v162, v41, v61
	global_load_dwordx2 v[78:79], v42, s[26:27] offset:392
	global_load_dwordx2 v[80:81], v42, s[26:27] offset:264
	global_load_dwordx2 v[82:83], v[76:77], off offset:8
	global_load_dwordx2 v[84:85], v[66:67], off offset:8
	v_pk_mul_f32 v[74:75], v[60:61], v[74:75] op_sel_hi:[0,1]
	v_pk_mul_f32 v[72:73], v[60:61], v[72:73] op_sel_hi:[0,1]
	s_waitcnt vmcnt(3)
	v_mov_b32_e32 v86, v78
	s_waitcnt vmcnt(2)
	v_mov_b32_e32 v87, v80
	v_mov_b32_e32 v80, v79
	s_waitcnt vmcnt(1)
	v_mov_b32_e32 v88, v82
	s_waitcnt vmcnt(0)
	v_mov_b32_e32 v89, v84
	v_mov_b32_e32 v90, v84
	v_mov_b32_e32 v91, v82
	v_mov_b32_e32 v84, v83
	v_mov_b32_e32 v82, v85
	v_pk_mul_f32 v[74:75], v[74:75], v[86:87]
	v_pk_mul_f32 v[72:73], v[72:73], v[80:81]
	v_pk_mul_f32 v[78:79], v[74:75], v[88:89]
	v_pk_mul_f32 v[74:75], v[74:75], v[90:91]
	v_pk_mul_f32 v[80:81], v[72:73], v[84:85]
	v_pk_mul_f32 v[72:73], v[72:73], v[82:83]
	v_sub_f32_e32 v39, v79, v78
	v_add_f32_e32 v41, v74, v75
	v_sub_f32_e32 v43, v81, v80
	v_add_f32_e32 v61, v72, v73
	v_cvt_pk_bf16_f32 v167, v39, v43
	v_cvt_pk_bf16_f32 v163, v41, v61
	global_load_dwordx2 v[72:73], v42, s[26:27] offset:400
	global_load_dwordx2 v[74:75], v42, s[26:27] offset:272
	global_load_dwordx2 v[78:79], v[76:77], off offset:16
	global_load_dwordx2 v[80:81], v[66:67], off offset:16
	v_pk_mul_f32 v[70:71], v[60:61], v[70:71] op_sel_hi:[0,1]
	v_pk_mul_f32 v[68:69], v[60:61], v[68:69] op_sel_hi:[0,1]
	s_waitcnt vmcnt(3)
	v_mov_b32_e32 v82, v72
	s_waitcnt vmcnt(2)
	v_mov_b32_e32 v83, v74
	v_mov_b32_e32 v74, v73
	s_waitcnt vmcnt(1)
	v_mov_b32_e32 v84, v78
	s_waitcnt vmcnt(0)
	v_mov_b32_e32 v85, v80
	v_mov_b32_e32 v86, v80
	v_mov_b32_e32 v87, v78
	v_mov_b32_e32 v80, v79
	v_mov_b32_e32 v78, v81
	v_pk_mul_f32 v[70:71], v[70:71], v[82:83]
	v_pk_mul_f32 v[68:69], v[68:69], v[74:75]
	v_pk_mul_f32 v[72:73], v[70:71], v[84:85]
	v_pk_mul_f32 v[70:71], v[70:71], v[86:87]
	v_pk_mul_f32 v[74:75], v[68:69], v[80:81]
	v_pk_mul_f32 v[68:69], v[68:69], v[78:79]
	v_sub_f32_e32 v39, v73, v72
	v_add_f32_e32 v41, v70, v71
	v_sub_f32_e32 v43, v75, v74
	v_add_f32_e32 v61, v68, v69
	v_cvt_pk_bf16_f32 v168, v39, v43
	v_cvt_pk_bf16_f32 v164, v41, v61
	global_load_dwordx2 v[68:69], v42, s[26:27] offset:280
	global_load_dwordx2 v[70:71], v42, s[26:27] offset:408
	global_load_dwordx2 v[72:73], v[66:67], off offset:24
	global_load_dwordx2 v[74:75], v[76:77], off offset:24
	v_pk_mul_f32 v[64:65], v[60:61], v[64:65] op_sel_hi:[0,1]
	v_pk_mul_f32 v[62:63], v[60:61], v[62:63] op_sel_hi:[0,1]
	s_waitcnt vmcnt(3)
; #define SBAR() __builtin_amdgcn_sched_barrier(0)
; #define QF(d, e) __uint_as_float(((unsigned)(unsigned short)qr[d][e]) << 16)
; template <typename TQ> ...
;     ...
;         for (int e = 0; e < 8; e += 2) {
;           float o1[2], o2[2];
; #pragma unroll
;           for (int k = 0; k < 2; ++k) { const float x1 = QF(dl, e + k) * rn * gl[e + k], x2 = QF(du, e + k) * rn * gu[e + k]; const float c = cp[e + k], sn = sp[e + k];
;             o1[k] = x1 * c - x2 * sn; o2[k] = x2 * c + x1 * sn; }
;           wl[e >> 1] = cvtpk(o1[0], o1[1]); wu[e >> 1] = cvtpk(o2[0], o2[1]);
;         }
;         u32x4 vl = {wl[0], wl[1], wl[2], wl[3]}, vu = {wu[0], wu[1], wu[2], wu[3]};
;         qr[dl] = *reinterpret_cast<bf16x8*>(&vl); qr[du] = *reinterpret_cast<bf16x8*>(&vu);
;       }
;   }
;     ...
;   SBAR();
;   f32x16 pA0, pA1, pB0, pB1; bf16x8 pa0, pa1, pa2, pa3; const int NT = seq / KVBLK;
;   f32x16 negm;
; #pragma unroll
;   for (int r = 0; r < 16; ++r) negm[r] = -mC;
;   asm volatile("" : "+v"(negm));
;   asm volatile("s_waitcnt vmcnt(0)" ::: "memory"); SWRITE(0, SE); __syncthreads();
	v_mov_b32_e32 v78, v68
	s_waitcnt vmcnt(2)
	v_mov_b32_e32 v79, v70
	v_mov_b32_e32 v70, v69
	s_waitcnt vmcnt(1)
	v_mov_b32_e32 v80, v72
	s_waitcnt vmcnt(0)
	v_mov_b32_e32 v81, v74
	v_mov_b32_e32 v82, v74
	v_mov_b32_e32 v83, v72
	v_mov_b32_e32 v74, v73
	v_mov_b32_e32 v72, v75
	v_pk_mul_f32 v[64:65], v[64:65], v[78:79]
	v_pk_mul_f32 v[62:63], v[62:63], v[70:71]
	v_pk_mul_f32 v[68:69], v[64:65], v[80:81]
	v_pk_mul_f32 v[64:65], v[64:65], v[82:83]
	v_pk_mul_f32 v[70:71], v[62:63], v[74:75]
	v_pk_mul_f32 v[62:63], v[62:63], v[72:73]
	v_sub_f32_e32 v39, v68, v69
	v_add_f32_e32 v41, v65, v64
	v_sub_f32_e32 v43, v70, v71
	v_add_f32_e32 v61, v63, v62
	v_cvt_pk_bf16_f32 v169, v39, v43
	v_cvt_pk_bf16_f32 v165, v41, v61
	global_load_dwordx2 v[62:63], v42, s[26:27] offset:448
	global_load_dwordx2 v[64:65], v42, s[26:27] offset:320
	global_load_dwordx2 v[68:69], v[76:77], off offset:64
	global_load_dwordx2 v[70:71], v[66:67], off offset:64
	v_pk_mul_f32 v[56:57], v[60:61], v[56:57] op_sel_hi:[0,1]
	v_pk_mul_f32 v[58:59], v[60:61], v[58:59] op_sel_hi:[0,1]
	v_pk_mul_f32 v[52:53], v[60:61], v[52:53] op_sel_hi:[0,1]
	v_pk_mul_f32 v[54:55], v[60:61], v[54:55] op_sel_hi:[0,1]
	v_pk_mul_f32 v[48:49], v[60:61], v[48:49] op_sel_hi:[0,1]
	v_pk_mul_f32 v[50:51], v[60:61], v[50:51] op_sel_hi:[0,1]
	s_waitcnt vmcnt(3)
	v_mov_b32_e32 v72, v62
	s_waitcnt vmcnt(2)
	v_mov_b32_e32 v73, v64
	v_mov_b32_e32 v64, v63
	s_waitcnt vmcnt(1)
	v_mov_b32_e32 v74, v68
	s_waitcnt vmcnt(0)
	v_mov_b32_e32 v75, v70
	v_mov_b32_e32 v78, v70
	v_mov_b32_e32 v79, v68
	v_mov_b32_e32 v70, v69
	v_mov_b32_e32 v68, v71
	v_pk_mul_f32 v[56:57], v[56:57], v[72:73]
	v_pk_mul_f32 v[58:59], v[58:59], v[64:65]
	v_pk_mul_f32 v[62:63], v[56:57], v[74:75]
	v_pk_mul_f32 v[56:57], v[56:57], v[78:79]
	v_pk_mul_f32 v[64:65], v[58:59], v[70:71]
	v_pk_mul_f32 v[58:59], v[58:59], v[68:69]
	v_add_f32_e32 v41, v56, v57
	v_add_f32_e32 v56, v58, v59
	v_sub_f32_e32 v39, v63, v62
	v_sub_f32_e32 v43, v65, v64
	v_cvt_pk_bf16_f32 v174, v39, v43
	v_cvt_pk_bf16_f32 v170, v41, v56
	global_load_dwordx2 v[56:57], v42, s[26:27] offset:456
	global_load_dwordx2 v[58:59], v42, s[26:27] offset:328
	global_load_dwordx2 v[62:63], v[76:77], off offset:72
	global_load_dwordx2 v[64:65], v[66:67], off offset:72
	s_waitcnt vmcnt(3)
	v_mov_b32_e32 v68, v56
	s_waitcnt vmcnt(2)
	v_mov_b32_e32 v69, v58
	v_mov_b32_e32 v58, v57
	s_waitcnt vmcnt(1)
	v_mov_b32_e32 v70, v62
	s_waitcnt vmcnt(0)
	v_mov_b32_e32 v71, v64
	v_mov_b32_e32 v72, v64
	v_mov_b32_e32 v73, v62
	v_mov_b32_e32 v64, v63
	v_mov_b32_e32 v62, v65
	v_pk_mul_f32 v[52:53], v[52:53], v[58:59]
	v_pk_mul_f32 v[54:55], v[54:55], v[68:69]
	v_pk_mul_f32 v[58:59], v[52:53], v[64:65]
	v_pk_mul_f32 v[52:53], v[52:53], v[62:63]
	v_pk_mul_f32 v[56:57], v[54:55], v[70:71]
	v_pk_mul_f32 v[54:55], v[54:55], v[72:73]
	v_add_f32_e32 v52, v52, v53
	v_sub_f32_e32 v39, v57, v56
	v_add_f32_e32 v41, v54, v55
	v_sub_f32_e32 v43, v59, v58
	v_cvt_pk_bf16_f32 v175, v39, v43
	v_cvt_pk_bf16_f32 v171, v41, v52
	global_load_dwordx2 v[52:53], v42, s[26:27] offset:464
	global_load_dwordx2 v[54:55], v42, s[26:27] offset:336
	global_load_dwordx2 v[56:57], v[76:77], off offset:80
	global_load_dwordx2 v[58:59], v[66:67], off offset:80
	s_waitcnt vmcnt(3)
	v_mov_b32_e32 v62, v52
	s_waitcnt vmcnt(2)
	v_mov_b32_e32 v63, v54
	v_mov_b32_e32 v54, v53
	s_waitcnt vmcnt(1)
	v_mov_b32_e32 v64, v56
	s_waitcnt vmcnt(0)
	v_mov_b32_e32 v65, v58
	v_mov_b32_e32 v68, v58
	v_mov_b32_e32 v69, v56
	v_mov_b32_e32 v58, v57
	v_mov_b32_e32 v56, v59
	v_pk_mul_f32 v[48:49], v[48:49], v[54:55]
	v_pk_mul_f32 v[50:51], v[50:51], v[62:63]
	v_pk_mul_f32 v[54:55], v[48:49], v[58:59]
	v_pk_mul_f32 v[48:49], v[48:49], v[56:57]
	v_pk_mul_f32 v[52:53], v[50:51], v[64:65]
	v_pk_mul_f32 v[50:51], v[50:51], v[68:69]
	v_sub_f32_e32 v43, v55, v54
	v_add_f32_e32 v48, v48, v49
	v_sub_f32_e32 v39, v53, v52
	v_add_f32_e32 v41, v50, v51
	v_cvt_pk_bf16_f32 v176, v39, v43
	v_cvt_pk_bf16_f32 v172, v41, v48
	global_load_dwordx2 v[48:49], v42, s[26:27] offset:472
	s_nop 0
	global_load_dwordx2 v[42:43], v42, s[26:27] offset:344
	s_nop 0
	global_load_dwordx2 v[50:51], v[76:77], off offset:88
	global_load_dwordx2 v[52:53], v[66:67], off offset:88
	v_and_b32_e32 v54, 0xfffff0, v38
	v_lshlrev_b32_e32 v55, 1, v38
	v_lshrrev_b32_e32 v56, 1, v38
	v_and_b32_e32 v58, 3, v38
	v_lshlrev_b32_e32 v39, 4, v114
	v_and_or_b32 v54, v55, 8, v54
	v_and_or_b32 v55, v56, 4, v58
	v_and_b32_e32 v56, 0xfffff0, v40
	v_lshlrev_b32_e32 v58, 1, v40
	v_lshlrev_b32_e32 v41, 1, v114
	v_bfe_u32 v57, v111, 5, 2
	v_lshlrev_b32_e32 v59, 3, v203
	v_and_b32_e32 v61, 0xc0, v39
	v_lshrrev_b32_e32 v54, 1, v54
	v_lshlrev_b32_e32 v62, 6, v55
	v_and_or_b32 v55, v58, 8, v56
	v_and_b32_e32 v41, 32, v41
	v_and_or_b32 v61, v59, 24, v61
	v_and_b32_e32 v59, 0x100, v59
	v_or_b32_e32 v54, v54, v57
	v_lshrrev_b32_e32 v55, 1, v55
	v_or3_b32 v76, v61, v41, v59
	v_lshlrev_b32_e32 v61, 9, v54
	v_or_b32_e32 v54, v55, v57
	v_and_b32_e32 v41, 48, v110
	v_lshlrev_b32_e32 v54, 9, v54
	v_or3_b32 v63, v54, v62, v41
	v_pk_mul_f32 v[46:47], v[60:61], v[46:47] op_sel_hi:[0,1]
	v_pk_mul_f32 v[44:45], v[60:61], v[44:45] op_sel_hi:[0,1]
	v_or3_b32 v41, v61, v62, v41
	s_waitcnt vmcnt(3)
	v_mov_b32_e32 v54, v48
	s_waitcnt vmcnt(2)
	v_mov_b32_e32 v55, v42
	v_mov_b32_e32 v42, v49
	s_waitcnt vmcnt(1)
	v_mov_b32_e32 v56, v50
	s_waitcnt vmcnt(0)
	v_mov_b32_e32 v57, v52
	v_mov_b32_e32 v58, v52
	v_mov_b32_e32 v59, v50
	v_mov_b32_e32 v52, v51
	v_mov_b32_e32 v50, v53
	v_pk_mul_f32 v[46:47], v[46:47], v[54:55]
	v_pk_mul_f32 v[42:43], v[44:45], v[42:43]
	v_pk_mul_f32 v[44:45], v[46:47], v[56:57]
	v_pk_mul_f32 v[46:47], v[46:47], v[58:59]
	v_pk_mul_f32 v[48:49], v[42:43], v[52:53]
	v_pk_mul_f32 v[42:43], v[42:43], v[50:51]
	v_sub_f32_e32 v44, v45, v44
	v_add_f32_e32 v45, v46, v47
	v_sub_f32_e32 v46, v49, v48
	v_add_f32_e32 v42, v42, v43
	v_cvt_pk_bf16_f32 v177, v44, v46
	v_cvt_pk_bf16_f32 v173, v45, v42
	v_mov_b64_e32 v[96:97], v[16:17]
	v_mov_b64_e32 v[94:95], v[14:15]
	v_mov_b64_e32 v[92:93], v[12:13]
	v_mov_b64_e32 v[90:91], v[10:11]
	v_mov_b64_e32 v[88:89], v[8:9]
	v_mov_b64_e32 v[86:87], v[6:7]
	v_mov_b64_e32 v[84:85], v[4:5]
	v_mov_b64_e32 v[82:83], v[2:3]
	v_add_u32_e32 v207, 0, v41
	v_add_u32_e32 v208, 0, v63
	s_waitcnt vmcnt(0)
	ds_write_b128 v207, v[22:25]
	ds_write_b128 v208, v[18:21]
	v_lshlrev_b32_e32 v18, 8, v38
	v_and_b32_e32 v19, 0xf0, v114
	v_bitop3_b32 v18, v110, v18, v19 bitop3:0xde
	v_add_u32_e32 v209, 0x10000, v18
	v_lshlrev_b32_e32 v18, 8, v40
	v_bitop3_b32 v18, v110, v18, v19 bitop3:0xde
	v_lshlrev_b32_e32 v56, 8, v202
	v_and_b32_e32 v57, 0xf0, v39
	v_add_u32_e32 v211, 0x10000, v18
	v_bitop3_b32 v18, v194, v56, v57 bitop3:0xde
	v_add_u32_e32 v210, 0x10000, v18
	ds_write_b128 v209, v[30:33] offset:0
	ds_write_b128 v211, v[26:29] offset:0
	s_waitcnt lgkmcnt(0)
	s_barrier
; #define SLOAD(i, k0) do { sr_[i].vs0 = St::ld8(&Vh[(long)((k0) + sr) * LDK + sc]); sr_[i].vs1 = St::ld8(&Vh[(long)((k0) + 32 + sr) * LDK + sc]); \
;     sr_[i].ks0 = St::ld8(&Kh[(long)((k0) + sr) * LDK + sc]); sr_[i].ks1 = St::ld8(&Kh[(long)((k0) + 32 + sr) * LDK + sc]); } while (0)
; #define SWAIT() do { if constexpr (SDEPTH == 2) asm volatile("s_waitcnt vmcnt(4)" ::: "memory"); else asm volatile("s_waitcnt vmcnt(0)" ::: "memory"); } while (0)
; __device__ __forceinline__ void qkt(f32x16& p0, f32x16& p1, const bf16* Ks, const bf16x8* qr, int r32, int hi, const f32x16& negm) {
; #pragma unroll
;   for (int d0 = 0; d0 < 8; ++d0) { int cb = (d0 * 16 + hi * 8) * 2;
;     bf16x8 b0 = *reinterpret_cast<const bf16x8*>((const char*)Ks + KSWZ(r32, cb));
;     bf16x8 b1 = *reinterpret_cast<const bf16x8*>((const char*)Ks + KSWZ(32 + r32, cb));
;     if (d0 == 0) { p0 = __builtin_amdgcn_mfma_f32_32x32x16_bf16(b0, qr[0], negm, 0, 0, 0); p1 = __builtin_amdgcn_mfma_f32_32x32x16_bf16(b1, qr[0], negm, 0, 0, 0); }
;     else { p0 = __builtin_amdgcn_mfma_f32_32x32x16_bf16(b0, qr[d0], p0, 0, 0, 0); p1 = __builtin_amdgcn_mfma_f32_32x32x16_bf16(b1, qr[d0], p1, 0, 0, 0); } }
; template <typename TQ> ...
;     ...
;   qkt(pA0, pA1, K_lds, qr, r32, hi, negm); partialSM(pA0, pA1, mC);
;   SLOAD(SO, KVBLK); if constexpr (SDEPTH == 2) { if (2 < NT) SLOAD(SE, 2 * KVBLK); }
;   SWAIT(); SWRITE(1, SO); __syncthreads();
	ds_read_b128 v[38:41], v210 offset:0
	s_waitcnt lgkmcnt(0)
	v_mfma_f32_32x32x16_bf16 v[18:33], v[38:41], v[150:153], v[82:97]
	ds_read_b128 v[38:41], v210 offset:8192
	v_or_b32_e32 v52, 0x80, v194
	v_lshl_add_u64 v[44:45], v[36:37], 0, s[10:11]
	v_lshl_add_u64 v[46:47], v[36:37], 0, s[24:25]
	v_bitop3_b32 v52, v52, v56, v57 bitop3:0xde
	v_lshl_add_u64 v[42:43], s[64:65], 0, v[44:45]
	v_lshl_add_u64 v[44:45], s[54:55], 0, v[44:45]
	s_waitcnt lgkmcnt(0)
	v_mfma_f32_32x32x16_bf16 v[98:113], v[38:41], v[150:153], v[82:97]
	v_or_b32_e32 v38, 32, v194
	v_bitop3_b32 v38, v38, v56, v57 bitop3:0xde
	v_add_u32_e32 v212, 0x10000, v38
	ds_read_b128 v[38:41], v212 offset:0
	v_lshl_add_u64 v[48:49], s[54:55], 0, v[46:47]
	v_add_u32_e32 v218, 0x10000, v52
	v_or_b32_e32 v58, 0xe0, v194
	s_waitcnt lgkmcnt(0)
	v_mfma_f32_32x32x16_bf16 v[18:33], v[38:41], v[158:161], v[18:33]
	ds_read_b128 v[38:41], v212 offset:8192
	s_cmp_lg_u32 0, -1
	s_cselect_b32 s1, 0, 0
	v_add_u32_e32 v206, s1, v76
	s_addk_i32 s1, 0x4000
	v_add_u32_e32 v204, s1, v76
	v_mov_b32_e32 v76, v205
	s_waitcnt lgkmcnt(0)
	v_mfma_f32_32x32x16_bf16 v[98:113], v[38:41], v[158:161], v[98:113]
	v_or_b32_e32 v38, 64, v194
	v_bitop3_b32 v38, v38, v56, v57 bitop3:0xde
	v_add_u32_e32 v213, 0x10000, v38
	ds_read_b128 v[38:41], v213 offset:0
	v_mov_b32_e32 v77, v205
	v_mov_b32_e32 v78, v205
	v_mov_b32_e32 v79, v205
	s_waitcnt lgkmcnt(0)
	v_mfma_f32_32x32x16_bf16 v[18:33], v[38:41], v[146:149], v[18:33]
	v_or_b32_e32 v38, 0x60, v194
	v_bitop3_b32 v38, v38, v56, v57 bitop3:0xde
	v_add_u32_e32 v214, 0x10000, v38
	ds_read_b128 v[38:41], v214 offset:0
	v_mov_b32_e32 v80, v205
	v_mov_b32_e32 v81, v205
	s_waitcnt lgkmcnt(0)
	v_mfma_f32_32x32x16_bf16 v[18:33], v[38:41], v[154:157], v[18:33]
	v_lshl_add_u64 v[40:41], s[64:65], 0, v[46:47]
	global_load_dwordx4 v[36:39], v[42:43], off
	s_nop 0
	global_load_dwordx4 v[40:43], v[40:41], off
	s_nop 0
	global_load_dwordx4 v[44:47], v[44:45], off
	s_nop 0
	global_load_dwordx4 v[48:51], v[48:49], off
	ds_read_b128 v[52:55], v218 offset:0
	s_waitcnt lgkmcnt(0)
	v_mfma_f32_32x32x16_bf16 v[18:33], v[52:55], v[166:169], v[18:33]
	v_or_b32_e32 v52, 0xa0, v194
	v_bitop3_b32 v52, v52, v56, v57 bitop3:0xde
	v_add_u32_e32 v217, 0x10000, v52
	ds_read_b128 v[52:55], v217 offset:0
	s_waitcnt lgkmcnt(0)
	v_mfma_f32_32x32x16_bf16 v[18:33], v[52:55], v[174:177], v[18:33]
	v_or_b32_e32 v52, 0xc0, v194
	v_bitop3_b32 v52, v52, v56, v57 bitop3:0xde
	v_add_u32_e32 v216, 0x10000, v52
	ds_read_b128 v[52:55], v216 offset:0
	v_bitop3_b32 v56, v58, v56, v57 bitop3:0xde
	v_add_u32_e32 v215, 0x10000, v56
	s_waitcnt lgkmcnt(0)
	v_mfma_f32_32x32x16_bf16 v[18:33], v[52:55], v[162:165], v[18:33]
	ds_read_b128 v[52:55], v215 offset:0
	ds_read_b128 v[56:59], v213 offset:8192
	ds_read_b128 v[60:63], v214 offset:8192
	ds_read_b128 v[64:67], v218 offset:8192
	ds_read_b128 v[68:71], v217 offset:8192
	ds_read_b128 v[72:75], v216 offset:8192
	s_waitcnt lgkmcnt(4)
	v_mfma_f32_32x32x16_bf16 v[98:113], v[56:59], v[146:149], v[98:113]
	v_mov_b32_e32 v56, v205
	v_mov_b32_e32 v57, v205
	v_mov_b32_e32 v58, v205
	v_mov_b32_e32 v59, v205
	s_waitcnt lgkmcnt(3)
	v_mfma_f32_32x32x16_bf16 v[98:113], v[60:63], v[154:157], v[98:113]
	v_mov_b32_e32 v60, v205
	v_mov_b32_e32 v61, v205
	v_mov_b32_e32 v62, v205
	v_mov_b32_e32 v63, v205
	s_waitcnt lgkmcnt(2)
	v_mfma_f32_32x32x16_bf16 v[98:113], v[64:67], v[166:169], v[98:113]
	v_mov_b32_e32 v64, v205
	v_mov_b32_e32 v65, v205
	v_mov_b32_e32 v66, 0
	v_mov_b32_e32 v67, v205
	s_waitcnt lgkmcnt(1)
	v_mfma_f32_32x32x16_bf16 v[98:113], v[68:71], v[174:177], v[98:113]
	v_mov_b32_e32 v68, v205
	v_mov_b32_e32 v69, v205
	v_mov_b32_e32 v70, v205
	v_mov_b32_e32 v71, v205
	v_mfma_f32_32x32x16_bf16 v[18:33], v[52:55], v[170:173], v[18:33]
	ds_read_b128 v[52:55], v215 offset:8192
	s_waitcnt vmcnt(0)
	s_waitcnt vmcnt(3)
	ds_write_b128 v207, v[36:39] offset:16384
	s_waitcnt vmcnt(2)
	ds_write_b128 v208, v[40:43] offset:16384
	s_waitcnt vmcnt(1)
	ds_write_b128 v209, v[44:47] offset:16384
	s_waitcnt vmcnt(0)
	ds_write_b128 v211, v[48:51] offset:16384
	v_mov_b32_e32 v36, v205
	v_mov_b32_e32 v37, v205
	v_mov_b32_e32 v38, v205
	s_waitcnt lgkmcnt(5)
	v_mfma_f32_32x32x16_bf16 v[98:113], v[72:75], v[162:165], v[98:113]
	v_exp_f32_e32 v232, v18
	v_exp_f32_e32 v234, v19
	v_exp_f32_e32 v230, v20
	v_exp_f32_e32 v233, v21
	v_exp_f32_e32 v229, v22
	v_exp_f32_e32 v231, v23
	v_exp_f32_e32 v227, v24
	s_waitcnt lgkmcnt(4)
	v_mfma_f32_32x32x16_bf16 v[98:113], v[52:55], v[170:173], v[98:113]
	v_exp_f32_e32 v228, v25
	v_exp_f32_e32 v224, v26
	v_exp_f32_e32 v226, v27
	v_exp_f32_e32 v223, v28
	v_exp_f32_e32 v225, v29
	v_exp_f32_e32 v220, v30
	v_exp_f32_e32 v222, v31
	v_exp_f32_e32 v219, v32
	v_exp_f32_e32 v221, v33
	v_and_b32_e32 v20, 15, v114
	v_mad_i64_i32 v[18:19], s[12:13], s96, v201, v[34:35]
	v_lshlrev_b32_e32 v20, 4, v20
	v_or3_b32 v18, v18, s95, v20
	v_lshl_add_u64 v[196:197], s[8:9], 0, v[18:19]
	v_mov_b32_e32 v18, 0
	v_mov_b32_e32 v19, v205
	v_mov_b32_e32 v20, v205
	v_mov_b32_e32 v21, v205
	v_mov_b32_e32 v22, v205
	v_mov_b32_e32 v23, v205
	v_mov_b32_e32 v24, v205
	v_mov_b32_e32 v25, v205
	v_mov_b32_e32 v26, v205
	v_mov_b32_e32 v27, v205
	v_mov_b32_e32 v28, v205
	v_mov_b32_e32 v29, v205
	v_mov_b32_e32 v30, v205
	v_mov_b32_e32 v31, v205
	v_mov_b32_e32 v32, v205
	v_mov_b32_e32 v33, v205
	v_mov_b32_e32 v34, 0
	v_mov_b32_e32 v35, v205
	v_mov_b32_e32 v39, v205
	v_mov_b32_e32 v40, v205
	v_mov_b32_e32 v41, v205
	v_mov_b32_e32 v42, v205
	v_mov_b32_e32 v43, v205
	v_mov_b32_e32 v44, v205
	v_mov_b32_e32 v45, v205
	v_mov_b32_e32 v46, v205
	v_mov_b32_e32 v47, v205
	v_mov_b32_e32 v48, v205
	v_mov_b32_e32 v49, v205
	v_mov_b32_e32 v50, 0
	v_mov_b32_e32 v51, v205
	v_mov_b32_e32 v52, v205
	v_mov_b32_e32 v53, v205
	v_mov_b32_e32 v54, v205
	v_mov_b32_e32 v55, v205
	v_mov_b32_e32 v72, v205
	v_mov_b32_e32 v73, v205
	v_mov_b32_e32 v74, v205
	v_mov_b32_e32 v75, v205
	s_waitcnt lgkmcnt(0)
	s_barrier
; #define SBAR() __builtin_amdgcn_sched_barrier(0)
; #define SLOAD(i, k0) do { sr_[i].vs0 = St::ld8(&Vh[(long)((k0) + sr) * LDK + sc]); sr_[i].vs1 = St::ld8(&Vh[(long)((k0) + 32 + sr) * LDK + sc]); \
;     sr_[i].ks0 = St::ld8(&Kh[(long)((k0) + sr) * LDK + sc]); sr_[i].ks1 = St::ld8(&Kh[(long)((k0) + 32 + sr) * LDK + sc]); } while (0)
; #define SWAIT() do { if constexpr (SDEPTH == 2) asm volatile("s_waitcnt vmcnt(4)" ::: "memory"); else asm volatile("s_waitcnt vmcnt(0)" ::: "memory"); } while (0)
; template <int D0> __device__ __forceinline__ void pv_one(f32x16& od, int vb, bf16x8 pa0, bf16x8 pa1, bf16x8 pa2, bf16x8 pa3) {
;   const s16x4 l0 = tr_read<v_rd_off(D0, 0, 0)>(vb), h0 = tr_read<v_rd_off(D0, 0, 1)>(vb), l1 = tr_read<v_rd_off(D0, 1, 0)>(vb), h1 = tr_read<v_rd_off(D0, 1, 1)>(vb);
;   const s16x4 l2 = tr_read<v_rd_off(D0, 2, 0)>(vb), h2 = tr_read<v_rd_off(D0, 2, 1)>(vb), l3 = tr_read<v_rd_off(D0, 3, 0)>(vb), h3 = tr_read<v_rd_off(D0, 3, 1)>(vb);
;   asm volatile("s_waitcnt lgkmcnt(0)" ::: "memory"); SBAR();
;     ...
;   od = __builtin_amdgcn_mfma_f32_32x32x16_bf16(pa0, PK(l0, h0), od, 0, 0, 0);
;   od = __builtin_amdgcn_mfma_f32_32x32x16_bf16(pa1, PK(l1, h1), od, 0, 0, 0);
;   od = __builtin_amdgcn_mfma_f32_32x32x16_bf16(pa2, PK(l2, h2), od, 0, 0, 0);
;   od = __builtin_amdgcn_mfma_f32_32x32x16_bf16(pa3, PK(l3, h3), od, 0, 0, 0);
; template <typename TQ> ...
;     ...
;   SLOAD(SO, KVBLK); if constexpr (SDEPTH == 2) { if (2 < NT) SLOAD(SE, 2 * KVBLK); }
;   SWAIT(); SWRITE(1, SO); __syncthreads();
;   for (int j = 1; j + 1 < NT; j += 2) {
;     SBAR(); SLOAD(SO, (j + SDEPTH) * KVBLK); SBAR();
;     qkt(pB0, pB1, (bf16*)((char*)K_lds + SHM_K), qr, r32, hi, negm);
;     finishSM(pA0, pA1, l_reg, pa0, pa1, pa2, pa3); SBAR();
;     pv_d0(o, vb0, pa0, pa1, pa2, pa3); partialSM(pB0, pB1, mC);
;     __syncthreads(); SWAIT(); SWRITE(0, SE);
;     __syncthreads();
;     SBAR(); if (SDEPTH == 1 || j + 3 < NT) SLOAD(SE, (j + 1 + SDEPTH) * KVBLK); SBAR();
;     qkt(pA0, pA1, K_lds, qr, r32, hi, negm);
;     finishSM(pB0, pB1, l_reg, pa0, pa1, pa2, pa3); SBAR();
;     pv_d0(o, vb0 + (int)SHM_V, pa0, pa1, pa2, pa3); partialSM(pA0, pA1, mC);
	s_lshr_b32 s1, s53, 6
	s_lshl_b32 s80, s1, 11
	s_add_u32 s79, s80, 0x10000
	s_lshl_b32 s1, s1, 3
	v_lshrrev_b32_e32 v178, 4, v203
	v_and_b32_e32 v179, 15, v203
	v_add_u32_e32 v180, s1, v178
	v_and_b32_e32 v196, 15, v180
	v_xor_b32_e32 v196, v196, v179
	v_lshlrev_b32_e32 v196, 4, v196
	v_lshl_or_b32 v196, v180, 9, v196
	v_add_u32_e32 v180, s1, v178
	v_add_u32_e32 v180, 4, v180
	v_and_b32_e32 v197, 15, v180
	v_xor_b32_e32 v197, v197, v179
	v_lshlrev_b32_e32 v197, 4, v197
	v_lshl_or_b32 v197, v180, 9, v197
	v_bfe_u32 v178, v203, 2, 3
	v_add_u32_e32 v178, s1, v178
	v_and_b32_e32 v179, 4, v178
	v_and_b32_e32 v180, 8, v178
	v_and_b32_e32 v178, 0xfffffff3, v178
	v_lshl_or_b32 v178, v179, 1, v178
	v_lshrrev_b32_e32 v180, 1, v180
	v_or_b32_e32 v178, v178, v180
	v_lshrrev_b32_e32 v179, 5, v203
	v_and_b32_e32 v180, 3, v203
	v_lshlrev_b32_e32 v180, 4, v180
	v_lshl_or_b32 v180, v179, 6, v180
	v_lshl_or_b32 v207, v178, 9, v180
	v_add_u32_e32 v208, 0x80, v207
	s_add_u32 s98, s54, 0x10000
	s_addc_u32 s99, s55, 0
	s_add_u32 s100, s64, 0x10000
	s_addc_u32 s101, s65, 0
	s_add_u32 m0, s79, 32768
	s_nop 0
	global_load_lds_dwordx4 v196, s[98:99]
	s_add_u32 m0, s79, 33792
	s_nop 0
	global_load_lds_dwordx4 v197, s[98:99]
	s_add_u32 m0, s80, 32768
	s_nop 0
	global_load_lds_dwordx4 v207, s[100:101]
	s_add_u32 m0, s80, 33792
	s_nop 0
	global_load_lds_dwordx4 v208, s[100:101]
	s_add_u32 s98, s98, 0x8000
	s_addc_u32 s99, s99, 0
	s_add_u32 m0, s79, 49152
	s_nop 0
	global_load_lds_dwordx4 v196, s[98:99]
	s_add_u32 m0, s79, 50176
	s_nop 0
	global_load_lds_dwordx4 v197, s[98:99]
	v_mov_b32_e32 v82, v232
	v_mov_b32_e32 v83, v234
	v_mov_b32_e32 v84, v230
	v_mov_b32_e32 v85, v233
	v_mov_b32_e32 v86, v229
	v_mov_b32_e32 v87, v231
	v_mov_b32_e32 v88, v227
	v_mov_b32_e32 v89, v228
	v_mov_b32_e32 v90, v224
	v_mov_b32_e32 v91, v226
	v_mov_b32_e32 v92, v223
	v_mov_b32_e32 v93, v225
	v_mov_b32_e32 v94, v220
	v_mov_b32_e32 v95, v222
	v_mov_b32_e32 v96, v219
	v_mov_b32_e32 v97, v221
	v_exp_f32_e32 v98, v98
	v_exp_f32_e32 v99, v99
	v_exp_f32_e32 v100, v100
	v_exp_f32_e32 v101, v101
	v_exp_f32_e32 v102, v102
	v_exp_f32_e32 v103, v103
	v_exp_f32_e32 v104, v104
	v_exp_f32_e32 v105, v105
	v_exp_f32_e32 v106, v106
	v_exp_f32_e32 v107, v107
	v_exp_f32_e32 v108, v108
	v_exp_f32_e32 v109, v109
	v_exp_f32_e32 v110, v110
	v_exp_f32_e32 v111, v111
	v_exp_f32_e32 v112, v112
	v_exp_f32_e32 v113, v113
	v_mov_b32_e32 v204, 0
	s_waitcnt vmcnt(0)
	s_barrier
	ds_read_b128 v[220:223], v210 offset:16384
	ds_read_b128 v[224:227], v210 offset:24576
	ds_read_b128 v[228:231], v212 offset:16384
	ds_read_b128 v[232:235], v212 offset:24576
	s_mov_b32 s0, 0
.Lattn_loop:
	s_barrier
	s_waitcnt lgkmcnt(3)
	v_mfma_f32_32x32x16_bf16 v[114:129], v[220:223], v[150:153], v[2:17]
	ds_read_b128 v[220:223], v213 offset:16384
	v_add_f32_e32 v205, v82, v205
	v_add_f32_e32 v204, v83, v204
	v_cvt_pk_bf16_f32 v82, v82, v83
	s_add_u32 s98, s98, 0x8000
	s_addc_u32 s99, s99, 0
	s_add_u32 s100, s100, 0x8000
	s_addc_u32 s101, s101, 0
	s_waitcnt lgkmcnt(3)
	v_mfma_f32_32x32x16_bf16 v[130:145], v[224:227], v[150:153], v[2:17]
	ds_read_b128 v[224:227], v213 offset:24576
	v_add_f32_e32 v205, v84, v205
	v_add_f32_e32 v204, v85, v204
	v_cvt_pk_bf16_f32 v83, v84, v85
	s_add_u32 m0, s79, 0
	s_nop 0
	global_load_lds_dwordx4 v196, s[98:99]
	s_waitcnt lgkmcnt(3)
	v_mfma_f32_32x32x16_bf16 v[114:129], v[228:231], v[158:161], v[114:129]
	ds_read_b128 v[228:231], v214 offset:16384
	v_add_f32_e32 v205, v86, v205
	v_add_f32_e32 v204, v87, v204
	v_cvt_pk_bf16_f32 v84, v86, v87
	s_add_u32 m0, s79, 1024
	s_nop 0
	global_load_lds_dwordx4 v197, s[98:99]
	s_waitcnt lgkmcnt(3)
	v_mfma_f32_32x32x16_bf16 v[130:145], v[232:235], v[158:161], v[130:145]
	ds_read_b128 v[232:235], v214 offset:24576
	v_add_f32_e32 v205, v88, v205
	v_add_f32_e32 v204, v89, v204
	v_cvt_pk_bf16_f32 v85, v88, v89
	s_add_u32 m0, s80, 49152
	s_nop 0
	global_load_lds_dwordx4 v207, s[100:101]
	s_waitcnt lgkmcnt(3)
	v_mfma_f32_32x32x16_bf16 v[114:129], v[220:223], v[146:149], v[114:129]
	ds_read_b128 v[220:223], v218 offset:16384
	v_add_f32_e32 v205, v90, v205
	v_add_f32_e32 v204, v91, v204
	v_cvt_pk_bf16_f32 v86, v90, v91
	v_permlane32_swap_b32_e32 v82, v84
	s_add_u32 m0, s80, 50176
	s_nop 0
	global_load_lds_dwordx4 v208, s[100:101]
	s_waitcnt lgkmcnt(3)
	v_mfma_f32_32x32x16_bf16 v[130:145], v[224:227], v[146:149], v[130:145]
	ds_read_b128 v[224:227], v218 offset:24576
	v_add_f32_e32 v205, v92, v205
	v_add_f32_e32 v204, v93, v204
	v_cvt_pk_bf16_f32 v87, v92, v93
	v_permlane32_swap_b32_e32 v83, v85
	s_waitcnt lgkmcnt(3)
	v_mfma_f32_32x32x16_bf16 v[114:129], v[228:231], v[154:157], v[114:129]
	ds_read_b128 v[228:231], v217 offset:16384
	v_add_f32_e32 v205, v94, v205
	v_add_f32_e32 v204, v95, v204
	v_cvt_pk_bf16_f32 v88, v94, v95
	s_waitcnt lgkmcnt(3)
	v_mfma_f32_32x32x16_bf16 v[130:145], v[232:235], v[154:157], v[130:145]
	ds_read_b128 v[232:235], v217 offset:24576
	v_add_f32_e32 v205, v96, v205
	v_add_f32_e32 v204, v97, v204
	v_cvt_pk_bf16_f32 v89, v96, v97
	s_waitcnt lgkmcnt(3)
	v_mfma_f32_32x32x16_bf16 v[114:129], v[220:223], v[166:169], v[114:129]
	ds_read_b128 v[220:223], v216 offset:16384
	v_add_f32_e32 v205, v98, v205
	v_add_f32_e32 v204, v99, v204
	v_cvt_pk_bf16_f32 v90, v98, v99
	v_permlane32_swap_b32_e32 v86, v88
	ds_read_b64_tr_b16 v[236:237], v206 offset:0
	s_waitcnt lgkmcnt(4)
	v_mfma_f32_32x32x16_bf16 v[130:145], v[224:227], v[166:169], v[130:145]
	ds_read_b128 v[224:227], v216 offset:24576
	v_add_f32_e32 v205, v100, v205
	v_add_f32_e32 v204, v101, v204
	v_cvt_pk_bf16_f32 v91, v100, v101
	v_permlane32_swap_b32_e32 v87, v89
	ds_read_b64_tr_b16 v[238:239], v206 offset:2048
	s_waitcnt lgkmcnt(5)
; #define SBAR() __builtin_amdgcn_sched_barrier(0)
; #define SLOAD(i, k0) do { sr_[i].vs0 = St::ld8(&Vh[(long)((k0) + sr) * LDK + sc]); sr_[i].vs1 = St::ld8(&Vh[(long)((k0) + 32 + sr) * LDK + sc]); \
;     sr_[i].ks0 = St::ld8(&Kh[(long)((k0) + sr) * LDK + sc]); sr_[i].ks1 = St::ld8(&Kh[(long)((k0) + 32 + sr) * LDK + sc]); } while (0)
; #define SWAIT() do { if constexpr (SDEPTH == 2) asm volatile("s_waitcnt vmcnt(4)" ::: "memory"); else asm volatile("s_waitcnt vmcnt(0)" ::: "memory"); } while (0)
; template <int D0> __device__ __forceinline__ void pv_one(f32x16& od, int vb, bf16x8 pa0, bf16x8 pa1, bf16x8 pa2, bf16x8 pa3) {
;   const s16x4 l0 = tr_read<v_rd_off(D0, 0, 0)>(vb), h0 = tr_read<v_rd_off(D0, 0, 1)>(vb), l1 = tr_read<v_rd_off(D0, 1, 0)>(vb), h1 = tr_read<v_rd_off(D0, 1, 1)>(vb);
;   const s16x4 l2 = tr_read<v_rd_off(D0, 2, 0)>(vb), h2 = tr_read<v_rd_off(D0, 2, 1)>(vb), l3 = tr_read<v_rd_off(D0, 3, 0)>(vb), h3 = tr_read<v_rd_off(D0, 3, 1)>(vb);
;   asm volatile("s_waitcnt lgkmcnt(0)" ::: "memory"); SBAR();
;     ...
;   od = __builtin_amdgcn_mfma_f32_32x32x16_bf16(pa0, PK(l0, h0), od, 0, 0, 0);
;   od = __builtin_amdgcn_mfma_f32_32x32x16_bf16(pa1, PK(l1, h1), od, 0, 0, 0);
;   od = __builtin_amdgcn_mfma_f32_32x32x16_bf16(pa2, PK(l2, h2), od, 0, 0, 0);
;   od = __builtin_amdgcn_mfma_f32_32x32x16_bf16(pa3, PK(l3, h3), od, 0, 0, 0);
;     ...
; }
; __device__ __forceinline__ void pv_d0(f32x16* o, int vb, bf16x8 pa0, bf16x8 pa1, bf16x8 pa2, bf16x8 pa3) {
;   pv_one<0>(o[0], vb, pa0, pa1, pa2, pa3); pv_one<1>(o[1], vb, pa0, pa1, pa2, pa3); pv_one<2>(o[2], vb, pa0, pa1, pa2, pa3); pv_one<3>(o[3], vb, pa0, pa1, pa2, pa3);
; template <typename TQ> ...
;     ...
;     qkt(pB0, pB1, (bf16*)((char*)K_lds + SHM_K), qr, r32, hi, negm);
;     finishSM(pA0, pA1, l_reg, pa0, pa1, pa2, pa3); SBAR();
;     pv_d0(o, vb0, pa0, pa1, pa2, pa3); partialSM(pB0, pB1, mC);
;     __syncthreads(); SWAIT(); SWRITE(0, SE);
;     __syncthreads();
;     SBAR(); if (SDEPTH == 1 || j + 3 < NT) SLOAD(SE, (j + 1 + SDEPTH) * KVBLK); SBAR();
;     qkt(pA0, pA1, K_lds, qr, r32, hi, negm);
;     finishSM(pB0, pB1, l_reg, pa0, pa1, pa2, pa3); SBAR();
;     pv_d0(o, vb0 + (int)SHM_V, pa0, pa1, pa2, pa3); partialSM(pA0, pA1, mC);
;     __syncthreads(); SWAIT(); SWRITE(1, SO);
	v_mfma_f32_32x32x16_bf16 v[114:129], v[228:231], v[174:177], v[114:129]
	ds_read_b128 v[228:231], v215 offset:16384
	v_add_f32_e32 v205, v102, v205
	v_add_f32_e32 v204, v103, v204
	v_cvt_pk_bf16_f32 v92, v102, v103
	ds_read_b64_tr_b16 v[240:241], v206 offset:4096
	s_waitcnt lgkmcnt(6)
	v_mfma_f32_32x32x16_bf16 v[130:145], v[232:235], v[174:177], v[130:145]
	ds_read_b128 v[232:235], v215 offset:24576
	v_add_f32_e32 v205, v104, v205
	v_add_f32_e32 v204, v105, v204
	v_cvt_pk_bf16_f32 v93, v104, v105
	ds_read_b64_tr_b16 v[242:243], v206 offset:6144
	s_waitcnt lgkmcnt(7)
	v_mfma_f32_32x32x16_bf16 v[114:129], v[220:223], v[162:165], v[114:129]
	v_add_f32_e32 v205, v106, v205
	v_add_f32_e32 v204, v107, v204
	v_cvt_pk_bf16_f32 v94, v106, v107
	v_permlane32_swap_b32_e32 v90, v92
	ds_read_b64_tr_b16 v[244:245], v206 offset:8192
	ds_read_b64_tr_b16 v[98:99], v206 offset:512
	s_waitcnt lgkmcnt(7)
	v_mfma_f32_32x32x16_bf16 v[130:145], v[224:227], v[162:165], v[130:145]
	v_add_f32_e32 v205, v108, v205
	v_add_f32_e32 v204, v109, v204
	v_cvt_pk_bf16_f32 v95, v108, v109
	v_permlane32_swap_b32_e32 v91, v93
	ds_read_b64_tr_b16 v[246:247], v206 offset:10240
	ds_read_b64_tr_b16 v[100:101], v206 offset:2560
	s_waitcnt lgkmcnt(7)
	v_mfma_f32_32x32x16_bf16 v[114:129], v[228:231], v[170:173], v[114:129]
	v_add_f32_e32 v205, v110, v205
	v_add_f32_e32 v204, v111, v204
	v_cvt_pk_bf16_f32 v96, v110, v111
	ds_read_b64_tr_b16 v[248:249], v206 offset:12288
	ds_read_b64_tr_b16 v[102:103], v206 offset:4608
	s_waitcnt lgkmcnt(7)
	v_mfma_f32_32x32x16_bf16 v[130:145], v[232:235], v[170:173], v[130:145]
	v_add_f32_e32 v205, v112, v205
	v_add_f32_e32 v204, v113, v204
	v_cvt_pk_bf16_f32 v97, v112, v113
	ds_read_b64_tr_b16 v[250:251], v206 offset:14336
	ds_read_b64_tr_b16 v[104:105], v206 offset:6656
	v_mfma_f32_32x32x16_bf16 v[18:33], v[82:85], v[236:239], v[18:33]
	v_permlane32_swap_b32_e32 v94, v96
	v_permlane32_swap_b32_e32 v95, v97
	ds_read_b64_tr_b16 v[236:237], v206 offset:8704
	ds_read_b64_tr_b16 v[238:239], v206 offset:10752
	s_waitcnt lgkmcnt(10)
	v_mfma_f32_32x32x16_bf16 v[18:33], v[86:89], v[240:243], v[18:33]
	ds_read_b64_tr_b16 v[240:241], v206 offset:12800
	ds_read_b64_tr_b16 v[242:243], v206 offset:14848
	v_exp_f32_e32 v114, v114
	v_exp_f32_e32 v115, v115
	s_waitcnt lgkmcnt(9)
	v_mfma_f32_32x32x16_bf16 v[18:33], v[90:93], v[244:247], v[18:33]
	ds_read_b64_tr_b16 v[244:245], v206 offset:1024
	ds_read_b64_tr_b16 v[246:247], v206 offset:3072
	v_exp_f32_e32 v116, v116
	v_exp_f32_e32 v117, v117
	s_waitcnt lgkmcnt(7)
	v_mfma_f32_32x32x16_bf16 v[18:33], v[94:97], v[248:251], v[18:33]
	ds_read_b64_tr_b16 v[248:249], v206 offset:5120
	ds_read_b64_tr_b16 v[250:251], v206 offset:7168
	v_exp_f32_e32 v118, v118
	v_exp_f32_e32 v119, v119
	v_mfma_f32_32x32x16_bf16 v[34:49], v[82:85], v[98:101], v[34:49]
	ds_read_b64_tr_b16 v[98:99], v206 offset:9216
	ds_read_b64_tr_b16 v[100:101], v206 offset:11264
	v_exp_f32_e32 v120, v120
	v_exp_f32_e32 v121, v121
	s_waitcnt lgkmcnt(10)
	v_mfma_f32_32x32x16_bf16 v[34:49], v[86:89], v[102:105], v[34:49]
	ds_read_b64_tr_b16 v[102:103], v206 offset:13312
	ds_read_b64_tr_b16 v[104:105], v206 offset:15360
	v_exp_f32_e32 v122, v122
	v_exp_f32_e32 v123, v123
	s_waitcnt lgkmcnt(10)
	v_mfma_f32_32x32x16_bf16 v[34:49], v[90:93], v[236:239], v[34:49]
	ds_read_b64_tr_b16 v[236:237], v206 offset:1536
	ds_read_b64_tr_b16 v[238:239], v206 offset:3584
	v_exp_f32_e32 v124, v124
	v_exp_f32_e32 v125, v125
	s_waitcnt lgkmcnt(10)
	v_mfma_f32_32x32x16_bf16 v[34:49], v[94:97], v[240:243], v[34:49]
	ds_read_b64_tr_b16 v[240:241], v206 offset:5632
	ds_read_b64_tr_b16 v[242:243], v206 offset:7680
	v_exp_f32_e32 v126, v126
	v_exp_f32_e32 v127, v127
	s_waitcnt lgkmcnt(10)
	v_mfma_f32_32x32x16_bf16 v[50:65], v[82:85], v[244:247], v[50:65]
	ds_read_b64_tr_b16 v[244:245], v206 offset:9728
	ds_read_b64_tr_b16 v[246:247], v206 offset:11776
	v_exp_f32_e32 v128, v128
	v_exp_f32_e32 v129, v129
	s_waitcnt lgkmcnt(10)
	v_mfma_f32_32x32x16_bf16 v[50:65], v[86:89], v[248:251], v[50:65]
	ds_read_b64_tr_b16 v[248:249], v206 offset:13824
	ds_read_b64_tr_b16 v[250:251], v206 offset:15872
	v_exp_f32_e32 v130, v130
	v_exp_f32_e32 v131, v131
	s_waitcnt lgkmcnt(10)
	v_mfma_f32_32x32x16_bf16 v[50:65], v[90:93], v[98:101], v[50:65]
	v_exp_f32_e32 v132, v132
	v_exp_f32_e32 v133, v133
	s_waitcnt lgkmcnt(8)
	v_mfma_f32_32x32x16_bf16 v[50:65], v[94:97], v[102:105], v[50:65]
	v_exp_f32_e32 v134, v134
	v_exp_f32_e32 v135, v135
	s_waitcnt lgkmcnt(6)
	v_mfma_f32_32x32x16_bf16 v[66:81], v[82:85], v[236:239], v[66:81]
	v_exp_f32_e32 v136, v136
	v_exp_f32_e32 v137, v137
	ds_read_b128 v[220:223], v210 offset:32768
	s_waitcnt lgkmcnt(5)
	v_mfma_f32_32x32x16_bf16 v[66:81], v[86:89], v[240:243], v[66:81]
	v_exp_f32_e32 v138, v138
	v_exp_f32_e32 v139, v139
	ds_read_b128 v[224:227], v210 offset:40960
	s_waitcnt lgkmcnt(4)
	v_mfma_f32_32x32x16_bf16 v[66:81], v[90:93], v[244:247], v[66:81]
	v_exp_f32_e32 v140, v140
	v_exp_f32_e32 v141, v141
	ds_read_b128 v[228:231], v212 offset:32768
	s_waitcnt lgkmcnt(3)
	v_mfma_f32_32x32x16_bf16 v[66:81], v[94:97], v[248:251], v[66:81]
	v_exp_f32_e32 v142, v142
	v_exp_f32_e32 v143, v143
	v_exp_f32_e32 v144, v144
	v_exp_f32_e32 v145, v145
	ds_read_b128 v[232:235], v212 offset:40960
	s_waitcnt vmcnt(4)
	s_barrier
; #define SBAR() __builtin_amdgcn_sched_barrier(0)
; #define SLOAD(i, k0) do { sr_[i].vs0 = St::ld8(&Vh[(long)((k0) + sr) * LDK + sc]); sr_[i].vs1 = St::ld8(&Vh[(long)((k0) + 32 + sr) * LDK + sc]); \
;     sr_[i].ks0 = St::ld8(&Kh[(long)((k0) + sr) * LDK + sc]); sr_[i].ks1 = St::ld8(&Kh[(long)((k0) + 32 + sr) * LDK + sc]); } while (0)
; #define SWAIT() do { if constexpr (SDEPTH == 2) asm volatile("s_waitcnt vmcnt(4)" ::: "memory"); else asm volatile("s_waitcnt vmcnt(0)" ::: "memory"); } while (0)
; template <int D0> __device__ __forceinline__ void pv_one(f32x16& od, int vb, bf16x8 pa0, bf16x8 pa1, bf16x8 pa2, bf16x8 pa3) {
;   const s16x4 l0 = tr_read<v_rd_off(D0, 0, 0)>(vb), h0 = tr_read<v_rd_off(D0, 0, 1)>(vb), l1 = tr_read<v_rd_off(D0, 1, 0)>(vb), h1 = tr_read<v_rd_off(D0, 1, 1)>(vb);
;   const s16x4 l2 = tr_read<v_rd_off(D0, 2, 0)>(vb), h2 = tr_read<v_rd_off(D0, 2, 1)>(vb), l3 = tr_read<v_rd_off(D0, 3, 0)>(vb), h3 = tr_read<v_rd_off(D0, 3, 1)>(vb);
;   asm volatile("s_waitcnt lgkmcnt(0)" ::: "memory"); SBAR();
;     ...
;   od = __builtin_amdgcn_mfma_f32_32x32x16_bf16(pa0, PK(l0, h0), od, 0, 0, 0);
;   od = __builtin_amdgcn_mfma_f32_32x32x16_bf16(pa1, PK(l1, h1), od, 0, 0, 0);
;   od = __builtin_amdgcn_mfma_f32_32x32x16_bf16(pa2, PK(l2, h2), od, 0, 0, 0);
;   od = __builtin_amdgcn_mfma_f32_32x32x16_bf16(pa3, PK(l3, h3), od, 0, 0, 0);
;     ...
; }
; __device__ __forceinline__ void pv_d0(f32x16* o, int vb, bf16x8 pa0, bf16x8 pa1, bf16x8 pa2, bf16x8 pa3) {
;   pv_one<0>(o[0], vb, pa0, pa1, pa2, pa3); pv_one<1>(o[1], vb, pa0, pa1, pa2, pa3); pv_one<2>(o[2], vb, pa0, pa1, pa2, pa3); pv_one<3>(o[3], vb, pa0, pa1, pa2, pa3);
; template <typename TQ> ...
;     ...
;   for (int j = 1; j + 1 < NT; j += 2) {
;     SBAR(); SLOAD(SO, (j + SDEPTH) * KVBLK); SBAR();
;     qkt(pB0, pB1, (bf16*)((char*)K_lds + SHM_K), qr, r32, hi, negm);
;     finishSM(pA0, pA1, l_reg, pa0, pa1, pa2, pa3); SBAR();
;     pv_d0(o, vb0, pa0, pa1, pa2, pa3); partialSM(pB0, pB1, mC);
;     __syncthreads(); SWAIT(); SWRITE(0, SE);
;     __syncthreads();
;     SBAR(); if (SDEPTH == 1 || j + 3 < NT) SLOAD(SE, (j + 1 + SDEPTH) * KVBLK); SBAR();
;     qkt(pA0, pA1, K_lds, qr, r32, hi, negm);
;     finishSM(pB0, pB1, l_reg, pa0, pa1, pa2, pa3); SBAR();
;     pv_d0(o, vb0 + (int)SHM_V, pa0, pa1, pa2, pa3); partialSM(pA0, pA1, mC);
;     __syncthreads(); SWAIT(); SWRITE(1, SO);
;     __syncthreads();
	s_waitcnt lgkmcnt(3)
	v_mfma_f32_32x32x16_bf16 v[82:97], v[220:223], v[150:153], v[2:17]
	ds_read_b128 v[220:223], v213 offset:32768
	v_add_f32_e32 v205, v114, v205
	v_add_f32_e32 v204, v115, v204
	v_cvt_pk_bf16_f32 v114, v114, v115
	s_add_u32 s98, s98, 0x8000
	s_addc_u32 s99, s99, 0
	s_add_u32 s100, s100, 0x8000
	s_addc_u32 s101, s101, 0
	s_waitcnt lgkmcnt(3)
	v_mfma_f32_32x32x16_bf16 v[98:113], v[224:227], v[150:153], v[2:17]
	ds_read_b128 v[224:227], v213 offset:40960
	v_add_f32_e32 v205, v116, v205
	v_add_f32_e32 v204, v117, v204
	v_cvt_pk_bf16_f32 v115, v116, v117
	s_add_u32 m0, s79, 16384
	s_nop 0
	global_load_lds_dwordx4 v196, s[98:99]
	s_waitcnt lgkmcnt(3)
	v_mfma_f32_32x32x16_bf16 v[82:97], v[228:231], v[158:161], v[82:97]
	ds_read_b128 v[228:231], v214 offset:32768
	v_add_f32_e32 v205, v118, v205
	v_add_f32_e32 v204, v119, v204
	v_cvt_pk_bf16_f32 v116, v118, v119
	s_add_u32 m0, s79, 17408
	s_nop 0
	global_load_lds_dwordx4 v197, s[98:99]
	s_waitcnt lgkmcnt(3)
	v_mfma_f32_32x32x16_bf16 v[98:113], v[232:235], v[158:161], v[98:113]
	ds_read_b128 v[232:235], v214 offset:40960
	v_add_f32_e32 v205, v120, v205
	v_add_f32_e32 v204, v121, v204
	v_cvt_pk_bf16_f32 v117, v120, v121
	s_add_u32 m0, s80, 0
	s_nop 0
	global_load_lds_dwordx4 v207, s[100:101]
	s_waitcnt lgkmcnt(3)
	v_mfma_f32_32x32x16_bf16 v[82:97], v[220:223], v[146:149], v[82:97]
	ds_read_b128 v[220:223], v218 offset:32768
	v_add_f32_e32 v205, v122, v205
	v_add_f32_e32 v204, v123, v204
	v_cvt_pk_bf16_f32 v118, v122, v123
	v_permlane32_swap_b32_e32 v114, v116
	s_add_u32 m0, s80, 1024
	s_nop 0
	global_load_lds_dwordx4 v208, s[100:101]
	s_waitcnt lgkmcnt(3)
	v_mfma_f32_32x32x16_bf16 v[98:113], v[224:227], v[146:149], v[98:113]
	ds_read_b128 v[224:227], v218 offset:40960
	v_add_f32_e32 v205, v124, v205
	v_add_f32_e32 v204, v125, v204
	v_cvt_pk_bf16_f32 v119, v124, v125
	v_permlane32_swap_b32_e32 v115, v117
	s_waitcnt lgkmcnt(3)
	v_mfma_f32_32x32x16_bf16 v[82:97], v[228:231], v[154:157], v[82:97]
	ds_read_b128 v[228:231], v217 offset:32768
	v_add_f32_e32 v205, v126, v205
	v_add_f32_e32 v204, v127, v204
	v_cvt_pk_bf16_f32 v120, v126, v127
	s_waitcnt lgkmcnt(3)
	v_mfma_f32_32x32x16_bf16 v[98:113], v[232:235], v[154:157], v[98:113]
	ds_read_b128 v[232:235], v217 offset:40960
	v_add_f32_e32 v205, v128, v205
	v_add_f32_e32 v204, v129, v204
	v_cvt_pk_bf16_f32 v121, v128, v129
	s_waitcnt lgkmcnt(3)
	v_mfma_f32_32x32x16_bf16 v[82:97], v[220:223], v[166:169], v[82:97]
	ds_read_b128 v[220:223], v216 offset:32768
	v_add_f32_e32 v205, v130, v205
	v_add_f32_e32 v204, v131, v204
	v_cvt_pk_bf16_f32 v122, v130, v131
	v_permlane32_swap_b32_e32 v118, v120
	ds_read_b64_tr_b16 v[236:237], v206 offset:16384
	s_waitcnt lgkmcnt(4)
	v_mfma_f32_32x32x16_bf16 v[98:113], v[224:227], v[166:169], v[98:113]
	ds_read_b128 v[224:227], v216 offset:40960
	v_add_f32_e32 v205, v132, v205
	v_add_f32_e32 v204, v133, v204
	v_cvt_pk_bf16_f32 v123, v132, v133
	v_permlane32_swap_b32_e32 v119, v121
	ds_read_b64_tr_b16 v[238:239], v206 offset:18432
	s_waitcnt lgkmcnt(5)
	v_mfma_f32_32x32x16_bf16 v[82:97], v[228:231], v[174:177], v[82:97]
	ds_read_b128 v[228:231], v215 offset:32768
	v_add_f32_e32 v205, v134, v205
	v_add_f32_e32 v204, v135, v204
	v_cvt_pk_bf16_f32 v124, v134, v135
	ds_read_b64_tr_b16 v[240:241], v206 offset:20480
	s_waitcnt lgkmcnt(6)
	v_mfma_f32_32x32x16_bf16 v[98:113], v[232:235], v[174:177], v[98:113]
	ds_read_b128 v[232:235], v215 offset:40960
	v_add_f32_e32 v205, v136, v205
	v_add_f32_e32 v204, v137, v204
	v_cvt_pk_bf16_f32 v125, v136, v137
	ds_read_b64_tr_b16 v[242:243], v206 offset:22528
	s_waitcnt lgkmcnt(7)
	v_mfma_f32_32x32x16_bf16 v[82:97], v[220:223], v[162:165], v[82:97]
	v_add_f32_e32 v205, v138, v205
	v_add_f32_e32 v204, v139, v204
	v_cvt_pk_bf16_f32 v126, v138, v139
	v_permlane32_swap_b32_e32 v122, v124
	ds_read_b64_tr_b16 v[244:245], v206 offset:24576
	ds_read_b64_tr_b16 v[130:131], v206 offset:16896
	s_waitcnt lgkmcnt(7)
	v_mfma_f32_32x32x16_bf16 v[98:113], v[224:227], v[162:165], v[98:113]
	v_add_f32_e32 v205, v140, v205
	v_add_f32_e32 v204, v141, v204
	v_cvt_pk_bf16_f32 v127, v140, v141
	v_permlane32_swap_b32_e32 v123, v125
	ds_read_b64_tr_b16 v[246:247], v206 offset:26624
	ds_read_b64_tr_b16 v[132:133], v206 offset:18944
	s_waitcnt lgkmcnt(7)
	v_mfma_f32_32x32x16_bf16 v[82:97], v[228:231], v[170:173], v[82:97]
	v_add_f32_e32 v205, v142, v205
	v_add_f32_e32 v204, v143, v204
	v_cvt_pk_bf16_f32 v128, v142, v143
	ds_read_b64_tr_b16 v[248:249], v206 offset:28672
	ds_read_b64_tr_b16 v[134:135], v206 offset:20992
	s_waitcnt lgkmcnt(7)
	v_mfma_f32_32x32x16_bf16 v[98:113], v[232:235], v[170:173], v[98:113]
	v_add_f32_e32 v205, v144, v205
	v_add_f32_e32 v204, v145, v204
	v_cvt_pk_bf16_f32 v129, v144, v145
	ds_read_b64_tr_b16 v[250:251], v206 offset:30720
	ds_read_b64_tr_b16 v[136:137], v206 offset:23040
	v_mfma_f32_32x32x16_bf16 v[18:33], v[114:117], v[236:239], v[18:33]
	v_permlane32_swap_b32_e32 v126, v128
	v_permlane32_swap_b32_e32 v127, v129
	ds_read_b64_tr_b16 v[236:237], v206 offset:25088
	ds_read_b64_tr_b16 v[238:239], v206 offset:27136
	s_waitcnt lgkmcnt(10)
	v_mfma_f32_32x32x16_bf16 v[18:33], v[118:121], v[240:243], v[18:33]
	ds_read_b64_tr_b16 v[240:241], v206 offset:29184
	ds_read_b64_tr_b16 v[242:243], v206 offset:31232
	v_exp_f32_e32 v82, v82
	v_exp_f32_e32 v83, v83
	s_waitcnt lgkmcnt(9)
	v_mfma_f32_32x32x16_bf16 v[18:33], v[122:125], v[244:247], v[18:33]
	ds_read_b64_tr_b16 v[244:245], v206 offset:17408
	ds_read_b64_tr_b16 v[246:247], v206 offset:19456
	v_exp_f32_e32 v84, v84
	v_exp_f32_e32 v85, v85
	s_waitcnt lgkmcnt(7)
; #define SBAR() __builtin_amdgcn_sched_barrier(0)
; #define SLOAD(i, k0) do { sr_[i].vs0 = St::ld8(&Vh[(long)((k0) + sr) * LDK + sc]); sr_[i].vs1 = St::ld8(&Vh[(long)((k0) + 32 + sr) * LDK + sc]); \
;     sr_[i].ks0 = St::ld8(&Kh[(long)((k0) + sr) * LDK + sc]); sr_[i].ks1 = St::ld8(&Kh[(long)((k0) + 32 + sr) * LDK + sc]); } while (0)
; #define SWAIT() do { if constexpr (SDEPTH == 2) asm volatile("s_waitcnt vmcnt(4)" ::: "memory"); else asm volatile("s_waitcnt vmcnt(0)" ::: "memory"); } while (0)
; template <int D0> __device__ __forceinline__ void pv_one(f32x16& od, int vb, bf16x8 pa0, bf16x8 pa1, bf16x8 pa2, bf16x8 pa3) {
;   const s16x4 l0 = tr_read<v_rd_off(D0, 0, 0)>(vb), h0 = tr_read<v_rd_off(D0, 0, 1)>(vb), l1 = tr_read<v_rd_off(D0, 1, 0)>(vb), h1 = tr_read<v_rd_off(D0, 1, 1)>(vb);
;   const s16x4 l2 = tr_read<v_rd_off(D0, 2, 0)>(vb), h2 = tr_read<v_rd_off(D0, 2, 1)>(vb), l3 = tr_read<v_rd_off(D0, 3, 0)>(vb), h3 = tr_read<v_rd_off(D0, 3, 1)>(vb);
;   asm volatile("s_waitcnt lgkmcnt(0)" ::: "memory"); SBAR();
;     ...
;   od = __builtin_amdgcn_mfma_f32_32x32x16_bf16(pa0, PK(l0, h0), od, 0, 0, 0);
;   od = __builtin_amdgcn_mfma_f32_32x32x16_bf16(pa1, PK(l1, h1), od, 0, 0, 0);
;   od = __builtin_amdgcn_mfma_f32_32x32x16_bf16(pa2, PK(l2, h2), od, 0, 0, 0);
;   od = __builtin_amdgcn_mfma_f32_32x32x16_bf16(pa3, PK(l3, h3), od, 0, 0, 0);
;     ...
; }
; __device__ __forceinline__ void pv_d0(f32x16* o, int vb, bf16x8 pa0, bf16x8 pa1, bf16x8 pa2, bf16x8 pa3) {
;   pv_one<0>(o[0], vb, pa0, pa1, pa2, pa3); pv_one<1>(o[1], vb, pa0, pa1, pa2, pa3); pv_one<2>(o[2], vb, pa0, pa1, pa2, pa3); pv_one<3>(o[3], vb, pa0, pa1, pa2, pa3);
; template <typename TQ> ...
;     ...
;   for (int j = 1; j + 1 < NT; j += 2) {
;     SBAR(); SLOAD(SO, (j + SDEPTH) * KVBLK); SBAR();
;     qkt(pB0, pB1, (bf16*)((char*)K_lds + SHM_K), qr, r32, hi, negm);
;     finishSM(pA0, pA1, l_reg, pa0, pa1, pa2, pa3); SBAR();
;     pv_d0(o, vb0, pa0, pa1, pa2, pa3); partialSM(pB0, pB1, mC);
;     __syncthreads(); SWAIT(); SWRITE(0, SE);
;     __syncthreads();
;     SBAR(); if (SDEPTH == 1 || j + 3 < NT) SLOAD(SE, (j + 1 + SDEPTH) * KVBLK); SBAR();
;     qkt(pA0, pA1, K_lds, qr, r32, hi, negm);
;     finishSM(pB0, pB1, l_reg, pa0, pa1, pa2, pa3); SBAR();
;     pv_d0(o, vb0 + (int)SHM_V, pa0, pa1, pa2, pa3); partialSM(pA0, pA1, mC);
;     __syncthreads(); SWAIT(); SWRITE(1, SO);
;     __syncthreads();
	v_mfma_f32_32x32x16_bf16 v[18:33], v[126:129], v[248:251], v[18:33]
	ds_read_b64_tr_b16 v[248:249], v206 offset:21504
	ds_read_b64_tr_b16 v[250:251], v206 offset:23552
	v_exp_f32_e32 v86, v86
	v_exp_f32_e32 v87, v87
	v_mfma_f32_32x32x16_bf16 v[34:49], v[114:117], v[130:133], v[34:49]
	ds_read_b64_tr_b16 v[130:131], v206 offset:25600
	ds_read_b64_tr_b16 v[132:133], v206 offset:27648
	v_exp_f32_e32 v88, v88
	v_exp_f32_e32 v89, v89
	s_waitcnt lgkmcnt(10)
	v_mfma_f32_32x32x16_bf16 v[34:49], v[118:121], v[134:137], v[34:49]
	ds_read_b64_tr_b16 v[134:135], v206 offset:29696
	ds_read_b64_tr_b16 v[136:137], v206 offset:31744
	v_exp_f32_e32 v90, v90
	v_exp_f32_e32 v91, v91
	s_waitcnt lgkmcnt(10)
	v_mfma_f32_32x32x16_bf16 v[34:49], v[122:125], v[236:239], v[34:49]
	ds_read_b64_tr_b16 v[236:237], v206 offset:17920
	ds_read_b64_tr_b16 v[238:239], v206 offset:19968
	v_exp_f32_e32 v92, v92
	v_exp_f32_e32 v93, v93
	s_waitcnt lgkmcnt(10)
	v_mfma_f32_32x32x16_bf16 v[34:49], v[126:129], v[240:243], v[34:49]
	ds_read_b64_tr_b16 v[240:241], v206 offset:22016
	ds_read_b64_tr_b16 v[242:243], v206 offset:24064
	v_exp_f32_e32 v94, v94
	v_exp_f32_e32 v95, v95
	s_waitcnt lgkmcnt(10)
	v_mfma_f32_32x32x16_bf16 v[50:65], v[114:117], v[244:247], v[50:65]
	ds_read_b64_tr_b16 v[244:245], v206 offset:26112
	ds_read_b64_tr_b16 v[246:247], v206 offset:28160
	v_exp_f32_e32 v96, v96
	v_exp_f32_e32 v97, v97
	s_waitcnt lgkmcnt(10)
	v_mfma_f32_32x32x16_bf16 v[50:65], v[118:121], v[248:251], v[50:65]
	ds_read_b64_tr_b16 v[248:249], v206 offset:30208
	ds_read_b64_tr_b16 v[250:251], v206 offset:32256
	v_exp_f32_e32 v98, v98
	v_exp_f32_e32 v99, v99
	s_waitcnt lgkmcnt(10)
	v_mfma_f32_32x32x16_bf16 v[50:65], v[122:125], v[130:133], v[50:65]
	v_exp_f32_e32 v100, v100
	v_exp_f32_e32 v101, v101
	s_waitcnt lgkmcnt(8)
	v_mfma_f32_32x32x16_bf16 v[50:65], v[126:129], v[134:137], v[50:65]
	v_exp_f32_e32 v102, v102
	v_exp_f32_e32 v103, v103
	s_waitcnt lgkmcnt(6)
	v_mfma_f32_32x32x16_bf16 v[66:81], v[114:117], v[236:239], v[66:81]
	v_exp_f32_e32 v104, v104
	v_exp_f32_e32 v105, v105
	ds_read_b128 v[220:223], v210 offset:49152
	s_waitcnt lgkmcnt(5)
	v_mfma_f32_32x32x16_bf16 v[66:81], v[118:121], v[240:243], v[66:81]
	v_exp_f32_e32 v106, v106
	v_exp_f32_e32 v107, v107
	ds_read_b128 v[224:227], v210 offset:57344
	s_waitcnt lgkmcnt(4)
	v_mfma_f32_32x32x16_bf16 v[66:81], v[122:125], v[244:247], v[66:81]
	v_exp_f32_e32 v108, v108
	v_exp_f32_e32 v109, v109
	ds_read_b128 v[228:231], v212 offset:49152
	s_waitcnt lgkmcnt(3)
	v_mfma_f32_32x32x16_bf16 v[66:81], v[126:129], v[248:251], v[66:81]
	v_exp_f32_e32 v110, v110
	v_exp_f32_e32 v111, v111
	v_exp_f32_e32 v112, v112
	v_exp_f32_e32 v113, v113
	ds_read_b128 v[232:235], v212 offset:57344
	s_waitcnt vmcnt(4)
	s_barrier
	s_waitcnt lgkmcnt(3)
	v_mfma_f32_32x32x16_bf16 v[114:129], v[220:223], v[150:153], v[2:17]
	ds_read_b128 v[220:223], v213 offset:49152
	v_add_f32_e32 v205, v82, v205
	v_add_f32_e32 v204, v83, v204
	v_cvt_pk_bf16_f32 v82, v82, v83
	s_add_u32 s98, s98, 0x8000
	s_addc_u32 s99, s99, 0
	s_add_u32 s100, s100, 0x8000
	s_addc_u32 s101, s101, 0
	s_waitcnt lgkmcnt(3)
	v_mfma_f32_32x32x16_bf16 v[130:145], v[224:227], v[150:153], v[2:17]
	ds_read_b128 v[224:227], v213 offset:57344
	v_add_f32_e32 v205, v84, v205
	v_add_f32_e32 v204, v85, v204
	v_cvt_pk_bf16_f32 v83, v84, v85
	s_add_u32 m0, s79, 32768
	s_nop 0
	global_load_lds_dwordx4 v196, s[98:99]
	s_waitcnt lgkmcnt(3)
	v_mfma_f32_32x32x16_bf16 v[114:129], v[228:231], v[158:161], v[114:129]
	ds_read_b128 v[228:231], v214 offset:49152
	v_add_f32_e32 v205, v86, v205
	v_add_f32_e32 v204, v87, v204
	v_cvt_pk_bf16_f32 v84, v86, v87
	s_add_u32 m0, s79, 33792
	s_nop 0
	global_load_lds_dwordx4 v197, s[98:99]
	s_waitcnt lgkmcnt(3)
	v_mfma_f32_32x32x16_bf16 v[130:145], v[232:235], v[158:161], v[130:145]
	ds_read_b128 v[232:235], v214 offset:57344
	v_add_f32_e32 v205, v88, v205
	v_add_f32_e32 v204, v89, v204
	v_cvt_pk_bf16_f32 v85, v88, v89
	s_add_u32 m0, s80, 16384
	s_nop 0
	global_load_lds_dwordx4 v207, s[100:101]
	s_waitcnt lgkmcnt(3)
	v_mfma_f32_32x32x16_bf16 v[114:129], v[220:223], v[146:149], v[114:129]
	ds_read_b128 v[220:223], v218 offset:49152
	v_add_f32_e32 v205, v90, v205
	v_add_f32_e32 v204, v91, v204
	v_cvt_pk_bf16_f32 v86, v90, v91
	v_permlane32_swap_b32_e32 v82, v84
	s_add_u32 m0, s80, 17408
	s_nop 0
	global_load_lds_dwordx4 v208, s[100:101]
	s_waitcnt lgkmcnt(3)
	v_mfma_f32_32x32x16_bf16 v[130:145], v[224:227], v[146:149], v[130:145]
	ds_read_b128 v[224:227], v218 offset:57344
	v_add_f32_e32 v205, v92, v205
	v_add_f32_e32 v204, v93, v204
	v_cvt_pk_bf16_f32 v87, v92, v93
	v_permlane32_swap_b32_e32 v83, v85
	s_waitcnt lgkmcnt(3)
	v_mfma_f32_32x32x16_bf16 v[114:129], v[228:231], v[154:157], v[114:129]
	ds_read_b128 v[228:231], v217 offset:49152
	v_add_f32_e32 v205, v94, v205
	v_add_f32_e32 v204, v95, v204
	v_cvt_pk_bf16_f32 v88, v94, v95
	s_waitcnt lgkmcnt(3)
	v_mfma_f32_32x32x16_bf16 v[130:145], v[232:235], v[154:157], v[130:145]
	ds_read_b128 v[232:235], v217 offset:57344
	v_add_f32_e32 v205, v96, v205
	v_add_f32_e32 v204, v97, v204
	v_cvt_pk_bf16_f32 v89, v96, v97
	s_waitcnt lgkmcnt(3)
	v_mfma_f32_32x32x16_bf16 v[114:129], v[220:223], v[166:169], v[114:129]
	ds_read_b128 v[220:223], v216 offset:49152
	v_add_f32_e32 v205, v98, v205
	v_add_f32_e32 v204, v99, v204
	v_cvt_pk_bf16_f32 v90, v98, v99
	v_permlane32_swap_b32_e32 v86, v88
	ds_read_b64_tr_b16 v[236:237], v206 offset:32768
	s_waitcnt lgkmcnt(4)
	v_mfma_f32_32x32x16_bf16 v[130:145], v[224:227], v[166:169], v[130:145]
	ds_read_b128 v[224:227], v216 offset:57344
	v_add_f32_e32 v205, v100, v205
	v_add_f32_e32 v204, v101, v204
	v_cvt_pk_bf16_f32 v91, v100, v101
	v_permlane32_swap_b32_e32 v87, v89
	ds_read_b64_tr_b16 v[238:239], v206 offset:34816
	s_waitcnt lgkmcnt(5)
; #define SBAR() __builtin_amdgcn_sched_barrier(0)
; #define SLOAD(i, k0) do { sr_[i].vs0 = St::ld8(&Vh[(long)((k0) + sr) * LDK + sc]); sr_[i].vs1 = St::ld8(&Vh[(long)((k0) + 32 + sr) * LDK + sc]); \
;     sr_[i].ks0 = St::ld8(&Kh[(long)((k0) + sr) * LDK + sc]); sr_[i].ks1 = St::ld8(&Kh[(long)((k0) + 32 + sr) * LDK + sc]); } while (0)
; #define SWAIT() do { if constexpr (SDEPTH == 2) asm volatile("s_waitcnt vmcnt(4)" ::: "memory"); else asm volatile("s_waitcnt vmcnt(0)" ::: "memory"); } while (0)
; template <int D0> __device__ __forceinline__ void pv_one(f32x16& od, int vb, bf16x8 pa0, bf16x8 pa1, bf16x8 pa2, bf16x8 pa3) {
;   const s16x4 l0 = tr_read<v_rd_off(D0, 0, 0)>(vb), h0 = tr_read<v_rd_off(D0, 0, 1)>(vb), l1 = tr_read<v_rd_off(D0, 1, 0)>(vb), h1 = tr_read<v_rd_off(D0, 1, 1)>(vb);
;   const s16x4 l2 = tr_read<v_rd_off(D0, 2, 0)>(vb), h2 = tr_read<v_rd_off(D0, 2, 1)>(vb), l3 = tr_read<v_rd_off(D0, 3, 0)>(vb), h3 = tr_read<v_rd_off(D0, 3, 1)>(vb);
;   asm volatile("s_waitcnt lgkmcnt(0)" ::: "memory"); SBAR();
;     ...
;   od = __builtin_amdgcn_mfma_f32_32x32x16_bf16(pa0, PK(l0, h0), od, 0, 0, 0);
;   od = __builtin_amdgcn_mfma_f32_32x32x16_bf16(pa1, PK(l1, h1), od, 0, 0, 0);
;   od = __builtin_amdgcn_mfma_f32_32x32x16_bf16(pa2, PK(l2, h2), od, 0, 0, 0);
;   od = __builtin_amdgcn_mfma_f32_32x32x16_bf16(pa3, PK(l3, h3), od, 0, 0, 0);
;     ...
; }
; __device__ __forceinline__ void pv_d0(f32x16* o, int vb, bf16x8 pa0, bf16x8 pa1, bf16x8 pa2, bf16x8 pa3) {
;   pv_one<0>(o[0], vb, pa0, pa1, pa2, pa3); pv_one<1>(o[1], vb, pa0, pa1, pa2, pa3); pv_one<2>(o[2], vb, pa0, pa1, pa2, pa3); pv_one<3>(o[3], vb, pa0, pa1, pa2, pa3);
; template <typename TQ> ...
;     ...
;   for (int j = 1; j + 1 < NT; j += 2) {
;     SBAR(); SLOAD(SO, (j + SDEPTH) * KVBLK); SBAR();
;     qkt(pB0, pB1, (bf16*)((char*)K_lds + SHM_K), qr, r32, hi, negm);
;     finishSM(pA0, pA1, l_reg, pa0, pa1, pa2, pa3); SBAR();
;     pv_d0(o, vb0, pa0, pa1, pa2, pa3); partialSM(pB0, pB1, mC);
;     __syncthreads(); SWAIT(); SWRITE(0, SE);
;     __syncthreads();
;     SBAR(); if (SDEPTH == 1 || j + 3 < NT) SLOAD(SE, (j + 1 + SDEPTH) * KVBLK); SBAR();
;     qkt(pA0, pA1, K_lds, qr, r32, hi, negm);
;     finishSM(pB0, pB1, l_reg, pa0, pa1, pa2, pa3); SBAR();
;     pv_d0(o, vb0 + (int)SHM_V, pa0, pa1, pa2, pa3); partialSM(pA0, pA1, mC);
;     __syncthreads(); SWAIT(); SWRITE(1, SO);
;     __syncthreads();
	v_mfma_f32_32x32x16_bf16 v[114:129], v[228:231], v[174:177], v[114:129]
	ds_read_b128 v[228:231], v215 offset:49152
	v_add_f32_e32 v205, v102, v205
	v_add_f32_e32 v204, v103, v204
	v_cvt_pk_bf16_f32 v92, v102, v103
	ds_read_b64_tr_b16 v[240:241], v206 offset:36864
	s_waitcnt lgkmcnt(6)
	v_mfma_f32_32x32x16_bf16 v[130:145], v[232:235], v[174:177], v[130:145]
	ds_read_b128 v[232:235], v215 offset:57344
	v_add_f32_e32 v205, v104, v205
	v_add_f32_e32 v204, v105, v204
	v_cvt_pk_bf16_f32 v93, v104, v105
	ds_read_b64_tr_b16 v[242:243], v206 offset:38912
	s_waitcnt lgkmcnt(7)
	v_mfma_f32_32x32x16_bf16 v[114:129], v[220:223], v[162:165], v[114:129]
	v_add_f32_e32 v205, v106, v205
	v_add_f32_e32 v204, v107, v204
	v_cvt_pk_bf16_f32 v94, v106, v107
	v_permlane32_swap_b32_e32 v90, v92
	ds_read_b64_tr_b16 v[244:245], v206 offset:40960
	ds_read_b64_tr_b16 v[98:99], v206 offset:33280
	s_waitcnt lgkmcnt(7)
	v_mfma_f32_32x32x16_bf16 v[130:145], v[224:227], v[162:165], v[130:145]
	v_add_f32_e32 v205, v108, v205
	v_add_f32_e32 v204, v109, v204
	v_cvt_pk_bf16_f32 v95, v108, v109
	v_permlane32_swap_b32_e32 v91, v93
	ds_read_b64_tr_b16 v[246:247], v206 offset:43008
	ds_read_b64_tr_b16 v[100:101], v206 offset:35328
	s_waitcnt lgkmcnt(7)
	v_mfma_f32_32x32x16_bf16 v[114:129], v[228:231], v[170:173], v[114:129]
	v_add_f32_e32 v205, v110, v205
	v_add_f32_e32 v204, v111, v204
	v_cvt_pk_bf16_f32 v96, v110, v111
	ds_read_b64_tr_b16 v[248:249], v206 offset:45056
	ds_read_b64_tr_b16 v[102:103], v206 offset:37376
	s_waitcnt lgkmcnt(7)
	v_mfma_f32_32x32x16_bf16 v[130:145], v[232:235], v[170:173], v[130:145]
	v_add_f32_e32 v205, v112, v205
	v_add_f32_e32 v204, v113, v204
	v_cvt_pk_bf16_f32 v97, v112, v113
	ds_read_b64_tr_b16 v[250:251], v206 offset:47104
	ds_read_b64_tr_b16 v[104:105], v206 offset:39424
	v_mfma_f32_32x32x16_bf16 v[18:33], v[82:85], v[236:239], v[18:33]
	v_permlane32_swap_b32_e32 v94, v96
	v_permlane32_swap_b32_e32 v95, v97
	ds_read_b64_tr_b16 v[236:237], v206 offset:41472
	ds_read_b64_tr_b16 v[238:239], v206 offset:43520
	s_waitcnt lgkmcnt(10)
	v_mfma_f32_32x32x16_bf16 v[18:33], v[86:89], v[240:243], v[18:33]
	ds_read_b64_tr_b16 v[240:241], v206 offset:45568
	ds_read_b64_tr_b16 v[242:243], v206 offset:47616
	v_exp_f32_e32 v114, v114
	v_exp_f32_e32 v115, v115
	s_waitcnt lgkmcnt(9)
	v_mfma_f32_32x32x16_bf16 v[18:33], v[90:93], v[244:247], v[18:33]
	ds_read_b64_tr_b16 v[244:245], v206 offset:33792
	ds_read_b64_tr_b16 v[246:247], v206 offset:35840
	v_exp_f32_e32 v116, v116
	v_exp_f32_e32 v117, v117
	s_waitcnt lgkmcnt(7)
	v_mfma_f32_32x32x16_bf16 v[18:33], v[94:97], v[248:251], v[18:33]
	ds_read_b64_tr_b16 v[248:249], v206 offset:37888
	ds_read_b64_tr_b16 v[250:251], v206 offset:39936
	v_exp_f32_e32 v118, v118
	v_exp_f32_e32 v119, v119
	v_mfma_f32_32x32x16_bf16 v[34:49], v[82:85], v[98:101], v[34:49]
	ds_read_b64_tr_b16 v[98:99], v206 offset:41984
	ds_read_b64_tr_b16 v[100:101], v206 offset:44032
	v_exp_f32_e32 v120, v120
	v_exp_f32_e32 v121, v121
	s_waitcnt lgkmcnt(10)
	v_mfma_f32_32x32x16_bf16 v[34:49], v[86:89], v[102:105], v[34:49]
	ds_read_b64_tr_b16 v[102:103], v206 offset:46080
	ds_read_b64_tr_b16 v[104:105], v206 offset:48128
	v_exp_f32_e32 v122, v122
	v_exp_f32_e32 v123, v123
	s_waitcnt lgkmcnt(10)
	v_mfma_f32_32x32x16_bf16 v[34:49], v[90:93], v[236:239], v[34:49]
	ds_read_b64_tr_b16 v[236:237], v206 offset:34304
	ds_read_b64_tr_b16 v[238:239], v206 offset:36352
	v_exp_f32_e32 v124, v124
	v_exp_f32_e32 v125, v125
	s_waitcnt lgkmcnt(10)
	v_mfma_f32_32x32x16_bf16 v[34:49], v[94:97], v[240:243], v[34:49]
	ds_read_b64_tr_b16 v[240:241], v206 offset:38400
	ds_read_b64_tr_b16 v[242:243], v206 offset:40448
	v_exp_f32_e32 v126, v126
	v_exp_f32_e32 v127, v127
	s_waitcnt lgkmcnt(10)
	v_mfma_f32_32x32x16_bf16 v[50:65], v[82:85], v[244:247], v[50:65]
	ds_read_b64_tr_b16 v[244:245], v206 offset:42496
	ds_read_b64_tr_b16 v[246:247], v206 offset:44544
	v_exp_f32_e32 v128, v128
	v_exp_f32_e32 v129, v129
	s_waitcnt lgkmcnt(10)
	v_mfma_f32_32x32x16_bf16 v[50:65], v[86:89], v[248:251], v[50:65]
	ds_read_b64_tr_b16 v[248:249], v206 offset:46592
	ds_read_b64_tr_b16 v[250:251], v206 offset:48640
	v_exp_f32_e32 v130, v130
	v_exp_f32_e32 v131, v131
	s_waitcnt lgkmcnt(10)
	v_mfma_f32_32x32x16_bf16 v[50:65], v[90:93], v[98:101], v[50:65]
	v_exp_f32_e32 v132, v132
	v_exp_f32_e32 v133, v133
	s_waitcnt lgkmcnt(8)
	v_mfma_f32_32x32x16_bf16 v[50:65], v[94:97], v[102:105], v[50:65]
	v_exp_f32_e32 v134, v134
	v_exp_f32_e32 v135, v135
	s_waitcnt lgkmcnt(6)
	v_mfma_f32_32x32x16_bf16 v[66:81], v[82:85], v[236:239], v[66:81]
	v_exp_f32_e32 v136, v136
	v_exp_f32_e32 v137, v137
	ds_read_b128 v[220:223], v210 offset:0
	s_waitcnt lgkmcnt(5)
	v_mfma_f32_32x32x16_bf16 v[66:81], v[86:89], v[240:243], v[66:81]
	v_exp_f32_e32 v138, v138
	v_exp_f32_e32 v139, v139
	ds_read_b128 v[224:227], v210 offset:8192
	s_waitcnt lgkmcnt(4)
	v_mfma_f32_32x32x16_bf16 v[66:81], v[90:93], v[244:247], v[66:81]
	v_exp_f32_e32 v140, v140
	v_exp_f32_e32 v141, v141
	ds_read_b128 v[228:231], v212 offset:0
	s_waitcnt lgkmcnt(3)
	v_mfma_f32_32x32x16_bf16 v[66:81], v[94:97], v[248:251], v[66:81]
	v_exp_f32_e32 v142, v142
	v_exp_f32_e32 v143, v143
	v_exp_f32_e32 v144, v144
	v_exp_f32_e32 v145, v145
	ds_read_b128 v[232:235], v212 offset:8192
	s_waitcnt vmcnt(4)
	s_barrier
; #define SBAR() __builtin_amdgcn_sched_barrier(0)
; #define SLOAD(i, k0) do { sr_[i].vs0 = St::ld8(&Vh[(long)((k0) + sr) * LDK + sc]); sr_[i].vs1 = St::ld8(&Vh[(long)((k0) + 32 + sr) * LDK + sc]); \
;     sr_[i].ks0 = St::ld8(&Kh[(long)((k0) + sr) * LDK + sc]); sr_[i].ks1 = St::ld8(&Kh[(long)((k0) + 32 + sr) * LDK + sc]); } while (0)
; #define SWAIT() do { if constexpr (SDEPTH == 2) asm volatile("s_waitcnt vmcnt(4)" ::: "memory"); else asm volatile("s_waitcnt vmcnt(0)" ::: "memory"); } while (0)
; template <int D0> __device__ __forceinline__ void pv_one(f32x16& od, int vb, bf16x8 pa0, bf16x8 pa1, bf16x8 pa2, bf16x8 pa3) {
;   const s16x4 l0 = tr_read<v_rd_off(D0, 0, 0)>(vb), h0 = tr_read<v_rd_off(D0, 0, 1)>(vb), l1 = tr_read<v_rd_off(D0, 1, 0)>(vb), h1 = tr_read<v_rd_off(D0, 1, 1)>(vb);
;   const s16x4 l2 = tr_read<v_rd_off(D0, 2, 0)>(vb), h2 = tr_read<v_rd_off(D0, 2, 1)>(vb), l3 = tr_read<v_rd_off(D0, 3, 0)>(vb), h3 = tr_read<v_rd_off(D0, 3, 1)>(vb);
;   asm volatile("s_waitcnt lgkmcnt(0)" ::: "memory"); SBAR();
;     ...
;   od = __builtin_amdgcn_mfma_f32_32x32x16_bf16(pa0, PK(l0, h0), od, 0, 0, 0);
;   od = __builtin_amdgcn_mfma_f32_32x32x16_bf16(pa1, PK(l1, h1), od, 0, 0, 0);
;   od = __builtin_amdgcn_mfma_f32_32x32x16_bf16(pa2, PK(l2, h2), od, 0, 0, 0);
;   od = __builtin_amdgcn_mfma_f32_32x32x16_bf16(pa3, PK(l3, h3), od, 0, 0, 0);
;     ...
; }
; __device__ __forceinline__ void pv_d0(f32x16* o, int vb, bf16x8 pa0, bf16x8 pa1, bf16x8 pa2, bf16x8 pa3) {
;   pv_one<0>(o[0], vb, pa0, pa1, pa2, pa3); pv_one<1>(o[1], vb, pa0, pa1, pa2, pa3); pv_one<2>(o[2], vb, pa0, pa1, pa2, pa3); pv_one<3>(o[3], vb, pa0, pa1, pa2, pa3);
; template <typename TQ> ...
;     ...
;   for (int j = 1; j + 1 < NT; j += 2) {
;     SBAR(); SLOAD(SO, (j + SDEPTH) * KVBLK); SBAR();
;     qkt(pB0, pB1, (bf16*)((char*)K_lds + SHM_K), qr, r32, hi, negm);
;     finishSM(pA0, pA1, l_reg, pa0, pa1, pa2, pa3); SBAR();
;     pv_d0(o, vb0, pa0, pa1, pa2, pa3); partialSM(pB0, pB1, mC);
;     __syncthreads(); SWAIT(); SWRITE(0, SE);
;     __syncthreads();
;     SBAR(); if (SDEPTH == 1 || j + 3 < NT) SLOAD(SE, (j + 1 + SDEPTH) * KVBLK); SBAR();
;     qkt(pA0, pA1, K_lds, qr, r32, hi, negm);
;     finishSM(pB0, pB1, l_reg, pa0, pa1, pa2, pa3); SBAR();
;     pv_d0(o, vb0 + (int)SHM_V, pa0, pa1, pa2, pa3); partialSM(pA0, pA1, mC);
;     __syncthreads(); SWAIT(); SWRITE(1, SO);
;     __syncthreads();
	s_waitcnt lgkmcnt(3)
	v_mfma_f32_32x32x16_bf16 v[82:97], v[220:223], v[150:153], v[2:17]
	ds_read_b128 v[220:223], v213 offset:0
	v_add_f32_e32 v205, v114, v205
	v_add_f32_e32 v204, v115, v204
	v_cvt_pk_bf16_f32 v114, v114, v115
	s_add_u32 s98, s98, 0x8000
	s_addc_u32 s99, s99, 0
	s_add_u32 s100, s100, 0x8000
	s_addc_u32 s101, s101, 0
	s_waitcnt lgkmcnt(3)
	v_mfma_f32_32x32x16_bf16 v[98:113], v[224:227], v[150:153], v[2:17]
	ds_read_b128 v[224:227], v213 offset:8192
	v_add_f32_e32 v205, v116, v205
	v_add_f32_e32 v204, v117, v204
	v_cvt_pk_bf16_f32 v115, v116, v117
	s_add_u32 m0, s79, 49152
	s_nop 0
	global_load_lds_dwordx4 v196, s[98:99]
	s_waitcnt lgkmcnt(3)
	v_mfma_f32_32x32x16_bf16 v[82:97], v[228:231], v[158:161], v[82:97]
	ds_read_b128 v[228:231], v214 offset:0
	v_add_f32_e32 v205, v118, v205
	v_add_f32_e32 v204, v119, v204
	v_cvt_pk_bf16_f32 v116, v118, v119
	s_add_u32 m0, s79, 50176
	s_nop 0
	global_load_lds_dwordx4 v197, s[98:99]
	s_waitcnt lgkmcnt(3)
	v_mfma_f32_32x32x16_bf16 v[98:113], v[232:235], v[158:161], v[98:113]
	ds_read_b128 v[232:235], v214 offset:8192
	v_add_f32_e32 v205, v120, v205
	v_add_f32_e32 v204, v121, v204
	v_cvt_pk_bf16_f32 v117, v120, v121
	s_add_u32 m0, s80, 32768
	s_nop 0
	global_load_lds_dwordx4 v207, s[100:101]
	s_waitcnt lgkmcnt(3)
	v_mfma_f32_32x32x16_bf16 v[82:97], v[220:223], v[146:149], v[82:97]
	ds_read_b128 v[220:223], v218 offset:0
	v_add_f32_e32 v205, v122, v205
	v_add_f32_e32 v204, v123, v204
	v_cvt_pk_bf16_f32 v118, v122, v123
	v_permlane32_swap_b32_e32 v114, v116
	s_add_u32 m0, s80, 33792
	s_nop 0
	global_load_lds_dwordx4 v208, s[100:101]
	s_waitcnt lgkmcnt(3)
	v_mfma_f32_32x32x16_bf16 v[98:113], v[224:227], v[146:149], v[98:113]
	ds_read_b128 v[224:227], v218 offset:8192
	v_add_f32_e32 v205, v124, v205
	v_add_f32_e32 v204, v125, v204
	v_cvt_pk_bf16_f32 v119, v124, v125
	v_permlane32_swap_b32_e32 v115, v117
	s_waitcnt lgkmcnt(3)
	v_mfma_f32_32x32x16_bf16 v[82:97], v[228:231], v[154:157], v[82:97]
	ds_read_b128 v[228:231], v217 offset:0
	v_add_f32_e32 v205, v126, v205
	v_add_f32_e32 v204, v127, v204
	v_cvt_pk_bf16_f32 v120, v126, v127
	s_waitcnt lgkmcnt(3)
	v_mfma_f32_32x32x16_bf16 v[98:113], v[232:235], v[154:157], v[98:113]
	ds_read_b128 v[232:235], v217 offset:8192
	v_add_f32_e32 v205, v128, v205
	v_add_f32_e32 v204, v129, v204
	v_cvt_pk_bf16_f32 v121, v128, v129
	s_waitcnt lgkmcnt(3)
	v_mfma_f32_32x32x16_bf16 v[82:97], v[220:223], v[166:169], v[82:97]
	ds_read_b128 v[220:223], v216 offset:0
	v_add_f32_e32 v205, v130, v205
	v_add_f32_e32 v204, v131, v204
	v_cvt_pk_bf16_f32 v122, v130, v131
	v_permlane32_swap_b32_e32 v118, v120
	ds_read_b64_tr_b16 v[236:237], v206 offset:49152
	s_waitcnt lgkmcnt(4)
	v_mfma_f32_32x32x16_bf16 v[98:113], v[224:227], v[166:169], v[98:113]
	ds_read_b128 v[224:227], v216 offset:8192
	v_add_f32_e32 v205, v132, v205
	v_add_f32_e32 v204, v133, v204
	v_cvt_pk_bf16_f32 v123, v132, v133
	v_permlane32_swap_b32_e32 v119, v121
	ds_read_b64_tr_b16 v[238:239], v206 offset:51200
	s_waitcnt lgkmcnt(5)
	v_mfma_f32_32x32x16_bf16 v[82:97], v[228:231], v[174:177], v[82:97]
	ds_read_b128 v[228:231], v215 offset:0
	v_add_f32_e32 v205, v134, v205
	v_add_f32_e32 v204, v135, v204
	v_cvt_pk_bf16_f32 v124, v134, v135
	ds_read_b64_tr_b16 v[240:241], v206 offset:53248
	s_waitcnt lgkmcnt(6)
	v_mfma_f32_32x32x16_bf16 v[98:113], v[232:235], v[174:177], v[98:113]
	ds_read_b128 v[232:235], v215 offset:8192
	v_add_f32_e32 v205, v136, v205
	v_add_f32_e32 v204, v137, v204
	v_cvt_pk_bf16_f32 v125, v136, v137
	ds_read_b64_tr_b16 v[242:243], v206 offset:55296
	s_waitcnt lgkmcnt(7)
	v_mfma_f32_32x32x16_bf16 v[82:97], v[220:223], v[162:165], v[82:97]
	v_add_f32_e32 v205, v138, v205
	v_add_f32_e32 v204, v139, v204
	v_cvt_pk_bf16_f32 v126, v138, v139
	v_permlane32_swap_b32_e32 v122, v124
	ds_read_b64_tr_b16 v[244:245], v206 offset:57344
	ds_read_b64_tr_b16 v[130:131], v206 offset:49664
	s_waitcnt lgkmcnt(7)
	v_mfma_f32_32x32x16_bf16 v[98:113], v[224:227], v[162:165], v[98:113]
	v_add_f32_e32 v205, v140, v205
	v_add_f32_e32 v204, v141, v204
	v_cvt_pk_bf16_f32 v127, v140, v141
	v_permlane32_swap_b32_e32 v123, v125
	ds_read_b64_tr_b16 v[246:247], v206 offset:59392
	ds_read_b64_tr_b16 v[132:133], v206 offset:51712
	s_waitcnt lgkmcnt(7)
	v_mfma_f32_32x32x16_bf16 v[82:97], v[228:231], v[170:173], v[82:97]
	v_add_f32_e32 v205, v142, v205
	v_add_f32_e32 v204, v143, v204
	v_cvt_pk_bf16_f32 v128, v142, v143
	ds_read_b64_tr_b16 v[248:249], v206 offset:61440
	ds_read_b64_tr_b16 v[134:135], v206 offset:53760
	s_waitcnt lgkmcnt(7)
	v_mfma_f32_32x32x16_bf16 v[98:113], v[232:235], v[170:173], v[98:113]
	v_add_f32_e32 v205, v144, v205
	v_add_f32_e32 v204, v145, v204
	v_cvt_pk_bf16_f32 v129, v144, v145
	ds_read_b64_tr_b16 v[250:251], v206 offset:63488
	ds_read_b64_tr_b16 v[136:137], v206 offset:55808
	v_mfma_f32_32x32x16_bf16 v[18:33], v[114:117], v[236:239], v[18:33]
	v_permlane32_swap_b32_e32 v126, v128
	v_permlane32_swap_b32_e32 v127, v129
	ds_read_b64_tr_b16 v[236:237], v206 offset:57856
	ds_read_b64_tr_b16 v[238:239], v206 offset:59904
	s_waitcnt lgkmcnt(10)
	v_mfma_f32_32x32x16_bf16 v[18:33], v[118:121], v[240:243], v[18:33]
	ds_read_b64_tr_b16 v[240:241], v206 offset:61952
	ds_read_b64_tr_b16 v[242:243], v206 offset:64000
	v_exp_f32_e32 v82, v82
	v_exp_f32_e32 v83, v83
	s_waitcnt lgkmcnt(9)
	v_mfma_f32_32x32x16_bf16 v[18:33], v[122:125], v[244:247], v[18:33]
	ds_read_b64_tr_b16 v[244:245], v206 offset:50176
	ds_read_b64_tr_b16 v[246:247], v206 offset:52224
	v_exp_f32_e32 v84, v84
	v_exp_f32_e32 v85, v85
	s_waitcnt lgkmcnt(7)
; #define SBAR() __builtin_amdgcn_sched_barrier(0)
; #define SWAIT() do { if constexpr (SDEPTH == 2) asm volatile("s_waitcnt vmcnt(4)" ::: "memory"); else asm volatile("s_waitcnt vmcnt(0)" ::: "memory"); } while (0)
; template <int D0> __device__ __forceinline__ void pv_one(f32x16& od, int vb, bf16x8 pa0, bf16x8 pa1, bf16x8 pa2, bf16x8 pa3) {
;   const s16x4 l0 = tr_read<v_rd_off(D0, 0, 0)>(vb), h0 = tr_read<v_rd_off(D0, 0, 1)>(vb), l1 = tr_read<v_rd_off(D0, 1, 0)>(vb), h1 = tr_read<v_rd_off(D0, 1, 1)>(vb);
;   const s16x4 l2 = tr_read<v_rd_off(D0, 2, 0)>(vb), h2 = tr_read<v_rd_off(D0, 2, 1)>(vb), l3 = tr_read<v_rd_off(D0, 3, 0)>(vb), h3 = tr_read<v_rd_off(D0, 3, 1)>(vb);
;   asm volatile("s_waitcnt lgkmcnt(0)" ::: "memory"); SBAR();
;     ...
;   od = __builtin_amdgcn_mfma_f32_32x32x16_bf16(pa0, PK(l0, h0), od, 0, 0, 0);
;   od = __builtin_amdgcn_mfma_f32_32x32x16_bf16(pa1, PK(l1, h1), od, 0, 0, 0);
;   od = __builtin_amdgcn_mfma_f32_32x32x16_bf16(pa2, PK(l2, h2), od, 0, 0, 0);
;   od = __builtin_amdgcn_mfma_f32_32x32x16_bf16(pa3, PK(l3, h3), od, 0, 0, 0);
;     ...
; }
; __device__ __forceinline__ void pv_d0(f32x16* o, int vb, bf16x8 pa0, bf16x8 pa1, bf16x8 pa2, bf16x8 pa3) {
;   pv_one<0>(o[0], vb, pa0, pa1, pa2, pa3); pv_one<1>(o[1], vb, pa0, pa1, pa2, pa3); pv_one<2>(o[2], vb, pa0, pa1, pa2, pa3); pv_one<3>(o[3], vb, pa0, pa1, pa2, pa3);
; template <typename TQ> ...
;     ...
;   for (int j = 1; j + 1 < NT; j += 2) {
;     SBAR(); SLOAD(SO, (j + SDEPTH) * KVBLK); SBAR();
;     qkt(pB0, pB1, (bf16*)((char*)K_lds + SHM_K), qr, r32, hi, negm);
;     finishSM(pA0, pA1, l_reg, pa0, pa1, pa2, pa3); SBAR();
;     pv_d0(o, vb0, pa0, pa1, pa2, pa3); partialSM(pB0, pB1, mC);
;     __syncthreads(); SWAIT(); SWRITE(0, SE);
;     __syncthreads();
;     SBAR(); if (SDEPTH == 1 || j + 3 < NT) SLOAD(SE, (j + 1 + SDEPTH) * KVBLK); SBAR();
;     qkt(pA0, pA1, K_lds, qr, r32, hi, negm);
;     finishSM(pB0, pB1, l_reg, pa0, pa1, pa2, pa3); SBAR();
;     pv_d0(o, vb0 + (int)SHM_V, pa0, pa1, pa2, pa3); partialSM(pA0, pA1, mC);
;     __syncthreads(); SWAIT(); SWRITE(1, SO);
;     __syncthreads();
;   }
;   SBAR(); qkt(pB0, pB1, (bf16*)((char*)K_lds + SHM_K), qr, r32, hi, negm);
;   finishSM(pA0, pA1, l_reg, pa0, pa1, pa2, pa3); SBAR();
;   pv_d0(o, vb0, pa0, pa1, pa2, pa3); partialSM(pB0, pB1, mC);
	v_mfma_f32_32x32x16_bf16 v[18:33], v[126:129], v[248:251], v[18:33]
	ds_read_b64_tr_b16 v[248:249], v206 offset:54272
	ds_read_b64_tr_b16 v[250:251], v206 offset:56320
	v_exp_f32_e32 v86, v86
	v_exp_f32_e32 v87, v87
	v_mfma_f32_32x32x16_bf16 v[34:49], v[114:117], v[130:133], v[34:49]
	ds_read_b64_tr_b16 v[130:131], v206 offset:58368
	ds_read_b64_tr_b16 v[132:133], v206 offset:60416
	v_exp_f32_e32 v88, v88
	v_exp_f32_e32 v89, v89
	s_waitcnt lgkmcnt(10)
	v_mfma_f32_32x32x16_bf16 v[34:49], v[118:121], v[134:137], v[34:49]
	ds_read_b64_tr_b16 v[134:135], v206 offset:62464
	ds_read_b64_tr_b16 v[136:137], v206 offset:64512
	v_exp_f32_e32 v90, v90
	v_exp_f32_e32 v91, v91
	s_waitcnt lgkmcnt(10)
	v_mfma_f32_32x32x16_bf16 v[34:49], v[122:125], v[236:239], v[34:49]
	ds_read_b64_tr_b16 v[236:237], v206 offset:50688
	ds_read_b64_tr_b16 v[238:239], v206 offset:52736
	v_exp_f32_e32 v92, v92
	v_exp_f32_e32 v93, v93
	s_waitcnt lgkmcnt(10)
	v_mfma_f32_32x32x16_bf16 v[34:49], v[126:129], v[240:243], v[34:49]
	ds_read_b64_tr_b16 v[240:241], v206 offset:54784
	ds_read_b64_tr_b16 v[242:243], v206 offset:56832
	v_exp_f32_e32 v94, v94
	v_exp_f32_e32 v95, v95
	s_waitcnt lgkmcnt(10)
	v_mfma_f32_32x32x16_bf16 v[50:65], v[114:117], v[244:247], v[50:65]
	ds_read_b64_tr_b16 v[244:245], v206 offset:58880
	ds_read_b64_tr_b16 v[246:247], v206 offset:60928
	v_exp_f32_e32 v96, v96
	v_exp_f32_e32 v97, v97
	s_waitcnt lgkmcnt(10)
	v_mfma_f32_32x32x16_bf16 v[50:65], v[118:121], v[248:251], v[50:65]
	ds_read_b64_tr_b16 v[248:249], v206 offset:62976
	ds_read_b64_tr_b16 v[250:251], v206 offset:65024
	v_exp_f32_e32 v98, v98
	v_exp_f32_e32 v99, v99
	s_waitcnt lgkmcnt(10)
	v_mfma_f32_32x32x16_bf16 v[50:65], v[122:125], v[130:133], v[50:65]
	v_exp_f32_e32 v100, v100
	v_exp_f32_e32 v101, v101
	s_waitcnt lgkmcnt(8)
	v_mfma_f32_32x32x16_bf16 v[50:65], v[126:129], v[134:137], v[50:65]
	v_exp_f32_e32 v102, v102
	v_exp_f32_e32 v103, v103
	s_waitcnt lgkmcnt(6)
	v_mfma_f32_32x32x16_bf16 v[66:81], v[114:117], v[236:239], v[66:81]
	v_exp_f32_e32 v104, v104
	v_exp_f32_e32 v105, v105
	ds_read_b128 v[220:223], v210 offset:16384
	s_waitcnt lgkmcnt(5)
	v_mfma_f32_32x32x16_bf16 v[66:81], v[118:121], v[240:243], v[66:81]
	v_exp_f32_e32 v106, v106
	v_exp_f32_e32 v107, v107
	ds_read_b128 v[224:227], v210 offset:24576
	s_waitcnt lgkmcnt(4)
	v_mfma_f32_32x32x16_bf16 v[66:81], v[122:125], v[244:247], v[66:81]
	v_exp_f32_e32 v108, v108
	v_exp_f32_e32 v109, v109
	ds_read_b128 v[228:231], v212 offset:16384
	s_waitcnt lgkmcnt(3)
	v_mfma_f32_32x32x16_bf16 v[66:81], v[126:129], v[248:251], v[66:81]
	v_exp_f32_e32 v110, v110
	v_exp_f32_e32 v111, v111
	v_exp_f32_e32 v112, v112
	v_exp_f32_e32 v113, v113
	ds_read_b128 v[232:235], v212 offset:24576
	s_waitcnt vmcnt(4)
	s_add_i32 s0, s0, 1
	s_cmp_lt_u32 s0, 32
	s_cbranch_scc1 .Lattn_loop
	s_barrier
	s_waitcnt lgkmcnt(3)
	v_mfma_f32_32x32x16_bf16 v[114:129], v[220:223], v[150:153], v[2:17]
	ds_read_b128 v[220:223], v213 offset:16384
	v_add_f32_e32 v205, v82, v205
	v_add_f32_e32 v204, v83, v204
	v_cvt_pk_bf16_f32 v82, v82, v83
	s_add_u32 s98, s98, 0x8000
	s_addc_u32 s99, s99, 0
	s_add_u32 s100, s100, 0x8000
	s_addc_u32 s101, s101, 0
	s_waitcnt lgkmcnt(3)
	v_mfma_f32_32x32x16_bf16 v[130:145], v[224:227], v[150:153], v[2:17]
	ds_read_b128 v[224:227], v213 offset:24576
	v_add_f32_e32 v205, v84, v205
	v_add_f32_e32 v204, v85, v204
	v_cvt_pk_bf16_f32 v83, v84, v85
	s_waitcnt lgkmcnt(3)
	v_mfma_f32_32x32x16_bf16 v[114:129], v[228:231], v[158:161], v[114:129]
	ds_read_b128 v[228:231], v214 offset:16384
	v_add_f32_e32 v205, v86, v205
	v_add_f32_e32 v204, v87, v204
	v_cvt_pk_bf16_f32 v84, v86, v87
	s_waitcnt lgkmcnt(3)
	v_mfma_f32_32x32x16_bf16 v[130:145], v[232:235], v[158:161], v[130:145]
	ds_read_b128 v[232:235], v214 offset:24576
	v_add_f32_e32 v205, v88, v205
	v_add_f32_e32 v204, v89, v204
	v_cvt_pk_bf16_f32 v85, v88, v89
	s_add_u32 m0, s80, 49152
	s_nop 0
	global_load_lds_dwordx4 v207, s[100:101]
	s_waitcnt lgkmcnt(3)
	v_mfma_f32_32x32x16_bf16 v[114:129], v[220:223], v[146:149], v[114:129]
	ds_read_b128 v[220:223], v218 offset:16384
	v_add_f32_e32 v205, v90, v205
	v_add_f32_e32 v204, v91, v204
	v_cvt_pk_bf16_f32 v86, v90, v91
	v_permlane32_swap_b32_e32 v82, v84
	s_add_u32 m0, s80, 50176
	s_nop 0
	global_load_lds_dwordx4 v208, s[100:101]
	s_waitcnt lgkmcnt(3)
	v_mfma_f32_32x32x16_bf16 v[130:145], v[224:227], v[146:149], v[130:145]
	ds_read_b128 v[224:227], v218 offset:24576
	v_add_f32_e32 v205, v92, v205
	v_add_f32_e32 v204, v93, v204
	v_cvt_pk_bf16_f32 v87, v92, v93
	v_permlane32_swap_b32_e32 v83, v85
	s_waitcnt lgkmcnt(3)
	v_mfma_f32_32x32x16_bf16 v[114:129], v[228:231], v[154:157], v[114:129]
	ds_read_b128 v[228:231], v217 offset:16384
	v_add_f32_e32 v205, v94, v205
	v_add_f32_e32 v204, v95, v204
	v_cvt_pk_bf16_f32 v88, v94, v95
	s_waitcnt lgkmcnt(3)
	v_mfma_f32_32x32x16_bf16 v[130:145], v[232:235], v[154:157], v[130:145]
	ds_read_b128 v[232:235], v217 offset:24576
	v_add_f32_e32 v205, v96, v205
	v_add_f32_e32 v204, v97, v204
	v_cvt_pk_bf16_f32 v89, v96, v97
	s_waitcnt lgkmcnt(3)
	v_mfma_f32_32x32x16_bf16 v[114:129], v[220:223], v[166:169], v[114:129]
	ds_read_b128 v[220:223], v216 offset:16384
	v_add_f32_e32 v205, v98, v205
	v_add_f32_e32 v204, v99, v204
	v_cvt_pk_bf16_f32 v90, v98, v99
	v_permlane32_swap_b32_e32 v86, v88
	ds_read_b64_tr_b16 v[236:237], v206 offset:0
	s_waitcnt lgkmcnt(4)
	v_mfma_f32_32x32x16_bf16 v[130:145], v[224:227], v[166:169], v[130:145]
	ds_read_b128 v[224:227], v216 offset:24576
	v_add_f32_e32 v205, v100, v205
	v_add_f32_e32 v204, v101, v204
	v_cvt_pk_bf16_f32 v91, v100, v101
	v_permlane32_swap_b32_e32 v87, v89
	ds_read_b64_tr_b16 v[238:239], v206 offset:2048
	s_waitcnt lgkmcnt(5)
; #define SBAR() __builtin_amdgcn_sched_barrier(0)
; template <int D0> __device__ __forceinline__ void pv_one(f32x16& od, int vb, bf16x8 pa0, bf16x8 pa1, bf16x8 pa2, bf16x8 pa3) {
;   const s16x4 l0 = tr_read<v_rd_off(D0, 0, 0)>(vb), h0 = tr_read<v_rd_off(D0, 0, 1)>(vb), l1 = tr_read<v_rd_off(D0, 1, 0)>(vb), h1 = tr_read<v_rd_off(D0, 1, 1)>(vb);
;   const s16x4 l2 = tr_read<v_rd_off(D0, 2, 0)>(vb), h2 = tr_read<v_rd_off(D0, 2, 1)>(vb), l3 = tr_read<v_rd_off(D0, 3, 0)>(vb), h3 = tr_read<v_rd_off(D0, 3, 1)>(vb);
;   asm volatile("s_waitcnt lgkmcnt(0)" ::: "memory"); SBAR();
;     ...
;   od = __builtin_amdgcn_mfma_f32_32x32x16_bf16(pa0, PK(l0, h0), od, 0, 0, 0);
;   od = __builtin_amdgcn_mfma_f32_32x32x16_bf16(pa1, PK(l1, h1), od, 0, 0, 0);
;   od = __builtin_amdgcn_mfma_f32_32x32x16_bf16(pa2, PK(l2, h2), od, 0, 0, 0);
;   od = __builtin_amdgcn_mfma_f32_32x32x16_bf16(pa3, PK(l3, h3), od, 0, 0, 0);
;     ...
; }
; __device__ __forceinline__ void pv_d0(f32x16* o, int vb, bf16x8 pa0, bf16x8 pa1, bf16x8 pa2, bf16x8 pa3) {
;   pv_one<0>(o[0], vb, pa0, pa1, pa2, pa3); pv_one<1>(o[1], vb, pa0, pa1, pa2, pa3); pv_one<2>(o[2], vb, pa0, pa1, pa2, pa3); pv_one<3>(o[3], vb, pa0, pa1, pa2, pa3);
; template <typename TQ> ...
;     ...
;   SBAR(); qkt(pB0, pB1, (bf16*)((char*)K_lds + SHM_K), qr, r32, hi, negm);
;   finishSM(pA0, pA1, l_reg, pa0, pa1, pa2, pa3); SBAR();
;   pv_d0(o, vb0, pa0, pa1, pa2, pa3); partialSM(pB0, pB1, mC);
;   __syncthreads();
	v_mfma_f32_32x32x16_bf16 v[114:129], v[228:231], v[174:177], v[114:129]
	ds_read_b128 v[228:231], v215 offset:16384
	v_add_f32_e32 v205, v102, v205
	v_add_f32_e32 v204, v103, v204
	v_cvt_pk_bf16_f32 v92, v102, v103
	ds_read_b64_tr_b16 v[240:241], v206 offset:4096
	s_waitcnt lgkmcnt(6)
	v_mfma_f32_32x32x16_bf16 v[130:145], v[232:235], v[174:177], v[130:145]
	ds_read_b128 v[232:235], v215 offset:24576
	v_add_f32_e32 v205, v104, v205
	v_add_f32_e32 v204, v105, v204
	v_cvt_pk_bf16_f32 v93, v104, v105
	ds_read_b64_tr_b16 v[242:243], v206 offset:6144
	s_waitcnt lgkmcnt(7)
	v_mfma_f32_32x32x16_bf16 v[114:129], v[220:223], v[162:165], v[114:129]
	v_add_f32_e32 v205, v106, v205
	v_add_f32_e32 v204, v107, v204
	v_cvt_pk_bf16_f32 v94, v106, v107
	v_permlane32_swap_b32_e32 v90, v92
	ds_read_b64_tr_b16 v[244:245], v206 offset:8192
	ds_read_b64_tr_b16 v[98:99], v206 offset:512
	s_waitcnt lgkmcnt(7)
	v_mfma_f32_32x32x16_bf16 v[130:145], v[224:227], v[162:165], v[130:145]
	v_add_f32_e32 v205, v108, v205
	v_add_f32_e32 v204, v109, v204
	v_cvt_pk_bf16_f32 v95, v108, v109
	v_permlane32_swap_b32_e32 v91, v93
	ds_read_b64_tr_b16 v[246:247], v206 offset:10240
	ds_read_b64_tr_b16 v[100:101], v206 offset:2560
	s_waitcnt lgkmcnt(7)
	v_mfma_f32_32x32x16_bf16 v[114:129], v[228:231], v[170:173], v[114:129]
	v_add_f32_e32 v205, v110, v205
	v_add_f32_e32 v204, v111, v204
	v_cvt_pk_bf16_f32 v96, v110, v111
	ds_read_b64_tr_b16 v[248:249], v206 offset:12288
	ds_read_b64_tr_b16 v[102:103], v206 offset:4608
	s_waitcnt lgkmcnt(7)
	v_mfma_f32_32x32x16_bf16 v[130:145], v[232:235], v[170:173], v[130:145]
	v_add_f32_e32 v205, v112, v205
	v_add_f32_e32 v204, v113, v204
	v_cvt_pk_bf16_f32 v97, v112, v113
	ds_read_b64_tr_b16 v[250:251], v206 offset:14336
	ds_read_b64_tr_b16 v[104:105], v206 offset:6656
	v_mfma_f32_32x32x16_bf16 v[18:33], v[82:85], v[236:239], v[18:33]
	v_permlane32_swap_b32_e32 v94, v96
	v_permlane32_swap_b32_e32 v95, v97
	ds_read_b64_tr_b16 v[236:237], v206 offset:8704
	ds_read_b64_tr_b16 v[238:239], v206 offset:10752
	s_waitcnt lgkmcnt(10)
	v_mfma_f32_32x32x16_bf16 v[18:33], v[86:89], v[240:243], v[18:33]
	ds_read_b64_tr_b16 v[240:241], v206 offset:12800
	ds_read_b64_tr_b16 v[242:243], v206 offset:14848
	v_exp_f32_e32 v114, v114
	v_exp_f32_e32 v115, v115
	s_waitcnt lgkmcnt(9)
	v_mfma_f32_32x32x16_bf16 v[18:33], v[90:93], v[244:247], v[18:33]
	ds_read_b64_tr_b16 v[244:245], v206 offset:1024
	ds_read_b64_tr_b16 v[246:247], v206 offset:3072
	v_exp_f32_e32 v116, v116
	v_exp_f32_e32 v117, v117
	s_waitcnt lgkmcnt(7)
	v_mfma_f32_32x32x16_bf16 v[18:33], v[94:97], v[248:251], v[18:33]
	ds_read_b64_tr_b16 v[248:249], v206 offset:5120
	ds_read_b64_tr_b16 v[250:251], v206 offset:7168
	v_exp_f32_e32 v118, v118
	v_exp_f32_e32 v119, v119
	v_mfma_f32_32x32x16_bf16 v[34:49], v[82:85], v[98:101], v[34:49]
	ds_read_b64_tr_b16 v[98:99], v206 offset:9216
	ds_read_b64_tr_b16 v[100:101], v206 offset:11264
	v_exp_f32_e32 v120, v120
	v_exp_f32_e32 v121, v121
	s_waitcnt lgkmcnt(10)
	v_mfma_f32_32x32x16_bf16 v[34:49], v[86:89], v[102:105], v[34:49]
	ds_read_b64_tr_b16 v[102:103], v206 offset:13312
	ds_read_b64_tr_b16 v[104:105], v206 offset:15360
	v_exp_f32_e32 v122, v122
	v_exp_f32_e32 v123, v123
	s_waitcnt lgkmcnt(10)
	v_mfma_f32_32x32x16_bf16 v[34:49], v[90:93], v[236:239], v[34:49]
	ds_read_b64_tr_b16 v[236:237], v206 offset:1536
	ds_read_b64_tr_b16 v[238:239], v206 offset:3584
	v_exp_f32_e32 v124, v124
	v_exp_f32_e32 v125, v125
	s_waitcnt lgkmcnt(10)
	v_mfma_f32_32x32x16_bf16 v[34:49], v[94:97], v[240:243], v[34:49]
	ds_read_b64_tr_b16 v[240:241], v206 offset:5632
	ds_read_b64_tr_b16 v[242:243], v206 offset:7680
	v_exp_f32_e32 v126, v126
	v_exp_f32_e32 v127, v127
	s_waitcnt lgkmcnt(10)
	v_mfma_f32_32x32x16_bf16 v[50:65], v[82:85], v[244:247], v[50:65]
	ds_read_b64_tr_b16 v[244:245], v206 offset:9728
	ds_read_b64_tr_b16 v[246:247], v206 offset:11776
	v_exp_f32_e32 v128, v128
	v_exp_f32_e32 v129, v129
	s_waitcnt lgkmcnt(10)
	v_mfma_f32_32x32x16_bf16 v[50:65], v[86:89], v[248:251], v[50:65]
	ds_read_b64_tr_b16 v[248:249], v206 offset:13824
	ds_read_b64_tr_b16 v[250:251], v206 offset:15872
	v_exp_f32_e32 v130, v130
	v_exp_f32_e32 v131, v131
	s_waitcnt lgkmcnt(10)
	v_mfma_f32_32x32x16_bf16 v[50:65], v[90:93], v[98:101], v[50:65]
	v_exp_f32_e32 v132, v132
	v_exp_f32_e32 v133, v133
	s_waitcnt lgkmcnt(8)
	v_mfma_f32_32x32x16_bf16 v[50:65], v[94:97], v[102:105], v[50:65]
	v_exp_f32_e32 v134, v134
	v_exp_f32_e32 v135, v135
	s_waitcnt lgkmcnt(6)
	v_mfma_f32_32x32x16_bf16 v[66:81], v[82:85], v[236:239], v[66:81]
	v_exp_f32_e32 v136, v136
	v_exp_f32_e32 v137, v137
	ds_read_b128 v[220:223], v210 offset:32768
	s_waitcnt lgkmcnt(5)
	v_mfma_f32_32x32x16_bf16 v[66:81], v[86:89], v[240:243], v[66:81]
	v_exp_f32_e32 v138, v138
	v_exp_f32_e32 v139, v139
	ds_read_b128 v[224:227], v210 offset:40960
	s_waitcnt lgkmcnt(4)
	v_mfma_f32_32x32x16_bf16 v[66:81], v[90:93], v[244:247], v[66:81]
	v_exp_f32_e32 v140, v140
	v_exp_f32_e32 v141, v141
	ds_read_b128 v[228:231], v212 offset:32768
	s_waitcnt lgkmcnt(3)
	v_mfma_f32_32x32x16_bf16 v[66:81], v[94:97], v[248:251], v[66:81]
	v_exp_f32_e32 v142, v142
	v_exp_f32_e32 v143, v143
	v_exp_f32_e32 v144, v144
	v_exp_f32_e32 v145, v145
	ds_read_b128 v[232:235], v212 offset:40960
	s_waitcnt vmcnt(2)
	s_barrier
; #define SBAR() __builtin_amdgcn_sched_barrier(0)
; template <int D0> __device__ __forceinline__ void pv_one(f32x16& od, int vb, bf16x8 pa0, bf16x8 pa1, bf16x8 pa2, bf16x8 pa3) {
;   const s16x4 l0 = tr_read<v_rd_off(D0, 0, 0)>(vb), h0 = tr_read<v_rd_off(D0, 0, 1)>(vb), l1 = tr_read<v_rd_off(D0, 1, 0)>(vb), h1 = tr_read<v_rd_off(D0, 1, 1)>(vb);
;   const s16x4 l2 = tr_read<v_rd_off(D0, 2, 0)>(vb), h2 = tr_read<v_rd_off(D0, 2, 1)>(vb), l3 = tr_read<v_rd_off(D0, 3, 0)>(vb), h3 = tr_read<v_rd_off(D0, 3, 1)>(vb);
;   asm volatile("s_waitcnt lgkmcnt(0)" ::: "memory"); SBAR();
;     ...
;   od = __builtin_amdgcn_mfma_f32_32x32x16_bf16(pa0, PK(l0, h0), od, 0, 0, 0);
;   od = __builtin_amdgcn_mfma_f32_32x32x16_bf16(pa1, PK(l1, h1), od, 0, 0, 0);
;   od = __builtin_amdgcn_mfma_f32_32x32x16_bf16(pa2, PK(l2, h2), od, 0, 0, 0);
;   od = __builtin_amdgcn_mfma_f32_32x32x16_bf16(pa3, PK(l3, h3), od, 0, 0, 0);
;     ...
; }
; __device__ __forceinline__ void pv_d0(f32x16* o, int vb, bf16x8 pa0, bf16x8 pa1, bf16x8 pa2, bf16x8 pa3) {
;   pv_one<0>(o[0], vb, pa0, pa1, pa2, pa3); pv_one<1>(o[1], vb, pa0, pa1, pa2, pa3); pv_one<2>(o[2], vb, pa0, pa1, pa2, pa3); pv_one<3>(o[3], vb, pa0, pa1, pa2, pa3);
; template <typename TQ> ...
;     ...
;   SBAR(); qkt(pB0, pB1, (bf16*)((char*)K_lds + SHM_K), qr, r32, hi, negm);
;   finishSM(pA0, pA1, l_reg, pa0, pa1, pa2, pa3); SBAR();
;   pv_d0(o, vb0, pa0, pa1, pa2, pa3); partialSM(pB0, pB1, mC);
;   __syncthreads();
;   finishSM(pB0, pB1, l_reg, pa0, pa1, pa2, pa3); SBAR();
	s_waitcnt lgkmcnt(3)
	v_mfma_f32_32x32x16_bf16 v[82:97], v[220:223], v[150:153], v[2:17]
	ds_read_b128 v[220:223], v213 offset:32768
	v_add_f32_e32 v205, v114, v205
	v_add_f32_e32 v204, v115, v204
	v_cvt_pk_bf16_f32 v114, v114, v115
	s_waitcnt lgkmcnt(3)
	v_mfma_f32_32x32x16_bf16 v[98:113], v[224:227], v[150:153], v[2:17]
	ds_read_b128 v[224:227], v213 offset:40960
	v_add_f32_e32 v205, v116, v205
	v_add_f32_e32 v204, v117, v204
	v_cvt_pk_bf16_f32 v115, v116, v117
	s_waitcnt lgkmcnt(3)
	v_mfma_f32_32x32x16_bf16 v[82:97], v[228:231], v[158:161], v[82:97]
	ds_read_b128 v[228:231], v214 offset:32768
	v_add_f32_e32 v205, v118, v205
	v_add_f32_e32 v204, v119, v204
	v_cvt_pk_bf16_f32 v116, v118, v119
	s_waitcnt lgkmcnt(3)
	v_mfma_f32_32x32x16_bf16 v[98:113], v[232:235], v[158:161], v[98:113]
	ds_read_b128 v[232:235], v214 offset:40960
	v_add_f32_e32 v205, v120, v205
	v_add_f32_e32 v204, v121, v204
	v_cvt_pk_bf16_f32 v117, v120, v121
	s_waitcnt lgkmcnt(3)
	v_mfma_f32_32x32x16_bf16 v[82:97], v[220:223], v[146:149], v[82:97]
	ds_read_b128 v[220:223], v218 offset:32768
	v_add_f32_e32 v205, v122, v205
	v_add_f32_e32 v204, v123, v204
	v_cvt_pk_bf16_f32 v118, v122, v123
	v_permlane32_swap_b32_e32 v114, v116
	s_waitcnt lgkmcnt(3)
	v_mfma_f32_32x32x16_bf16 v[98:113], v[224:227], v[146:149], v[98:113]
	ds_read_b128 v[224:227], v218 offset:40960
	v_add_f32_e32 v205, v124, v205
	v_add_f32_e32 v204, v125, v204
	v_cvt_pk_bf16_f32 v119, v124, v125
	v_permlane32_swap_b32_e32 v115, v117
	s_waitcnt lgkmcnt(3)
	v_mfma_f32_32x32x16_bf16 v[82:97], v[228:231], v[154:157], v[82:97]
	ds_read_b128 v[228:231], v217 offset:32768
	v_add_f32_e32 v205, v126, v205
	v_add_f32_e32 v204, v127, v204
	v_cvt_pk_bf16_f32 v120, v126, v127
	s_waitcnt lgkmcnt(3)
	v_mfma_f32_32x32x16_bf16 v[98:113], v[232:235], v[154:157], v[98:113]
	ds_read_b128 v[232:235], v217 offset:40960
	v_add_f32_e32 v205, v128, v205
	v_add_f32_e32 v204, v129, v204
	v_cvt_pk_bf16_f32 v121, v128, v129
	s_waitcnt lgkmcnt(3)
	v_mfma_f32_32x32x16_bf16 v[82:97], v[220:223], v[166:169], v[82:97]
	ds_read_b128 v[220:223], v216 offset:32768
	v_add_f32_e32 v205, v130, v205
	v_add_f32_e32 v204, v131, v204
	v_cvt_pk_bf16_f32 v122, v130, v131
	v_permlane32_swap_b32_e32 v118, v120
	ds_read_b64_tr_b16 v[236:237], v206 offset:16384
	s_waitcnt lgkmcnt(4)
	v_mfma_f32_32x32x16_bf16 v[98:113], v[224:227], v[166:169], v[98:113]
	ds_read_b128 v[224:227], v216 offset:40960
	v_add_f32_e32 v205, v132, v205
	v_add_f32_e32 v204, v133, v204
	v_cvt_pk_bf16_f32 v123, v132, v133
	v_permlane32_swap_b32_e32 v119, v121
	ds_read_b64_tr_b16 v[238:239], v206 offset:18432
	s_waitcnt lgkmcnt(5)
	v_mfma_f32_32x32x16_bf16 v[82:97], v[228:231], v[174:177], v[82:97]
	ds_read_b128 v[228:231], v215 offset:32768
	v_add_f32_e32 v205, v134, v205
	v_add_f32_e32 v204, v135, v204
	v_cvt_pk_bf16_f32 v124, v134, v135
	ds_read_b64_tr_b16 v[240:241], v206 offset:20480
	s_waitcnt lgkmcnt(6)
	v_mfma_f32_32x32x16_bf16 v[98:113], v[232:235], v[174:177], v[98:113]
	ds_read_b128 v[232:235], v215 offset:40960
	v_add_f32_e32 v205, v136, v205
	v_add_f32_e32 v204, v137, v204
	v_cvt_pk_bf16_f32 v125, v136, v137
	ds_read_b64_tr_b16 v[242:243], v206 offset:22528
	s_waitcnt lgkmcnt(7)
	v_mfma_f32_32x32x16_bf16 v[82:97], v[220:223], v[162:165], v[82:97]
	v_add_f32_e32 v205, v138, v205
	v_add_f32_e32 v204, v139, v204
	v_cvt_pk_bf16_f32 v126, v138, v139
	v_permlane32_swap_b32_e32 v122, v124
	ds_read_b64_tr_b16 v[244:245], v206 offset:24576
	ds_read_b64_tr_b16 v[130:131], v206 offset:16896
	s_waitcnt lgkmcnt(7)
	v_mfma_f32_32x32x16_bf16 v[98:113], v[224:227], v[162:165], v[98:113]
	v_add_f32_e32 v205, v140, v205
	v_add_f32_e32 v204, v141, v204
	v_cvt_pk_bf16_f32 v127, v140, v141
	v_permlane32_swap_b32_e32 v123, v125
	ds_read_b64_tr_b16 v[246:247], v206 offset:26624
	ds_read_b64_tr_b16 v[132:133], v206 offset:18944
	s_waitcnt lgkmcnt(7)
	v_mfma_f32_32x32x16_bf16 v[82:97], v[228:231], v[170:173], v[82:97]
	v_add_f32_e32 v205, v142, v205
	v_add_f32_e32 v204, v143, v204
	v_cvt_pk_bf16_f32 v128, v142, v143
	ds_read_b64_tr_b16 v[248:249], v206 offset:28672
	ds_read_b64_tr_b16 v[134:135], v206 offset:20992
	s_waitcnt lgkmcnt(7)
	v_mfma_f32_32x32x16_bf16 v[98:113], v[232:235], v[170:173], v[98:113]
	v_add_f32_e32 v205, v144, v205
	v_add_f32_e32 v204, v145, v204
	v_cvt_pk_bf16_f32 v129, v144, v145
	ds_read_b64_tr_b16 v[250:251], v206 offset:30720
	ds_read_b64_tr_b16 v[136:137], v206 offset:23040
	v_mfma_f32_32x32x16_bf16 v[18:33], v[114:117], v[236:239], v[18:33]
	v_permlane32_swap_b32_e32 v126, v128
	v_permlane32_swap_b32_e32 v127, v129
	ds_read_b64_tr_b16 v[236:237], v206 offset:25088
	ds_read_b64_tr_b16 v[238:239], v206 offset:27136
	s_waitcnt lgkmcnt(10)
	v_mfma_f32_32x32x16_bf16 v[18:33], v[118:121], v[240:243], v[18:33]
	ds_read_b64_tr_b16 v[240:241], v206 offset:29184
	ds_read_b64_tr_b16 v[242:243], v206 offset:31232
	v_exp_f32_e32 v82, v82
	v_exp_f32_e32 v83, v83
	s_waitcnt lgkmcnt(9)
	v_mfma_f32_32x32x16_bf16 v[18:33], v[122:125], v[244:247], v[18:33]
	ds_read_b64_tr_b16 v[244:245], v206 offset:17408
	ds_read_b64_tr_b16 v[246:247], v206 offset:19456
	v_exp_f32_e32 v84, v84
	v_exp_f32_e32 v85, v85
	s_waitcnt lgkmcnt(7)
	v_mfma_f32_32x32x16_bf16 v[18:33], v[126:129], v[248:251], v[18:33]
	ds_read_b64_tr_b16 v[248:249], v206 offset:21504
	ds_read_b64_tr_b16 v[250:251], v206 offset:23552
	v_exp_f32_e32 v86, v86
	v_exp_f32_e32 v87, v87
	v_mfma_f32_32x32x16_bf16 v[34:49], v[114:117], v[130:133], v[34:49]
	ds_read_b64_tr_b16 v[130:131], v206 offset:25600
	ds_read_b64_tr_b16 v[132:133], v206 offset:27648
	v_exp_f32_e32 v88, v88
	v_exp_f32_e32 v89, v89
	s_waitcnt lgkmcnt(10)
; #define SBAR() __builtin_amdgcn_sched_barrier(0)
; template <int D0> __device__ __forceinline__ void pv_one(f32x16& od, int vb, bf16x8 pa0, bf16x8 pa1, bf16x8 pa2, bf16x8 pa3) {
;   const s16x4 l0 = tr_read<v_rd_off(D0, 0, 0)>(vb), h0 = tr_read<v_rd_off(D0, 0, 1)>(vb), l1 = tr_read<v_rd_off(D0, 1, 0)>(vb), h1 = tr_read<v_rd_off(D0, 1, 1)>(vb);
;   const s16x4 l2 = tr_read<v_rd_off(D0, 2, 0)>(vb), h2 = tr_read<v_rd_off(D0, 2, 1)>(vb), l3 = tr_read<v_rd_off(D0, 3, 0)>(vb), h3 = tr_read<v_rd_off(D0, 3, 1)>(vb);
;   asm volatile("s_waitcnt lgkmcnt(0)" ::: "memory"); SBAR();
;     ...
;   od = __builtin_amdgcn_mfma_f32_32x32x16_bf16(pa0, PK(l0, h0), od, 0, 0, 0);
;   od = __builtin_amdgcn_mfma_f32_32x32x16_bf16(pa1, PK(l1, h1), od, 0, 0, 0);
;   od = __builtin_amdgcn_mfma_f32_32x32x16_bf16(pa2, PK(l2, h2), od, 0, 0, 0);
;   od = __builtin_amdgcn_mfma_f32_32x32x16_bf16(pa3, PK(l3, h3), od, 0, 0, 0);
;     ...
; }
; __device__ __forceinline__ void pv_d0(f32x16* o, int vb, bf16x8 pa0, bf16x8 pa1, bf16x8 pa2, bf16x8 pa3) {
;   pv_one<0>(o[0], vb, pa0, pa1, pa2, pa3); pv_one<1>(o[1], vb, pa0, pa1, pa2, pa3); pv_one<2>(o[2], vb, pa0, pa1, pa2, pa3); pv_one<3>(o[3], vb, pa0, pa1, pa2, pa3);
; template <typename TQ> ...
;     ...
;   SBAR(); qkt(pB0, pB1, (bf16*)((char*)K_lds + SHM_K), qr, r32, hi, negm);
;   finishSM(pA0, pA1, l_reg, pa0, pa1, pa2, pa3); SBAR();
;   pv_d0(o, vb0, pa0, pa1, pa2, pa3); partialSM(pB0, pB1, mC);
;   __syncthreads();
;   finishSM(pB0, pB1, l_reg, pa0, pa1, pa2, pa3); SBAR();
;   pv_d0(o, vb0 + (int)SHM_V, pa0, pa1, pa2, pa3);
	v_mfma_f32_32x32x16_bf16 v[34:49], v[118:121], v[134:137], v[34:49]
	ds_read_b64_tr_b16 v[134:135], v206 offset:29696
	ds_read_b64_tr_b16 v[136:137], v206 offset:31744
	v_exp_f32_e32 v90, v90
	v_exp_f32_e32 v91, v91
	s_waitcnt lgkmcnt(10)
	v_mfma_f32_32x32x16_bf16 v[34:49], v[122:125], v[236:239], v[34:49]
	ds_read_b64_tr_b16 v[236:237], v206 offset:17920
	ds_read_b64_tr_b16 v[238:239], v206 offset:19968
	v_exp_f32_e32 v92, v92
	v_exp_f32_e32 v93, v93
	s_waitcnt lgkmcnt(10)
	v_mfma_f32_32x32x16_bf16 v[34:49], v[126:129], v[240:243], v[34:49]
	ds_read_b64_tr_b16 v[240:241], v206 offset:22016
	ds_read_b64_tr_b16 v[242:243], v206 offset:24064
	v_exp_f32_e32 v94, v94
	v_exp_f32_e32 v95, v95
	s_waitcnt lgkmcnt(10)
	v_mfma_f32_32x32x16_bf16 v[50:65], v[114:117], v[244:247], v[50:65]
	ds_read_b64_tr_b16 v[244:245], v206 offset:26112
	ds_read_b64_tr_b16 v[246:247], v206 offset:28160
	v_exp_f32_e32 v96, v96
	v_exp_f32_e32 v97, v97
	s_waitcnt lgkmcnt(10)
	v_mfma_f32_32x32x16_bf16 v[50:65], v[118:121], v[248:251], v[50:65]
	ds_read_b64_tr_b16 v[248:249], v206 offset:30208
	ds_read_b64_tr_b16 v[250:251], v206 offset:32256
	v_exp_f32_e32 v98, v98
	v_exp_f32_e32 v99, v99
	s_waitcnt lgkmcnt(10)
	v_mfma_f32_32x32x16_bf16 v[50:65], v[122:125], v[130:133], v[50:65]
	v_exp_f32_e32 v100, v100
	v_exp_f32_e32 v101, v101
	s_waitcnt lgkmcnt(8)
	v_mfma_f32_32x32x16_bf16 v[50:65], v[126:129], v[134:137], v[50:65]
	v_exp_f32_e32 v102, v102
	v_exp_f32_e32 v103, v103
	s_waitcnt lgkmcnt(6)
	v_mfma_f32_32x32x16_bf16 v[66:81], v[114:117], v[236:239], v[66:81]
	v_exp_f32_e32 v104, v104
	v_exp_f32_e32 v105, v105
	ds_read_b128 v[220:223], v210 offset:49152
	s_waitcnt lgkmcnt(5)
	v_mfma_f32_32x32x16_bf16 v[66:81], v[118:121], v[240:243], v[66:81]
	v_exp_f32_e32 v106, v106
	v_exp_f32_e32 v107, v107
	ds_read_b128 v[224:227], v210 offset:57344
	s_waitcnt lgkmcnt(4)
	v_mfma_f32_32x32x16_bf16 v[66:81], v[122:125], v[244:247], v[66:81]
	v_exp_f32_e32 v108, v108
	v_exp_f32_e32 v109, v109
	ds_read_b128 v[228:231], v212 offset:49152
	s_waitcnt lgkmcnt(3)
	v_mfma_f32_32x32x16_bf16 v[66:81], v[126:129], v[248:251], v[66:81]
	v_exp_f32_e32 v110, v110
	v_exp_f32_e32 v111, v111
	v_exp_f32_e32 v112, v112
	v_exp_f32_e32 v113, v113
	ds_read_b128 v[232:235], v212 offset:57344
	s_waitcnt vmcnt(0)
	s_barrier
	s_waitcnt lgkmcnt(3)
	v_mfma_f32_32x32x16_bf16 v[114:129], v[220:223], v[150:153], v[2:17]
	ds_read_b128 v[220:223], v213 offset:49152
	v_add_f32_e32 v205, v82, v205
	v_add_f32_e32 v204, v83, v204
	v_cvt_pk_bf16_f32 v82, v82, v83
	s_waitcnt lgkmcnt(3)
	v_mfma_f32_32x32x16_bf16 v[130:145], v[224:227], v[150:153], v[2:17]
	ds_read_b128 v[224:227], v213 offset:57344
	v_add_f32_e32 v205, v84, v205
	v_add_f32_e32 v204, v85, v204
	v_cvt_pk_bf16_f32 v83, v84, v85
	s_waitcnt lgkmcnt(3)
	v_mfma_f32_32x32x16_bf16 v[114:129], v[228:231], v[158:161], v[114:129]
	ds_read_b128 v[228:231], v214 offset:49152
	v_add_f32_e32 v205, v86, v205
	v_add_f32_e32 v204, v87, v204
	v_cvt_pk_bf16_f32 v84, v86, v87
	s_waitcnt lgkmcnt(3)
	v_mfma_f32_32x32x16_bf16 v[130:145], v[232:235], v[158:161], v[130:145]
	ds_read_b128 v[232:235], v214 offset:57344
	v_add_f32_e32 v205, v88, v205
	v_add_f32_e32 v204, v89, v204
	v_cvt_pk_bf16_f32 v85, v88, v89
	s_waitcnt lgkmcnt(3)
	v_mfma_f32_32x32x16_bf16 v[114:129], v[220:223], v[146:149], v[114:129]
	ds_read_b128 v[220:223], v218 offset:49152
	v_add_f32_e32 v205, v90, v205
	v_add_f32_e32 v204, v91, v204
	v_cvt_pk_bf16_f32 v86, v90, v91
	v_permlane32_swap_b32_e32 v82, v84
	s_waitcnt lgkmcnt(3)
	v_mfma_f32_32x32x16_bf16 v[130:145], v[224:227], v[146:149], v[130:145]
	ds_read_b128 v[224:227], v218 offset:57344
	v_add_f32_e32 v205, v92, v205
	v_add_f32_e32 v204, v93, v204
	v_cvt_pk_bf16_f32 v87, v92, v93
	v_permlane32_swap_b32_e32 v83, v85
	s_waitcnt lgkmcnt(3)
	v_mfma_f32_32x32x16_bf16 v[114:129], v[228:231], v[154:157], v[114:129]
	ds_read_b128 v[228:231], v217 offset:49152
	v_add_f32_e32 v205, v94, v205
	v_add_f32_e32 v204, v95, v204
	v_cvt_pk_bf16_f32 v88, v94, v95
	s_waitcnt lgkmcnt(3)
	v_mfma_f32_32x32x16_bf16 v[130:145], v[232:235], v[154:157], v[130:145]
	ds_read_b128 v[232:235], v217 offset:57344
	v_add_f32_e32 v205, v96, v205
	v_add_f32_e32 v204, v97, v204
	v_cvt_pk_bf16_f32 v89, v96, v97
	s_waitcnt lgkmcnt(3)
	v_mfma_f32_32x32x16_bf16 v[114:129], v[220:223], v[166:169], v[114:129]
	ds_read_b128 v[220:223], v216 offset:49152
	v_add_f32_e32 v205, v98, v205
	v_add_f32_e32 v204, v99, v204
	v_cvt_pk_bf16_f32 v90, v98, v99
	v_permlane32_swap_b32_e32 v86, v88
	ds_read_b64_tr_b16 v[236:237], v206 offset:32768
	s_waitcnt lgkmcnt(4)
	v_mfma_f32_32x32x16_bf16 v[130:145], v[224:227], v[166:169], v[130:145]
	ds_read_b128 v[224:227], v216 offset:57344
	v_add_f32_e32 v205, v100, v205
	v_add_f32_e32 v204, v101, v204
	v_cvt_pk_bf16_f32 v91, v100, v101
	v_permlane32_swap_b32_e32 v87, v89
	ds_read_b64_tr_b16 v[238:239], v206 offset:34816
	s_waitcnt lgkmcnt(5)
	v_mfma_f32_32x32x16_bf16 v[114:129], v[228:231], v[174:177], v[114:129]
	ds_read_b128 v[228:231], v215 offset:49152
	v_add_f32_e32 v205, v102, v205
	v_add_f32_e32 v204, v103, v204
	v_cvt_pk_bf16_f32 v92, v102, v103
	ds_read_b64_tr_b16 v[240:241], v206 offset:36864
	s_waitcnt lgkmcnt(6)
	v_mfma_f32_32x32x16_bf16 v[130:145], v[232:235], v[174:177], v[130:145]
	ds_read_b128 v[232:235], v215 offset:57344
	v_add_f32_e32 v205, v104, v205
	v_add_f32_e32 v204, v105, v204
	v_cvt_pk_bf16_f32 v93, v104, v105
	ds_read_b64_tr_b16 v[242:243], v206 offset:38912
	s_waitcnt lgkmcnt(7)
	v_mfma_f32_32x32x16_bf16 v[114:129], v[220:223], v[162:165], v[114:129]
	v_add_f32_e32 v205, v106, v205
	v_add_f32_e32 v204, v107, v204
	v_cvt_pk_bf16_f32 v94, v106, v107
	v_permlane32_swap_b32_e32 v90, v92
	ds_read_b64_tr_b16 v[244:245], v206 offset:40960
	ds_read_b64_tr_b16 v[98:99], v206 offset:33280
	s_waitcnt lgkmcnt(7)
; #define SBAR() __builtin_amdgcn_sched_barrier(0)
; template <int D0> __device__ __forceinline__ void pv_one(f32x16& od, int vb, bf16x8 pa0, bf16x8 pa1, bf16x8 pa2, bf16x8 pa3) {
;   const s16x4 l0 = tr_read<v_rd_off(D0, 0, 0)>(vb), h0 = tr_read<v_rd_off(D0, 0, 1)>(vb), l1 = tr_read<v_rd_off(D0, 1, 0)>(vb), h1 = tr_read<v_rd_off(D0, 1, 1)>(vb);
;   const s16x4 l2 = tr_read<v_rd_off(D0, 2, 0)>(vb), h2 = tr_read<v_rd_off(D0, 2, 1)>(vb), l3 = tr_read<v_rd_off(D0, 3, 0)>(vb), h3 = tr_read<v_rd_off(D0, 3, 1)>(vb);
;   asm volatile("s_waitcnt lgkmcnt(0)" ::: "memory"); SBAR();
;     ...
;   od = __builtin_amdgcn_mfma_f32_32x32x16_bf16(pa0, PK(l0, h0), od, 0, 0, 0);
;   od = __builtin_amdgcn_mfma_f32_32x32x16_bf16(pa1, PK(l1, h1), od, 0, 0, 0);
;   od = __builtin_amdgcn_mfma_f32_32x32x16_bf16(pa2, PK(l2, h2), od, 0, 0, 0);
;   od = __builtin_amdgcn_mfma_f32_32x32x16_bf16(pa3, PK(l3, h3), od, 0, 0, 0);
;     ...
; }
; __device__ __forceinline__ void pv_d0(f32x16* o, int vb, bf16x8 pa0, bf16x8 pa1, bf16x8 pa2, bf16x8 pa3) {
;   pv_one<0>(o[0], vb, pa0, pa1, pa2, pa3); pv_one<1>(o[1], vb, pa0, pa1, pa2, pa3); pv_one<2>(o[2], vb, pa0, pa1, pa2, pa3); pv_one<3>(o[3], vb, pa0, pa1, pa2, pa3);
; template <typename TQ> ...
;     ...
;   pv_d0(o, vb0, pa0, pa1, pa2, pa3); partialSM(pB0, pB1, mC);
;   __syncthreads();
;   finishSM(pB0, pB1, l_reg, pa0, pa1, pa2, pa3); SBAR();
;   pv_d0(o, vb0 + (int)SHM_V, pa0, pa1, pa2, pa3);
	v_mfma_f32_32x32x16_bf16 v[130:145], v[224:227], v[162:165], v[130:145]
	v_add_f32_e32 v205, v108, v205
	v_add_f32_e32 v204, v109, v204
	v_cvt_pk_bf16_f32 v95, v108, v109
	v_permlane32_swap_b32_e32 v91, v93
	ds_read_b64_tr_b16 v[246:247], v206 offset:43008
	ds_read_b64_tr_b16 v[100:101], v206 offset:35328
	s_waitcnt lgkmcnt(7)
	v_mfma_f32_32x32x16_bf16 v[114:129], v[228:231], v[170:173], v[114:129]
	v_add_f32_e32 v205, v110, v205
	v_add_f32_e32 v204, v111, v204
	v_cvt_pk_bf16_f32 v96, v110, v111
	ds_read_b64_tr_b16 v[248:249], v206 offset:45056
	ds_read_b64_tr_b16 v[102:103], v206 offset:37376
	s_waitcnt lgkmcnt(7)
	v_mfma_f32_32x32x16_bf16 v[130:145], v[232:235], v[170:173], v[130:145]
	v_add_f32_e32 v205, v112, v205
	v_add_f32_e32 v204, v113, v204
	v_cvt_pk_bf16_f32 v97, v112, v113
	ds_read_b64_tr_b16 v[250:251], v206 offset:47104
	ds_read_b64_tr_b16 v[104:105], v206 offset:39424
	v_mfma_f32_32x32x16_bf16 v[18:33], v[82:85], v[236:239], v[18:33]
	v_permlane32_swap_b32_e32 v94, v96
	v_permlane32_swap_b32_e32 v95, v97
	ds_read_b64_tr_b16 v[236:237], v206 offset:41472
	ds_read_b64_tr_b16 v[238:239], v206 offset:43520
	s_waitcnt lgkmcnt(10)
	v_mfma_f32_32x32x16_bf16 v[18:33], v[86:89], v[240:243], v[18:33]
	ds_read_b64_tr_b16 v[240:241], v206 offset:45568
	ds_read_b64_tr_b16 v[242:243], v206 offset:47616
	v_exp_f32_e32 v114, v114
	v_exp_f32_e32 v115, v115
	s_waitcnt lgkmcnt(9)
	v_mfma_f32_32x32x16_bf16 v[18:33], v[90:93], v[244:247], v[18:33]
	ds_read_b64_tr_b16 v[244:245], v206 offset:33792
	ds_read_b64_tr_b16 v[246:247], v206 offset:35840
	v_exp_f32_e32 v116, v116
	v_exp_f32_e32 v117, v117
	s_waitcnt lgkmcnt(7)
	v_mfma_f32_32x32x16_bf16 v[18:33], v[94:97], v[248:251], v[18:33]
	ds_read_b64_tr_b16 v[248:249], v206 offset:37888
	ds_read_b64_tr_b16 v[250:251], v206 offset:39936
	v_exp_f32_e32 v118, v118
	v_exp_f32_e32 v119, v119
	v_mfma_f32_32x32x16_bf16 v[34:49], v[82:85], v[98:101], v[34:49]
	ds_read_b64_tr_b16 v[98:99], v206 offset:41984
	ds_read_b64_tr_b16 v[100:101], v206 offset:44032
	v_exp_f32_e32 v120, v120
	v_exp_f32_e32 v121, v121
	s_waitcnt lgkmcnt(10)
	v_mfma_f32_32x32x16_bf16 v[34:49], v[86:89], v[102:105], v[34:49]
	ds_read_b64_tr_b16 v[102:103], v206 offset:46080
	ds_read_b64_tr_b16 v[104:105], v206 offset:48128
	v_exp_f32_e32 v122, v122
	v_exp_f32_e32 v123, v123
	s_waitcnt lgkmcnt(10)
	v_mfma_f32_32x32x16_bf16 v[34:49], v[90:93], v[236:239], v[34:49]
	ds_read_b64_tr_b16 v[236:237], v206 offset:34304
	ds_read_b64_tr_b16 v[238:239], v206 offset:36352
	v_exp_f32_e32 v124, v124
	v_exp_f32_e32 v125, v125
	s_waitcnt lgkmcnt(10)
	v_mfma_f32_32x32x16_bf16 v[34:49], v[94:97], v[240:243], v[34:49]
	ds_read_b64_tr_b16 v[240:241], v206 offset:38400
	ds_read_b64_tr_b16 v[242:243], v206 offset:40448
	v_exp_f32_e32 v126, v126
	v_exp_f32_e32 v127, v127
	s_waitcnt lgkmcnt(10)
	v_mfma_f32_32x32x16_bf16 v[50:65], v[82:85], v[244:247], v[50:65]
	ds_read_b64_tr_b16 v[244:245], v206 offset:42496
	ds_read_b64_tr_b16 v[246:247], v206 offset:44544
	v_exp_f32_e32 v128, v128
	v_exp_f32_e32 v129, v129
	s_waitcnt lgkmcnt(10)
	v_mfma_f32_32x32x16_bf16 v[50:65], v[86:89], v[248:251], v[50:65]
	ds_read_b64_tr_b16 v[248:249], v206 offset:46592
	ds_read_b64_tr_b16 v[250:251], v206 offset:48640
	v_exp_f32_e32 v130, v130
	v_exp_f32_e32 v131, v131
	s_waitcnt lgkmcnt(10)
	v_mfma_f32_32x32x16_bf16 v[50:65], v[90:93], v[98:101], v[50:65]
	v_exp_f32_e32 v132, v132
	v_exp_f32_e32 v133, v133
	s_waitcnt lgkmcnt(8)
	v_mfma_f32_32x32x16_bf16 v[50:65], v[94:97], v[102:105], v[50:65]
	v_exp_f32_e32 v134, v134
	v_exp_f32_e32 v135, v135
	s_waitcnt lgkmcnt(6)
	v_mfma_f32_32x32x16_bf16 v[66:81], v[82:85], v[236:239], v[66:81]
	v_exp_f32_e32 v136, v136
	v_exp_f32_e32 v137, v137
	s_waitcnt lgkmcnt(4)
	v_mfma_f32_32x32x16_bf16 v[66:81], v[86:89], v[240:243], v[66:81]
	v_exp_f32_e32 v138, v138
	v_exp_f32_e32 v139, v139
	s_waitcnt lgkmcnt(2)
	v_mfma_f32_32x32x16_bf16 v[66:81], v[90:93], v[244:247], v[66:81]
	v_exp_f32_e32 v140, v140
	v_exp_f32_e32 v141, v141
	s_waitcnt lgkmcnt(0)
	v_mfma_f32_32x32x16_bf16 v[66:81], v[94:97], v[248:251], v[66:81]
	v_exp_f32_e32 v142, v142
	v_exp_f32_e32 v143, v143
	v_exp_f32_e32 v144, v144
	v_exp_f32_e32 v145, v145
	s_waitcnt vmcnt(0)
; #define SBAR() __builtin_amdgcn_sched_barrier(0)
; template <int D0> __device__ __forceinline__ void pv_one(f32x16& od, int vb, bf16x8 pa0, bf16x8 pa1, bf16x8 pa2, bf16x8 pa3) {
;   const s16x4 l0 = tr_read<v_rd_off(D0, 0, 0)>(vb), h0 = tr_read<v_rd_off(D0, 0, 1)>(vb), l1 = tr_read<v_rd_off(D0, 1, 0)>(vb), h1 = tr_read<v_rd_off(D0, 1, 1)>(vb);
;   const s16x4 l2 = tr_read<v_rd_off(D0, 2, 0)>(vb), h2 = tr_read<v_rd_off(D0, 2, 1)>(vb), l3 = tr_read<v_rd_off(D0, 3, 0)>(vb), h3 = tr_read<v_rd_off(D0, 3, 1)>(vb);
;   asm volatile("s_waitcnt lgkmcnt(0)" ::: "memory"); SBAR();
;     ...
;   od = __builtin_amdgcn_mfma_f32_32x32x16_bf16(pa0, PK(l0, h0), od, 0, 0, 0);
;   od = __builtin_amdgcn_mfma_f32_32x32x16_bf16(pa1, PK(l1, h1), od, 0, 0, 0);
;   od = __builtin_amdgcn_mfma_f32_32x32x16_bf16(pa2, PK(l2, h2), od, 0, 0, 0);
;   od = __builtin_amdgcn_mfma_f32_32x32x16_bf16(pa3, PK(l3, h3), od, 0, 0, 0);
;     ...
; }
; __device__ __forceinline__ void pv_d0(f32x16* o, int vb, bf16x8 pa0, bf16x8 pa1, bf16x8 pa2, bf16x8 pa3) {
;   pv_one<0>(o[0], vb, pa0, pa1, pa2, pa3); pv_one<1>(o[1], vb, pa0, pa1, pa2, pa3); pv_one<2>(o[2], vb, pa0, pa1, pa2, pa3); pv_one<3>(o[3], vb, pa0, pa1, pa2, pa3);
; template <typename TQ> ...
;     ...
;   finishSM(pB0, pB1, l_reg, pa0, pa1, pa2, pa3); SBAR();
;   pv_d0(o, vb0 + (int)SHM_V, pa0, pa1, pa2, pa3);
;   if (hi == 0) li_l[r32] = l_reg; asm volatile("s_waitcnt lgkmcnt(0)" ::: "memory");
	ds_read_b64_tr_b16 v[236:237], v206 offset:49152
	ds_read_b64_tr_b16 v[238:239], v206 offset:51200
	ds_read_b64_tr_b16 v[240:241], v206 offset:53248
	ds_read_b64_tr_b16 v[242:243], v206 offset:55296
	ds_read_b64_tr_b16 v[244:245], v206 offset:57344
	ds_read_b64_tr_b16 v[246:247], v206 offset:59392
	ds_read_b64_tr_b16 v[248:249], v206 offset:61440
	ds_read_b64_tr_b16 v[250:251], v206 offset:63488
	v_add_f32_e32 v205, v114, v205
	v_add_f32_e32 v204, v115, v204
	v_cvt_pk_bf16_f32 v114, v114, v115
	v_add_f32_e32 v205, v116, v205
	v_add_f32_e32 v204, v117, v204
	v_cvt_pk_bf16_f32 v115, v116, v117
	v_add_f32_e32 v205, v118, v205
	v_add_f32_e32 v204, v119, v204
	v_cvt_pk_bf16_f32 v116, v118, v119
	v_add_f32_e32 v205, v120, v205
	v_add_f32_e32 v204, v121, v204
	v_cvt_pk_bf16_f32 v117, v120, v121
	v_add_f32_e32 v205, v122, v205
	v_add_f32_e32 v204, v123, v204
	v_cvt_pk_bf16_f32 v118, v122, v123
	v_add_f32_e32 v205, v124, v205
	v_add_f32_e32 v204, v125, v204
	v_cvt_pk_bf16_f32 v119, v124, v125
	v_add_f32_e32 v205, v126, v205
	v_add_f32_e32 v204, v127, v204
	v_cvt_pk_bf16_f32 v120, v126, v127
	v_add_f32_e32 v205, v128, v205
	v_add_f32_e32 v204, v129, v204
	v_cvt_pk_bf16_f32 v121, v128, v129
	v_add_f32_e32 v205, v130, v205
	v_add_f32_e32 v204, v131, v204
	v_cvt_pk_bf16_f32 v122, v130, v131
	v_add_f32_e32 v205, v132, v205
	v_add_f32_e32 v204, v133, v204
	v_cvt_pk_bf16_f32 v123, v132, v133
	v_add_f32_e32 v205, v134, v205
	v_add_f32_e32 v204, v135, v204
	v_cvt_pk_bf16_f32 v124, v134, v135
	v_add_f32_e32 v205, v136, v205
	v_add_f32_e32 v204, v137, v204
	v_cvt_pk_bf16_f32 v125, v136, v137
	v_add_f32_e32 v205, v138, v205
	v_add_f32_e32 v204, v139, v204
	v_cvt_pk_bf16_f32 v126, v138, v139
	v_add_f32_e32 v205, v140, v205
	v_add_f32_e32 v204, v141, v204
	v_cvt_pk_bf16_f32 v127, v140, v141
	v_add_f32_e32 v205, v142, v205
	v_add_f32_e32 v204, v143, v204
	v_cvt_pk_bf16_f32 v128, v142, v143
	v_add_f32_e32 v205, v144, v205
	v_add_f32_e32 v204, v145, v204
	v_cvt_pk_bf16_f32 v129, v144, v145
	s_nop 1
	v_permlane32_swap_b32_e32 v114, v116
	v_permlane32_swap_b32_e32 v115, v117
	v_permlane32_swap_b32_e32 v118, v120
	v_permlane32_swap_b32_e32 v119, v121
	v_permlane32_swap_b32_e32 v122, v124
	v_permlane32_swap_b32_e32 v123, v125
	v_permlane32_swap_b32_e32 v126, v128
	v_permlane32_swap_b32_e32 v127, v129
	ds_read_b64_tr_b16 v[130:131], v206 offset:49664
	ds_read_b64_tr_b16 v[132:133], v206 offset:51712
	ds_read_b64_tr_b16 v[134:135], v206 offset:53760
	ds_read_b64_tr_b16 v[136:137], v206 offset:55808
	s_waitcnt lgkmcnt(10)
	v_mfma_f32_32x32x16_bf16 v[18:33], v[114:117], v[236:239], v[18:33]
	ds_read_b64_tr_b16 v[236:237], v206 offset:57856
	ds_read_b64_tr_b16 v[238:239], v206 offset:59904
	s_waitcnt lgkmcnt(10)
	v_mfma_f32_32x32x16_bf16 v[18:33], v[118:121], v[240:243], v[18:33]
	ds_read_b64_tr_b16 v[240:241], v206 offset:61952
	ds_read_b64_tr_b16 v[242:243], v206 offset:64000
	s_waitcnt lgkmcnt(10)
	v_mfma_f32_32x32x16_bf16 v[18:33], v[122:125], v[244:247], v[18:33]
	ds_read_b64_tr_b16 v[244:245], v206 offset:50176
	ds_read_b64_tr_b16 v[246:247], v206 offset:52224
	s_waitcnt lgkmcnt(10)
	v_mfma_f32_32x32x16_bf16 v[18:33], v[126:129], v[248:251], v[18:33]
	ds_read_b64_tr_b16 v[248:249], v206 offset:54272
	ds_read_b64_tr_b16 v[250:251], v206 offset:56320
	s_waitcnt lgkmcnt(10)
	v_mfma_f32_32x32x16_bf16 v[34:49], v[114:117], v[130:133], v[34:49]
	ds_read_b64_tr_b16 v[130:131], v206 offset:58368
	ds_read_b64_tr_b16 v[132:133], v206 offset:60416
	s_waitcnt lgkmcnt(10)
	v_mfma_f32_32x32x16_bf16 v[34:49], v[118:121], v[134:137], v[34:49]
	ds_read_b64_tr_b16 v[134:135], v206 offset:62464
	ds_read_b64_tr_b16 v[136:137], v206 offset:64512
	s_waitcnt lgkmcnt(10)
	v_mfma_f32_32x32x16_bf16 v[34:49], v[122:125], v[236:239], v[34:49]
	ds_read_b64_tr_b16 v[236:237], v206 offset:50688
	ds_read_b64_tr_b16 v[238:239], v206 offset:52736
	s_waitcnt lgkmcnt(10)
	v_mfma_f32_32x32x16_bf16 v[34:49], v[126:129], v[240:243], v[34:49]
	ds_read_b64_tr_b16 v[240:241], v206 offset:54784
	ds_read_b64_tr_b16 v[242:243], v206 offset:56832
	s_waitcnt lgkmcnt(10)
	v_mfma_f32_32x32x16_bf16 v[50:65], v[114:117], v[244:247], v[50:65]
	ds_read_b64_tr_b16 v[244:245], v206 offset:58880
	ds_read_b64_tr_b16 v[246:247], v206 offset:60928
	s_waitcnt lgkmcnt(10)
	v_mfma_f32_32x32x16_bf16 v[50:65], v[118:121], v[248:251], v[50:65]
	ds_read_b64_tr_b16 v[248:249], v206 offset:62976
	ds_read_b64_tr_b16 v[250:251], v206 offset:65024
	s_waitcnt lgkmcnt(10)
	v_mfma_f32_32x32x16_bf16 v[50:65], v[122:125], v[130:133], v[50:65]
	s_waitcnt lgkmcnt(8)
	v_mfma_f32_32x32x16_bf16 v[50:65], v[126:129], v[134:137], v[50:65]
	s_waitcnt lgkmcnt(6)
	v_mfma_f32_32x32x16_bf16 v[66:81], v[114:117], v[236:239], v[66:81]
	s_waitcnt lgkmcnt(4)
	v_mfma_f32_32x32x16_bf16 v[66:81], v[118:121], v[240:243], v[66:81]
	s_waitcnt lgkmcnt(2)
	v_mfma_f32_32x32x16_bf16 v[66:81], v[122:125], v[244:247], v[66:81]
	s_waitcnt lgkmcnt(0)
	v_mfma_f32_32x32x16_bf16 v[66:81], v[126:129], v[248:251], v[66:81]
	s_and_b32 s0, s53, 0x3fffffc0
	s_lshl_b32 s0, s0, 2
	s_add_i32 s15, s0, 0x20800
	v_add_f32_e32 v205, v205, v204
	v_cmp_gt_u32_e32 vcc, 32, v203
	v_mov_b32_e32 v204, v205
	v_lshl_add_u32 v219, v202, 2, s15
	s_nop 1
	v_permlane32_swap_b32_e32 v205, v204
	v_add_f32_e32 v205, v205, v204
	s_and_saveexec_b64 s[0:1], vcc
	ds_write_b32 v219, v205
	s_branch .LBB0_817
